# v6 + GEMM loops fully VALU-free: all 16 LDS-DMA loads use saddr form (+0x80 bases in SGPRs), LDS read addresses hoisted
# speedup vs baseline: 1.0141x; 1.0044x over previous
; #define PG8_STAGE(bufoff, gbase, voff) do { _Pragma("unroll") for (int _i = 0; _i < 2; ++_i) \
;         __builtin_amdgcn_global_load_lds((const unsigned*)((const char*)(gbase) + (voff)[_i]), (LAS unsigned*)(lds + (bufoff) + ldsw + _i * 8192), 16, 0, 0); } while (0)
; #define PG8_LDA(dst, b, h) do { _Pragma("unroll") for (int m = 0; m < 4; ++m) _Pragma("unroll") for (int k = 0; k < 2; ++k) dst[m][k] = *(const LAS bf16x8*)(lds + PG8_SA(b, h) + aoff + m * 2048 + k * 1024); } while (0)
; #define PG8_LDB(dst, b, h) do { _Pragma("unroll") for (int n = 0; n < 2; ++n) _Pragma("unroll") for (int k = 0; k < 2; ++k) dst[n][k] = *(const LAS bf16x8*)(lds + PG8_SB(b, h) + boff + n * 2048 + k * 1024); } while (0)
; #define PG8_MMA(ai, bj, At, Bt) do { __builtin_amdgcn_s_setprio(1); _Pragma("unroll") for (int m = 0; m < 4; ++m) _Pragma("unroll") for (int n = 0; n < 2; ++n) _Pragma("unroll") for (int k = 0; k < 2; ++k) \
;         acc[ai][bj][m][n] = __builtin_amdgcn_mfma_f32_16x16x32_bf16(Bt[n][k], At[m][k], acc[ai][bj][m][n], 0, 0, 0); __builtin_amdgcn_s_setprio(0); } while (0)
; #define PG8_WAIT_L(n) asm volatile("s_waitcnt lgkmcnt(" #n ")" ::: "memory")
; #define PG8_BAR __builtin_amdgcn_s_barrier()
; #define PG8_SCHED __builtin_amdgcn_sched_barrier(0)
; template <class Epi, class Ptrs>
; __device__ __forceinline__ void gemm_phase(LAS unsigned char* lds, const int K, const StaticOrder& S, const Ptrs& P, const Epi& E) {
;     ...
;         for (int t = 0; t < nt; t += 2) {
;             const bool last = (t == nt - 2);
;             const char* a1 = cA + (size_t)(t + 1) * kstep;
;             const char* a2 = last ? nA : cA + (size_t)(t + 2) * kstep; const char* b2 = last ? nB : cB + (size_t)(t + 2) * kstep;
;             const char* a3 = a2 + kstep; const char* b3 = b2 + kstep;
;             PG8_LDB(B0, 0, 0); PG8_SCHED; PG8_LDA(At, 0, 0); PG8_STAGE(PG8_SA(1, 1), a1 + hstep, voffA);
;             PG8_WAIT_L(8); PG8_BAR; PG8_WAIT_L(0); PG8_MMA(0, 0, At, B0); PG8_BAR; PG8_SCHED;
;     ...
; #pragma unroll
;         for (int a = 0; a < 2; ++a)
; #pragma unroll
;             for (int b = 0; b < 2; ++b)
; #pragma unroll
;                 for (int m = 0; m < 4; ++m)
; #pragma unroll
;                     for (int n = 0; n < 2; ++n) acc[a][b][m][n] = (f32x4){0.f, 0.f, 0.f, 0.f};
;         cur = nxt; cA = nA; cB = nB; ++ui;
.LBB0_126:
	s_add_u32 s6, s6, 0x40080
	s_nop 0
	s_nop 0
	s_nop 0
	s_nop 0
	s_nop 0
	s_nop 0
	s_nop 0
	s_nop 0
	s_nop 0
	s_nop 0
	s_nop 0
	s_nop 0
	s_nop 0
	s_nop 0
	s_nop 0
	s_nop 0
	s_nop 0
	s_nop 0
	s_nop 0
	s_nop 0
	s_nop 0
	s_nop 0
	s_nop 0
	s_nop 0
	s_nop 0
	s_nop 0
	s_nop 0
	s_nop 0
	s_nop 0
	s_nop 0
	s_nop 0
	s_nop 0
	s_nop 0
	s_nop 0
	s_nop 0
	s_nop 0
	s_nop 0
	s_nop 0
	s_nop 0
	s_nop 0
	s_nop 0
	s_nop 0
	s_nop 0
	s_nop 0
	s_nop 0
	s_nop 0
	s_nop 0
	s_nop 0
	s_nop 0
	s_nop 0
	s_nop 0
	s_nop 0
	s_nop 0
	s_nop 0
	s_nop 0
	s_nop 0
	s_nop 0
	s_nop 0
	s_nop 0
	s_nop 0
	s_addc_u32 s7, s7, 0
	s_add_u32 s20, s78, 0x100
	v_mov_b32_e32 v0, 0
	s_addc_u32 s25, s79, 0
	s_mov_b32 s63, -2
	v_mov_b32_e32 v1, v0
	v_mov_b32_e32 v2, v0
	v_mov_b32_e32 v3, v0
	v_mov_b32_e32 v12, v0
	v_mov_b32_e32 v13, v0
	v_mov_b32_e32 v14, v0
	v_mov_b32_e32 v15, v0
	v_mov_b32_e32 v16, v0
	v_mov_b32_e32 v17, v0
	v_mov_b32_e32 v18, v0
	v_mov_b32_e32 v19, v0
	v_mov_b32_e32 v28, v0
	v_mov_b32_e32 v29, v0
	v_mov_b32_e32 v30, v0
	v_mov_b32_e32 v31, v0
	v_mov_b32_e32 v32, v0
	v_mov_b32_e32 v33, v0
	v_mov_b32_e32 v34, v0
	v_mov_b32_e32 v35, v0
	v_mov_b32_e32 v44, v0
	v_mov_b32_e32 v45, v0
	v_mov_b32_e32 v46, v0
	v_mov_b32_e32 v47, v0
	v_mov_b32_e32 v48, v0
	v_mov_b32_e32 v49, v0
	v_mov_b32_e32 v50, v0
	v_mov_b32_e32 v51, v0
	v_mov_b32_e32 v60, v0
	v_mov_b32_e32 v61, v0
	v_mov_b32_e32 v62, v0
	v_mov_b32_e32 v63, v0
	v_mov_b32_e32 v4, v0
	v_mov_b32_e32 v5, v0
	v_mov_b32_e32 v6, v0
	v_mov_b32_e32 v7, v0
	v_mov_b32_e32 v8, v0
	v_mov_b32_e32 v9, v0
	v_mov_b32_e32 v10, v0
	v_mov_b32_e32 v11, v0
	v_mov_b32_e32 v20, v0
	v_mov_b32_e32 v21, v0
	v_mov_b32_e32 v22, v0
	v_mov_b32_e32 v23, v0
	v_mov_b32_e32 v24, v0
	v_mov_b32_e32 v25, v0
	v_mov_b32_e32 v26, v0
	v_mov_b32_e32 v27, v0
	v_mov_b32_e32 v36, v0
	v_mov_b32_e32 v37, v0
	v_mov_b32_e32 v38, v0
	v_mov_b32_e32 v39, v0
	v_mov_b32_e32 v40, v0
	v_mov_b32_e32 v41, v0
	v_mov_b32_e32 v42, v0
	v_mov_b32_e32 v43, v0
	v_mov_b32_e32 v52, v0
	v_mov_b32_e32 v53, v0
	v_mov_b32_e32 v54, v0
	v_mov_b32_e32 v55, v0
	v_mov_b32_e32 v56, v0
	v_mov_b32_e32 v57, v0
	v_mov_b32_e32 v58, v0
	v_mov_b32_e32 v59, v0
	v_mov_b32_e32 v64, v0
	v_mov_b32_e32 v65, v0
	v_mov_b32_e32 v66, v0
	v_mov_b32_e32 v67, v0
	v_mov_b32_e32 v76, v0
	v_mov_b32_e32 v77, v0
	v_mov_b32_e32 v78, v0
	v_mov_b32_e32 v79, v0
	v_mov_b32_e32 v80, v0
	v_mov_b32_e32 v81, v0
	v_mov_b32_e32 v82, v0
	v_mov_b32_e32 v83, v0
	v_mov_b32_e32 v92, v0
	v_mov_b32_e32 v93, v0
	v_mov_b32_e32 v94, v0
	v_mov_b32_e32 v95, v0
	v_mov_b32_e32 v96, v0
	v_mov_b32_e32 v97, v0
	v_mov_b32_e32 v98, v0
	v_mov_b32_e32 v99, v0
	v_mov_b32_e32 v108, v0
	v_mov_b32_e32 v109, v0
	v_mov_b32_e32 v110, v0
	v_mov_b32_e32 v111, v0
	v_mov_b32_e32 v112, v0
	v_mov_b32_e32 v113, v0
	v_mov_b32_e32 v114, v0
	v_mov_b32_e32 v115, v0
	v_mov_b32_e32 v124, v0
	v_mov_b32_e32 v125, v0
	v_mov_b32_e32 v126, v0
	v_mov_b32_e32 v127, v0
	v_mov_b32_e32 v68, v0
	v_mov_b32_e32 v69, v0
	v_mov_b32_e32 v70, v0
	v_mov_b32_e32 v71, v0
	v_mov_b32_e32 v72, v0
	v_mov_b32_e32 v73, v0
	v_mov_b32_e32 v74, v0
	v_mov_b32_e32 v75, v0
	v_mov_b32_e32 v84, v0
	v_mov_b32_e32 v85, v0
	v_mov_b32_e32 v86, v0
	v_mov_b32_e32 v87, v0
	v_mov_b32_e32 v88, v0
	v_mov_b32_e32 v89, v0
	v_mov_b32_e32 v90, v0
	v_mov_b32_e32 v91, v0
	v_mov_b32_e32 v100, v0
	v_mov_b32_e32 v101, v0
	v_mov_b32_e32 v102, v0
	v_mov_b32_e32 v103, v0
	v_mov_b32_e32 v104, v0
	v_mov_b32_e32 v105, v0
	v_mov_b32_e32 v106, v0
	v_mov_b32_e32 v107, v0
	v_mov_b32_e32 v116, v0
	v_mov_b32_e32 v117, v0
	v_mov_b32_e32 v118, v0
	v_mov_b32_e32 v119, v0
	v_mov_b32_e32 v120, v0
	v_mov_b32_e32 v121, v0
	v_mov_b32_e32 v122, v0
	v_mov_b32_e32 v123, v0
	v_add_u32_e32 v252, 0x18000, v131
	v_add_u32_e32 v253, 0x1c000, v131
.LBB0_127:
	ds_read_b128 v[150:153], v205
	ds_read_b128 v[154:157], v205 offset:1024
	ds_read_b128 v[158:161], v205 offset:2048
	ds_read_b128 v[162:165], v205 offset:3072
	s_add_u32 s69, s6, 0xfffc0080
	s_addc_u32 s71, s7, -1
	s_cmp_eq_u32 s63, 12
	s_cselect_b32 s81, s1, s71
	s_cselect_b32 s80, s0, s69
	s_cselect_b32 s79, s73, s25
	s_cselect_b32 s78, s72, s20
	s_add_i32 m0, s67, 0xc000
	ds_read_b128 v[166:169], v206
	ds_read_b128 v[170:173], v206 offset:1024
	ds_read_b128 v[174:177], v206 offset:2048
	ds_read_b128 v[178:181], v206 offset:3072
	ds_read_b128 v[182:185], v206 offset:4096
	ds_read_b128 v[186:189], v206 offset:5120
	ds_read_b128 v[190:193], v206 offset:6144
	ds_read_b128 v[194:197], v206 offset:7168
	global_load_lds_dwordx4 v142, s[6:7]
	s_add_i32 m0, s67, 0xe000
	s_nop 0
	global_load_lds_dwordx4 v144, s[6:7]
	s_waitcnt lgkmcnt(8)
	s_barrier
	s_waitcnt lgkmcnt(0)
	s_setprio 1
	s_waitcnt lgkmcnt(0)
	v_mfma_f32_16x16x32_bf16 v[120:123], v[150:153], v[166:169], v[120:123]
	v_mfma_f32_16x16x32_bf16 v[120:123], v[154:157], v[170:173], v[120:123]
	v_mfma_f32_16x16x32_bf16 v[116:119], v[162:165], v[170:173], v[116:119]
	v_mfma_f32_16x16x32_bf16 v[116:119], v[158:161], v[166:169], v[116:119]
	v_mfma_f32_16x16x32_bf16 v[100:103], v[158:161], v[174:177], v[100:103]
	v_mfma_f32_16x16x32_bf16 v[100:103], v[162:165], v[178:181], v[100:103]
	v_mfma_f32_16x16x32_bf16 v[104:107], v[154:157], v[178:181], v[104:107]
	v_mfma_f32_16x16x32_bf16 v[104:107], v[150:153], v[174:177], v[104:107]
	v_mfma_f32_16x16x32_bf16 v[88:91], v[150:153], v[182:185], v[88:91]
	v_mfma_f32_16x16x32_bf16 v[88:91], v[154:157], v[186:189], v[88:91]
	v_mfma_f32_16x16x32_bf16 v[84:87], v[162:165], v[186:189], v[84:87]
	v_mfma_f32_16x16x32_bf16 v[84:87], v[158:161], v[182:185], v[84:87]
	v_mfma_f32_16x16x32_bf16 v[68:71], v[158:161], v[190:193], v[68:71]
	v_mfma_f32_16x16x32_bf16 v[68:71], v[162:165], v[194:197], v[68:71]
	v_mfma_f32_16x16x32_bf16 v[72:75], v[154:157], v[194:197], v[72:75]
	v_mfma_f32_16x16x32_bf16 v[72:75], v[150:153], v[190:193], v[72:75]
	s_setprio 0
	s_barrier
; #define PG8_STAGE(bufoff, gbase, voff) do { _Pragma("unroll") for (int _i = 0; _i < 2; ++_i) \
;         __builtin_amdgcn_global_load_lds((const unsigned*)((const char*)(gbase) + (voff)[_i]), (LAS unsigned*)(lds + (bufoff) + ldsw + _i * 8192), 16, 0, 0); } while (0)
; #define PG8_LDA(dst, b, h) do { _Pragma("unroll") for (int m = 0; m < 4; ++m) _Pragma("unroll") for (int k = 0; k < 2; ++k) dst[m][k] = *(const LAS bf16x8*)(lds + PG8_SA(b, h) + aoff + m * 2048 + k * 1024); } while (0)
; #define PG8_LDB(dst, b, h) do { _Pragma("unroll") for (int n = 0; n < 2; ++n) _Pragma("unroll") for (int k = 0; k < 2; ++k) dst[n][k] = *(const LAS bf16x8*)(lds + PG8_SB(b, h) + boff + n * 2048 + k * 1024); } while (0)
; #define PG8_MMA(ai, bj, At, Bt) do { __builtin_amdgcn_s_setprio(1); _Pragma("unroll") for (int m = 0; m < 4; ++m) _Pragma("unroll") for (int n = 0; n < 2; ++n) _Pragma("unroll") for (int k = 0; k < 2; ++k) \
;         acc[ai][bj][m][n] = __builtin_amdgcn_mfma_f32_16x16x32_bf16(Bt[n][k], At[m][k], acc[ai][bj][m][n], 0, 0, 0); __builtin_amdgcn_s_setprio(0); } while (0)
; #define PG8_WAIT_V(n) asm volatile("s_waitcnt vmcnt(" #n ")" ::: "memory")
; #define PG8_WAIT_L(n) asm volatile("s_waitcnt lgkmcnt(" #n ")" ::: "memory")
; #define PG8_BAR __builtin_amdgcn_s_barrier()
; #define PG8_SCHED __builtin_amdgcn_sched_barrier(0)
; template <class Epi, class Ptrs>
; __device__ __forceinline__ void gemm_phase(LAS unsigned char* lds, const int K, const StaticOrder& S, const Ptrs& P, const Epi& E) {
;     ...
;             PG8_LDB(B1, 0, 1); PG8_STAGE(PG8_SB(0, 0), b2, voffB);
;             PG8_BAR; PG8_WAIT_L(0); PG8_MMA(0, 1, At, B1); PG8_BAR;
;             PG8_LDA(At, 0, 1); PG8_STAGE(PG8_SA(0, 0), a2, voffA);
;             PG8_BAR; PG8_WAIT_L(0); PG8_MMA(1, 0, At, B0); PG8_BAR; PG8_SCHED;
;             PG8_STAGE(PG8_SB(0, 1), b2 + hstep, voffB);
;             PG8_WAIT_V(6); PG8_BAR; PG8_MMA(1, 1, At, B1); PG8_BAR;
;             PG8_LDB(B0, 1, 0); PG8_SCHED; PG8_LDA(At, 1, 0); PG8_STAGE(PG8_SA(0, 1), a2 + hstep, voffA);
;             PG8_WAIT_L(8); PG8_BAR; PG8_WAIT_L(0); PG8_MMA(0, 0, At, B0); PG8_BAR; PG8_SCHED;
	s_add_i32 s69, s91, s65
	s_add_u32 s100, s78, 0x80
	s_addc_u32 s101, s79, 0
	s_mov_b32 m0, s69
	ds_read_b128 v[198:201], v207
	ds_read_b128 v[210:213], v207 offset:1024
	ds_read_b128 v[214:217], v207 offset:2048
	ds_read_b128 v[218:221], v207 offset:3072
	global_load_lds_dwordx4 v134, s[78:79]
	s_add_i32 m0, s69, 0x2000
	s_nop 0
	global_load_lds_dwordx4 v138, s[78:79]
	s_barrier
	s_waitcnt lgkmcnt(0)
	s_setprio 1
	s_waitcnt lgkmcnt(0)
	v_mfma_f32_16x16x32_bf16 v[124:127], v[198:201], v[166:169], v[124:127]
	v_mfma_f32_16x16x32_bf16 v[124:127], v[210:213], v[170:173], v[124:127]
	v_mfma_f32_16x16x32_bf16 v[112:115], v[218:221], v[170:173], v[112:115]
	v_mfma_f32_16x16x32_bf16 v[112:115], v[214:217], v[166:169], v[112:115]
	v_mfma_f32_16x16x32_bf16 v[96:99], v[214:217], v[174:177], v[96:99]
	v_mfma_f32_16x16x32_bf16 v[96:99], v[218:221], v[178:181], v[96:99]
	v_mfma_f32_16x16x32_bf16 v[108:111], v[210:213], v[178:181], v[108:111]
	v_mfma_f32_16x16x32_bf16 v[108:111], v[198:201], v[174:177], v[108:111]
	v_mfma_f32_16x16x32_bf16 v[92:95], v[198:201], v[182:185], v[92:95]
	v_mfma_f32_16x16x32_bf16 v[92:95], v[210:213], v[186:189], v[92:95]
	v_mfma_f32_16x16x32_bf16 v[80:83], v[218:221], v[186:189], v[80:83]
	v_mfma_f32_16x16x32_bf16 v[80:83], v[214:217], v[182:185], v[80:83]
	v_mfma_f32_16x16x32_bf16 v[64:67], v[214:217], v[190:193], v[64:67]
	v_mfma_f32_16x16x32_bf16 v[64:67], v[218:221], v[194:197], v[64:67]
	v_mfma_f32_16x16x32_bf16 v[76:79], v[210:213], v[194:197], v[76:79]
	v_mfma_f32_16x16x32_bf16 v[76:79], v[198:201], v[190:193], v[76:79]
	s_setprio 0
	s_mov_b32 m0, s67
	s_barrier
	ds_read_b128 v[166:169], v206 offset:16384
	ds_read_b128 v[170:173], v206 offset:17408
	ds_read_b128 v[174:177], v206 offset:18432
	ds_read_b128 v[178:181], v206 offset:19456
	ds_read_b128 v[182:185], v206 offset:20480
	ds_read_b128 v[186:189], v206 offset:21504
	ds_read_b128 v[190:193], v206 offset:22528
	ds_read_b128 v[194:197], v206 offset:23552
	global_load_lds_dwordx4 v132, s[80:81]
	s_mov_b32 m0, s75
	s_nop 0
	global_load_lds_dwordx4 v136, s[80:81]
	s_barrier
	s_waitcnt lgkmcnt(0)
	s_setprio 1
	s_waitcnt lgkmcnt(0)
	v_mfma_f32_16x16x32_bf16 v[56:59], v[150:153], v[166:169], v[56:59]
	v_mfma_f32_16x16x32_bf16 v[56:59], v[154:157], v[170:173], v[56:59]
	v_mfma_f32_16x16x32_bf16 v[52:55], v[162:165], v[170:173], v[52:55]
	v_mfma_f32_16x16x32_bf16 v[52:55], v[158:161], v[166:169], v[52:55]
	v_mfma_f32_16x16x32_bf16 v[36:39], v[158:161], v[174:177], v[36:39]
	v_mfma_f32_16x16x32_bf16 v[36:39], v[162:165], v[178:181], v[36:39]
	v_mfma_f32_16x16x32_bf16 v[40:43], v[154:157], v[178:181], v[40:43]
	v_mfma_f32_16x16x32_bf16 v[40:43], v[150:153], v[174:177], v[40:43]
	v_mfma_f32_16x16x32_bf16 v[24:27], v[150:153], v[182:185], v[24:27]
	v_mfma_f32_16x16x32_bf16 v[24:27], v[154:157], v[186:189], v[24:27]
	v_mfma_f32_16x16x32_bf16 v[20:23], v[162:165], v[186:189], v[20:23]
	v_mfma_f32_16x16x32_bf16 v[20:23], v[158:161], v[182:185], v[20:23]
	v_mfma_f32_16x16x32_bf16 v[4:7], v[158:161], v[190:193], v[4:7]
	v_mfma_f32_16x16x32_bf16 v[4:7], v[162:165], v[194:197], v[4:7]
	v_mfma_f32_16x16x32_bf16 v[8:11], v[154:157], v[194:197], v[8:11]
	v_mfma_f32_16x16x32_bf16 v[8:11], v[150:153], v[190:193], v[8:11]
	s_setprio 0
	s_barrier
	s_add_u32 s82, s78, 0x40000
	s_addc_u32 s83, s79, 0
	s_add_i32 s69, s92, s65
	s_mov_b32 m0, s69
	s_nop 0
	global_load_lds_dwordx4 v134, s[82:83]
	s_add_i32 m0, s69, 0x2000
	s_nop 0
	global_load_lds_dwordx4 v138, s[82:83]
	s_waitcnt vmcnt(6)
	s_barrier
	s_setprio 1
	v_mfma_f32_16x16x32_bf16 v[60:63], v[198:201], v[166:169], v[60:63]
	v_mfma_f32_16x16x32_bf16 v[60:63], v[210:213], v[170:173], v[60:63]
	v_mfma_f32_16x16x32_bf16 v[48:51], v[218:221], v[170:173], v[48:51]
	v_mfma_f32_16x16x32_bf16 v[48:51], v[214:217], v[166:169], v[48:51]
	v_mfma_f32_16x16x32_bf16 v[32:35], v[214:217], v[174:177], v[32:35]
	v_mfma_f32_16x16x32_bf16 v[32:35], v[218:221], v[178:181], v[32:35]
	v_mfma_f32_16x16x32_bf16 v[44:47], v[210:213], v[178:181], v[44:47]
	v_mfma_f32_16x16x32_bf16 v[44:47], v[198:201], v[174:177], v[44:47]
	v_mfma_f32_16x16x32_bf16 v[28:31], v[198:201], v[182:185], v[28:31]
	v_mfma_f32_16x16x32_bf16 v[28:31], v[210:213], v[186:189], v[28:31]
	v_mfma_f32_16x16x32_bf16 v[16:19], v[218:221], v[186:189], v[16:19]
	v_mfma_f32_16x16x32_bf16 v[16:19], v[214:217], v[182:185], v[16:19]
	v_mfma_f32_16x16x32_bf16 v[0:3], v[214:217], v[190:193], v[0:3]
	v_mfma_f32_16x16x32_bf16 v[0:3], v[218:221], v[194:197], v[0:3]
	v_mfma_f32_16x16x32_bf16 v[12:15], v[210:213], v[194:197], v[12:15]
	v_mfma_f32_16x16x32_bf16 v[12:15], v[198:201], v[190:193], v[12:15]
	s_setprio 0
	s_add_i32 s69, 0, 0x18000
	s_barrier
	ds_read_b128 v[150:153], v252
	ds_read_b128 v[154:157], v252 offset:1024
	ds_read_b128 v[158:161], v252 offset:2048
	ds_read_b128 v[162:165], v252 offset:3072
	s_add_u32 s80, s80, 0x40000
	s_addc_u32 s81, s81, 0
	s_mov_b32 m0, s77
	ds_read_b128 v[166:169], v206 offset:32768
	ds_read_b128 v[170:173], v206 offset:33792
	ds_read_b128 v[174:177], v206 offset:34816
	ds_read_b128 v[178:181], v206 offset:35840
	ds_read_b128 v[182:185], v206 offset:36864
	ds_read_b128 v[186:189], v206 offset:37888
	ds_read_b128 v[190:193], v206 offset:38912
	ds_read_b128 v[194:197], v206 offset:39936
	global_load_lds_dwordx4 v132, s[80:81]
	s_mov_b32 m0, s85
	s_nop 0
	global_load_lds_dwordx4 v136, s[80:81]
	s_waitcnt lgkmcnt(8)
	s_barrier
; #define PG8_WAIT_V(n) asm volatile("s_waitcnt vmcnt(" #n ")" ::: "memory")
; #define PG8_WAIT_L(n) asm volatile("s_waitcnt lgkmcnt(" #n ")" ::: "memory")
; template <class Epi, class Ptrs>
; __device__ __forceinline__ void gemm_phase(LAS unsigned char* lds, const int K, const StaticOrder& S, const Ptrs& P, const Epi& E) {
;     ...
;             PG8_WAIT_L(8); PG8_BAR; PG8_WAIT_L(0); PG8_MMA(0, 0, At, B0); PG8_BAR; PG8_SCHED;
;             PG8_LDB(B1, 1, 1); PG8_STAGE(PG8_SB(1, 0), b3, voffB);
;             PG8_BAR; PG8_WAIT_L(0); PG8_MMA(0, 1, At, B1); PG8_BAR;
;             PG8_LDA(At, 1, 1); PG8_STAGE(PG8_SA(1, 0), a3, voffA);
;             PG8_BAR; PG8_WAIT_L(0); PG8_MMA(1, 0, At, B0); PG8_BAR; PG8_SCHED;
;             PG8_STAGE(PG8_SB(1, 1), b3 + hstep, voffB);
;             PG8_WAIT_V(6); PG8_BAR; PG8_MMA(1, 1, At, B1); PG8_BAR;
;         }
;     __device__ __forceinline__ void operator()(const f32x4 (&acc)[2][2][4][2], const Unit& u, int ui, int wr, int wc, int fr, int fq) const {
;         const int pn = u.pn;
;         if (pn < 8) {
;             bf16_t* base = (bf16_t*)(ws + WS_U) + (size_t)(u.pm * 256 + wr * 64 + fr) * DM + pn * 128 + wc * 32 + 8 * fq;
; #pragma unroll
;             for (int ai = 0; ai < 2; ++ai)
; #pragma unroll
;                 for (int m = 0; m < 4; ++m) {
;                     const f32x4 g0 = g1_4(acc[ai][0][m][0], acc[ai][1][m][0]), g1 = g1_4(acc[ai][0][m][1], acc[ai][1][m][1]);
;                     *(u32x4*)(base + (size_t)(ai * 128 + m * 16) * DM) = pack8(g0, g1); }
;             return; }
;         if (pn >= 17 && pn < 21) {
;             bf16_t* base = (bf16_t*)(dout + DO_GVT) + (size_t)((pn - 17) * 256 + wr * 64 + fr) * MTOK + u.pm * 256 + wc * 32 + 8 * fq;
;             float* pp = (float*)(ws + WS_PART) + (size_t)(u.pm * 256 + wc * 32 + 8 * fq) * 8 + (pn - 17) * 2 + wr;
; #pragma unroll
;             for (int bj = 0; bj < 2; ++bj) { f32x4 sq0 = {0.f, 0.f, 0.f, 0.f}, sq1 = {0.f, 0.f, 0.f, 0.f};
; #pragma unroll
;                 for (int ai = 0; ai < 2; ++ai)
; #pragma unroll
;                     for (int m = 0; m < 4; ++m) { const f32x4 g0 = gelu4(acc[ai][bj][m][0]), g1 = gelu4(acc[ai][bj][m][1]);
;                         sq0 += g0 * g0; sq1 += g1 * g1;
;                         *(u32x4*)(base + (size_t)(ai * 128 + m * 16) * MTOK + bj * 128) = pack8(g0, g1); }
; #pragma unroll
	s_waitcnt lgkmcnt(0)
	s_setprio 1
	s_waitcnt lgkmcnt(0)
	v_mfma_f32_16x16x32_bf16 v[120:123], v[150:153], v[166:169], v[120:123]
	v_mfma_f32_16x16x32_bf16 v[120:123], v[154:157], v[170:173], v[120:123]
	v_mfma_f32_16x16x32_bf16 v[116:119], v[162:165], v[170:173], v[116:119]
	v_mfma_f32_16x16x32_bf16 v[116:119], v[158:161], v[166:169], v[116:119]
	v_mfma_f32_16x16x32_bf16 v[100:103], v[158:161], v[174:177], v[100:103]
	v_mfma_f32_16x16x32_bf16 v[100:103], v[162:165], v[178:181], v[100:103]
	v_mfma_f32_16x16x32_bf16 v[104:107], v[154:157], v[178:181], v[104:107]
	v_mfma_f32_16x16x32_bf16 v[104:107], v[150:153], v[174:177], v[104:107]
	v_mfma_f32_16x16x32_bf16 v[88:91], v[150:153], v[182:185], v[88:91]
	v_mfma_f32_16x16x32_bf16 v[88:91], v[154:157], v[186:189], v[88:91]
	v_mfma_f32_16x16x32_bf16 v[84:87], v[162:165], v[186:189], v[84:87]
	v_mfma_f32_16x16x32_bf16 v[84:87], v[158:161], v[182:185], v[84:87]
	v_mfma_f32_16x16x32_bf16 v[68:71], v[158:161], v[190:193], v[68:71]
	v_mfma_f32_16x16x32_bf16 v[68:71], v[162:165], v[194:197], v[68:71]
	v_mfma_f32_16x16x32_bf16 v[72:75], v[154:157], v[194:197], v[72:75]
	v_mfma_f32_16x16x32_bf16 v[72:75], v[150:153], v[190:193], v[72:75]
	s_setprio 0
	s_barrier
	s_add_i32 s71, 0, 0x1c000
	s_add_i32 s69, s69, s65
	s_mov_b32 m0, s69
	ds_read_b128 v[198:201], v253
	ds_read_b128 v[210:213], v253 offset:1024
	ds_read_b128 v[214:217], v253 offset:2048
	ds_read_b128 v[218:221], v253 offset:3072
	global_load_lds_dwordx4 v134, s[100:101]
	s_add_i32 m0, s69, 0x2000
	s_nop 0
	global_load_lds_dwordx4 v138, s[100:101]
	s_barrier
	s_waitcnt lgkmcnt(0)
	s_setprio 1
	s_waitcnt lgkmcnt(0)
	v_mfma_f32_16x16x32_bf16 v[124:127], v[198:201], v[166:169], v[124:127]
	v_mfma_f32_16x16x32_bf16 v[124:127], v[210:213], v[170:173], v[124:127]
	v_mfma_f32_16x16x32_bf16 v[112:115], v[218:221], v[170:173], v[112:115]
	v_mfma_f32_16x16x32_bf16 v[112:115], v[214:217], v[166:169], v[112:115]
	v_mfma_f32_16x16x32_bf16 v[96:99], v[214:217], v[174:177], v[96:99]
	v_mfma_f32_16x16x32_bf16 v[96:99], v[218:221], v[178:181], v[96:99]
	v_mfma_f32_16x16x32_bf16 v[108:111], v[210:213], v[178:181], v[108:111]
	v_mfma_f32_16x16x32_bf16 v[108:111], v[198:201], v[174:177], v[108:111]
	v_mfma_f32_16x16x32_bf16 v[92:95], v[198:201], v[182:185], v[92:95]
	v_mfma_f32_16x16x32_bf16 v[92:95], v[210:213], v[186:189], v[92:95]
	v_mfma_f32_16x16x32_bf16 v[80:83], v[218:221], v[186:189], v[80:83]
	v_mfma_f32_16x16x32_bf16 v[80:83], v[214:217], v[182:185], v[80:83]
	v_mfma_f32_16x16x32_bf16 v[64:67], v[214:217], v[190:193], v[64:67]
	v_mfma_f32_16x16x32_bf16 v[64:67], v[218:221], v[194:197], v[64:67]
	v_mfma_f32_16x16x32_bf16 v[76:79], v[210:213], v[194:197], v[76:79]
	v_mfma_f32_16x16x32_bf16 v[76:79], v[198:201], v[190:193], v[76:79]
	s_setprio 0
	s_mov_b32 m0, s89
	s_add_u32 s100, s80, 0xfffc0080
	s_addc_u32 s101, s81, -1
	s_barrier
	ds_read_b128 v[166:169], v206 offset:49152
	ds_read_b128 v[170:173], v206 offset:50176
	ds_read_b128 v[174:177], v206 offset:51200
	ds_read_b128 v[178:181], v206 offset:52224
	ds_read_b128 v[182:185], v206 offset:53248
	ds_read_b128 v[186:189], v206 offset:54272
	ds_read_b128 v[190:193], v206 offset:55296
	ds_read_b128 v[194:197], v206 offset:56320
	global_load_lds_dwordx4 v132, s[100:101]
	s_mov_b32 m0, s90
	s_nop 0
	global_load_lds_dwordx4 v136, s[100:101]
	s_barrier
	s_waitcnt lgkmcnt(0)
	s_setprio 1
	s_waitcnt lgkmcnt(0)
	v_mfma_f32_16x16x32_bf16 v[56:59], v[150:153], v[166:169], v[56:59]
	v_mfma_f32_16x16x32_bf16 v[56:59], v[154:157], v[170:173], v[56:59]
	v_mfma_f32_16x16x32_bf16 v[52:55], v[162:165], v[170:173], v[52:55]
	v_mfma_f32_16x16x32_bf16 v[52:55], v[158:161], v[166:169], v[52:55]
	v_mfma_f32_16x16x32_bf16 v[36:39], v[158:161], v[174:177], v[36:39]
	v_mfma_f32_16x16x32_bf16 v[36:39], v[162:165], v[178:181], v[36:39]
	v_mfma_f32_16x16x32_bf16 v[40:43], v[154:157], v[178:181], v[40:43]
	v_mfma_f32_16x16x32_bf16 v[40:43], v[150:153], v[174:177], v[40:43]
	v_mfma_f32_16x16x32_bf16 v[24:27], v[150:153], v[182:185], v[24:27]
	v_mfma_f32_16x16x32_bf16 v[24:27], v[154:157], v[186:189], v[24:27]
	v_mfma_f32_16x16x32_bf16 v[20:23], v[162:165], v[186:189], v[20:23]
	v_mfma_f32_16x16x32_bf16 v[20:23], v[158:161], v[182:185], v[20:23]
	v_mfma_f32_16x16x32_bf16 v[4:7], v[158:161], v[190:193], v[4:7]
	v_mfma_f32_16x16x32_bf16 v[4:7], v[162:165], v[194:197], v[4:7]
	v_mfma_f32_16x16x32_bf16 v[8:11], v[154:157], v[194:197], v[8:11]
	v_mfma_f32_16x16x32_bf16 v[8:11], v[150:153], v[190:193], v[8:11]
	s_setprio 0
	s_barrier
	s_add_u32 s78, s78, 0x40080
	s_addc_u32 s79, s79, 0
	s_add_i32 s69, s71, s65
	s_mov_b32 m0, s69
	s_nop 0
	global_load_lds_dwordx4 v134, s[78:79]
	s_add_i32 m0, s69, 0x2000
	s_nop 0
	global_load_lds_dwordx4 v138, s[78:79]
	s_waitcnt vmcnt(6)
	s_barrier
	s_setprio 1
	v_mfma_f32_16x16x32_bf16 v[60:63], v[198:201], v[166:169], v[60:63]
	v_mfma_f32_16x16x32_bf16 v[60:63], v[210:213], v[170:173], v[60:63]
	v_mfma_f32_16x16x32_bf16 v[48:51], v[218:221], v[170:173], v[48:51]
	v_mfma_f32_16x16x32_bf16 v[48:51], v[214:217], v[166:169], v[48:51]
	v_mfma_f32_16x16x32_bf16 v[32:35], v[214:217], v[174:177], v[32:35]
	v_mfma_f32_16x16x32_bf16 v[32:35], v[218:221], v[178:181], v[32:35]
	v_mfma_f32_16x16x32_bf16 v[44:47], v[210:213], v[178:181], v[44:47]
	v_mfma_f32_16x16x32_bf16 v[44:47], v[198:201], v[174:177], v[44:47]
	v_mfma_f32_16x16x32_bf16 v[28:31], v[198:201], v[182:185], v[28:31]
	v_mfma_f32_16x16x32_bf16 v[28:31], v[210:213], v[186:189], v[28:31]
	v_mfma_f32_16x16x32_bf16 v[16:19], v[218:221], v[186:189], v[16:19]
	v_mfma_f32_16x16x32_bf16 v[16:19], v[214:217], v[182:185], v[16:19]
	v_mfma_f32_16x16x32_bf16 v[0:3], v[214:217], v[190:193], v[0:3]
	v_mfma_f32_16x16x32_bf16 v[0:3], v[218:221], v[194:197], v[0:3]
	v_mfma_f32_16x16x32_bf16 v[12:15], v[210:213], v[194:197], v[12:15]
	v_mfma_f32_16x16x32_bf16 v[12:15], v[198:201], v[190:193], v[12:15]
	s_setprio 0
	s_add_i32 s63, s63, 2
	s_add_u32 s6, s6, 0x100
	s_addc_u32 s7, s7, 0
	s_add_u32 s20, s20, 0x100
	s_addc_u32 s25, s25, 0
	s_cmp_gt_u32 s63, 13
	s_barrier
	s_cbranch_scc0 .LBB0_127
	s_nop 0
	s_nop 0
	s_nop 0
	s_nop 0
	s_nop 0
	s_nop 0
	s_nop 0
	s_nop 0
	s_nop 0
	s_nop 0
	s_nop 0
	s_nop 0
	s_nop 0
	s_nop 0
	s_nop 0
	s_nop 0
	s_nop 0
	s_nop 0
	s_nop 0
	s_nop 0
	s_nop 0
	s_nop 0
	s_nop 0
	s_nop 0
	s_nop 0
	s_nop 0
	s_nop 0
	s_nop 0
	s_nop 0
	s_cmp_gt_i32 s74, 7
	s_mov_b64 s[6:7], -1
	s_cbranch_scc0 .LBB0_188
	s_sub_i32 s25, s74, 17
	s_cmp_gt_u32 s25, 3
	s_cbranch_scc0 .LBB0_170
	s_lshl_b32 s69, s76, 8
	s_cmp_gt_u32 s74, 11
	s_cbranch_scc0 .LBB0_135
	s_cmp_eq_u32 s74, 12
	s_mov_b64 s[6:7], 0
	s_cbranch_scc1 .LBB0_134
	s_cmp_gt_u32 s74, 16
	s_cbranch_scc1 .LBB0_191
	s_lshl_b32 s20, s74, 8
	v_readlane_b32 s80, v254, 2
	s_addk_i32 s20, 0xf300
	s_mov_b64 s[78:79], 0x400
	s_mov_b64 s[82:83], -1
	s_mov_b32 s63, s69
	v_readlane_b32 s81, v254, 3
	s_andn2_b64 vcc, exec, s[6:7]
	s_cbranch_vccz .LBB0_136
	s_branch .LBB0_137

; #define PG8_STAGE(bufoff, gbase, voff) do { _Pragma("unroll") for (int _i = 0; _i < 2; ++_i) \
;         __builtin_amdgcn_global_load_lds((const unsigned*)((const char*)(gbase) + (voff)[_i]), (LAS unsigned*)(lds + (bufoff) + ldsw + _i * 8192), 16, 0, 0); } while (0)
; #define PG8_LDA(dst, b, h) do { _Pragma("unroll") for (int m = 0; m < 4; ++m) _Pragma("unroll") for (int k = 0; k < 2; ++k) dst[m][k] = *(const LAS bf16x8*)(lds + PG8_SA(b, h) + aoff + m * 2048 + k * 1024); } while (0)
; #define PG8_LDB(dst, b, h) do { _Pragma("unroll") for (int n = 0; n < 2; ++n) _Pragma("unroll") for (int k = 0; k < 2; ++k) dst[n][k] = *(const LAS bf16x8*)(lds + PG8_SB(b, h) + boff + n * 2048 + k * 1024); } while (0)
; #define PG8_MMA(ai, bj, At, Bt) do { __builtin_amdgcn_s_setprio(1); _Pragma("unroll") for (int m = 0; m < 4; ++m) _Pragma("unroll") for (int n = 0; n < 2; ++n) _Pragma("unroll") for (int k = 0; k < 2; ++k) \
;         acc[ai][bj][m][n] = __builtin_amdgcn_mfma_f32_16x16x32_bf16(Bt[n][k], At[m][k], acc[ai][bj][m][n], 0, 0, 0); __builtin_amdgcn_s_setprio(0); } while (0)
; #define PG8_WAIT_L(n) asm volatile("s_waitcnt lgkmcnt(" #n ")" ::: "memory")
; #define PG8_BAR __builtin_amdgcn_s_barrier()
; #define PG8_SCHED __builtin_amdgcn_sched_barrier(0)
; template <class Epi, class Ptrs>
; __device__ __forceinline__ void gemm_phase(LAS unsigned char* lds, const int K, const StaticOrder& S, const Ptrs& P, const Epi& E) {
;     ...
;         for (int t = 0; t < nt; t += 2) {
;             const bool last = (t == nt - 2);
;             const char* a1 = cA + (size_t)(t + 1) * kstep;
;             const char* a2 = last ? nA : cA + (size_t)(t + 2) * kstep; const char* b2 = last ? nB : cB + (size_t)(t + 2) * kstep;
;             const char* a3 = a2 + kstep; const char* b3 = b2 + kstep;
;             PG8_LDB(B0, 0, 0); PG8_SCHED; PG8_LDA(At, 0, 0); PG8_STAGE(PG8_SA(1, 1), a1 + hstep, voffA);
;             PG8_WAIT_L(8); PG8_BAR; PG8_WAIT_L(0); PG8_MMA(0, 0, At, B0); PG8_BAR; PG8_SCHED;
;     ...
; #pragma unroll
;         for (int a = 0; a < 2; ++a)
; #pragma unroll
;             for (int b = 0; b < 2; ++b)
; #pragma unroll
;                 for (int m = 0; m < 4; ++m)
; #pragma unroll
;                     for (int n = 0; n < 2; ++n) acc[a][b][m][n] = (f32x4){0.f, 0.f, 0.f, 0.f};
;         cur = nxt; cA = nA; cB = nB; ++ui;
.LBB0_352:
	s_add_u32 s38, s44, 0x40080
	s_nop 0
	s_nop 0
	s_nop 0
	s_nop 0
	s_nop 0
	s_nop 0
	s_nop 0
	s_nop 0
	s_nop 0
	s_nop 0
	s_nop 0
	s_nop 0
	s_nop 0
	s_nop 0
	s_nop 0
	s_nop 0
	s_nop 0
	s_nop 0
	s_nop 0
	s_nop 0
	s_nop 0
	s_nop 0
	s_nop 0
	s_nop 0
	s_nop 0
	s_nop 0
	s_nop 0
	s_nop 0
	s_nop 0
	s_nop 0
	s_nop 0
	s_nop 0
	s_nop 0
	s_nop 0
	s_nop 0
	s_nop 0
	s_nop 0
	s_nop 0
	s_nop 0
	s_nop 0
	s_nop 0
	s_nop 0
	s_nop 0
	s_nop 0
	s_nop 0
	s_nop 0
	s_nop 0
	s_nop 0
	s_nop 0
	s_nop 0
	s_nop 0
	s_nop 0
	s_nop 0
	s_nop 0
	s_nop 0
	s_nop 0
	s_nop 0
	s_nop 0
	s_nop 0
	s_nop 0
	s_nop 0
	s_nop 0
	s_nop 0
	s_addc_u32 s39, s45, 0
	s_add_u32 s21, s42, 0x100
	v_mov_b32_e32 v0, 0
	s_addc_u32 s23, s43, 0
	s_mov_b32 s41, -2
	v_mov_b32_e32 v1, v0
	v_mov_b32_e32 v2, v0
	v_mov_b32_e32 v3, v0
	v_mov_b32_e32 v4, v0
	v_mov_b32_e32 v5, v0
	v_mov_b32_e32 v6, v0
	v_mov_b32_e32 v7, v0
	v_mov_b32_e32 v16, v0
	v_mov_b32_e32 v17, v0
	v_mov_b32_e32 v18, v0
	v_mov_b32_e32 v19, v0
	v_mov_b32_e32 v20, v0
	v_mov_b32_e32 v21, v0
	v_mov_b32_e32 v22, v0
	v_mov_b32_e32 v23, v0
	v_mov_b32_e32 v32, v0
	v_mov_b32_e32 v33, v0
	v_mov_b32_e32 v34, v0
	v_mov_b32_e32 v35, v0
	v_mov_b32_e32 v36, v0
	v_mov_b32_e32 v37, v0
	v_mov_b32_e32 v38, v0
	v_mov_b32_e32 v39, v0
	v_mov_b32_e32 v48, v0
	v_mov_b32_e32 v49, v0
	v_mov_b32_e32 v50, v0
	v_mov_b32_e32 v51, v0
	v_mov_b32_e32 v52, v0
	v_mov_b32_e32 v53, v0
	v_mov_b32_e32 v54, v0
	v_mov_b32_e32 v55, v0
	v_mov_b32_e32 v8, v0
	v_mov_b32_e32 v9, v0
	v_mov_b32_e32 v10, v0
	v_mov_b32_e32 v11, v0
	v_mov_b32_e32 v12, v0
	v_mov_b32_e32 v13, v0
	v_mov_b32_e32 v14, v0
	v_mov_b32_e32 v15, v0
	v_mov_b32_e32 v24, v0
	v_mov_b32_e32 v25, v0
	v_mov_b32_e32 v26, v0
	v_mov_b32_e32 v27, v0
	v_mov_b32_e32 v28, v0
	v_mov_b32_e32 v29, v0
	v_mov_b32_e32 v30, v0
	v_mov_b32_e32 v31, v0
	v_mov_b32_e32 v40, v0
	v_mov_b32_e32 v41, v0
	v_mov_b32_e32 v42, v0
	v_mov_b32_e32 v43, v0
	v_mov_b32_e32 v44, v0
	v_mov_b32_e32 v45, v0
	v_mov_b32_e32 v46, v0
	v_mov_b32_e32 v47, v0
	v_mov_b32_e32 v56, v0
	v_mov_b32_e32 v57, v0
	v_mov_b32_e32 v58, v0
	v_mov_b32_e32 v59, v0
	v_mov_b32_e32 v60, v0
	v_mov_b32_e32 v61, v0
	v_mov_b32_e32 v62, v0
	v_mov_b32_e32 v63, v0
	v_mov_b32_e32 v64, v0
	v_mov_b32_e32 v65, v0
	v_mov_b32_e32 v66, v0
	v_mov_b32_e32 v67, v0
	v_mov_b32_e32 v68, v0
	v_mov_b32_e32 v69, v0
	v_mov_b32_e32 v70, v0
	v_mov_b32_e32 v71, v0
	v_mov_b32_e32 v80, v0
	v_mov_b32_e32 v81, v0
	v_mov_b32_e32 v82, v0
	v_mov_b32_e32 v83, v0
	v_mov_b32_e32 v84, v0
	v_mov_b32_e32 v85, v0
	v_mov_b32_e32 v86, v0
	v_mov_b32_e32 v87, v0
	v_mov_b32_e32 v96, v0
	v_mov_b32_e32 v97, v0
	v_mov_b32_e32 v98, v0
	v_mov_b32_e32 v99, v0
	v_mov_b32_e32 v100, v0
	v_mov_b32_e32 v101, v0
	v_mov_b32_e32 v102, v0
	v_mov_b32_e32 v103, v0
	v_mov_b32_e32 v112, v0
	v_mov_b32_e32 v113, v0
	v_mov_b32_e32 v114, v0
	v_mov_b32_e32 v115, v0
	v_mov_b32_e32 v116, v0
	v_mov_b32_e32 v117, v0
	v_mov_b32_e32 v118, v0
	v_mov_b32_e32 v119, v0
	v_mov_b32_e32 v72, v0
	v_mov_b32_e32 v73, v0
	v_mov_b32_e32 v74, v0
	v_mov_b32_e32 v75, v0
	v_mov_b32_e32 v76, v0
	v_mov_b32_e32 v77, v0
	v_mov_b32_e32 v78, v0
	v_mov_b32_e32 v79, v0
	v_mov_b32_e32 v88, v0
	v_mov_b32_e32 v89, v0
	v_mov_b32_e32 v90, v0
	v_mov_b32_e32 v91, v0
	v_mov_b32_e32 v92, v0
	v_mov_b32_e32 v93, v0
	v_mov_b32_e32 v94, v0
	v_mov_b32_e32 v95, v0
	v_mov_b32_e32 v104, v0
	v_mov_b32_e32 v105, v0
	v_mov_b32_e32 v106, v0
	v_mov_b32_e32 v107, v0
	v_mov_b32_e32 v108, v0
	v_mov_b32_e32 v109, v0
	v_mov_b32_e32 v110, v0
	v_mov_b32_e32 v111, v0
	v_mov_b32_e32 v120, v0
	v_mov_b32_e32 v121, v0
	v_mov_b32_e32 v122, v0
	v_mov_b32_e32 v123, v0
	v_mov_b32_e32 v124, v0
	v_mov_b32_e32 v125, v0
	v_mov_b32_e32 v126, v0
	v_mov_b32_e32 v127, v0
	v_add_u32_e32 v252, 0x18000, v205
	v_add_u32_e32 v253, 0x1c000, v205
.LBB0_353:
	ds_read_b128 v[128:131], v207
	ds_read_b128 v[132:135], v207 offset:1024
	ds_read_b128 v[136:139], v207 offset:2048
	ds_read_b128 v[140:143], v207 offset:3072
	s_add_u32 s42, s38, 0xfffc0080
	s_addc_u32 s43, s39, -1
	s_cmp_eq_u32 s41, 12
	s_cselect_b32 s45, s1, s43
	s_cselect_b32 s44, s0, s42
	s_cselect_b32 s43, s25, s23
	s_cselect_b32 s42, s24, s21
	s_add_i32 m0, s54, 0xc000
	ds_read_b128 v[144:147], v209
	ds_read_b128 v[148:151], v209 offset:1024
	ds_read_b128 v[152:155], v209 offset:2048
	ds_read_b128 v[156:159], v209 offset:3072
	ds_read_b128 v[160:163], v209 offset:4096
	ds_read_b128 v[164:167], v209 offset:5120
	ds_read_b128 v[168:171], v209 offset:6144
	ds_read_b128 v[172:175], v209 offset:7168
	global_load_lds_dwordx4 v184, s[38:39]
	s_add_i32 m0, s54, 0xe000
	s_nop 0
	global_load_lds_dwordx4 v186, s[38:39]
	s_waitcnt lgkmcnt(8)
	s_barrier
	s_waitcnt lgkmcnt(0)
	s_setprio 1
	s_waitcnt lgkmcnt(0)
	v_mfma_f32_16x16x32_bf16 v[124:127], v[128:131], v[144:147], v[124:127]
	v_mfma_f32_16x16x32_bf16 v[124:127], v[132:135], v[148:151], v[124:127]
	v_mfma_f32_16x16x32_bf16 v[120:123], v[140:143], v[148:151], v[120:123]
	v_mfma_f32_16x16x32_bf16 v[120:123], v[136:139], v[144:147], v[120:123]
	v_mfma_f32_16x16x32_bf16 v[104:107], v[136:139], v[152:155], v[104:107]
	v_mfma_f32_16x16x32_bf16 v[104:107], v[140:143], v[156:159], v[104:107]
	v_mfma_f32_16x16x32_bf16 v[108:111], v[132:135], v[156:159], v[108:111]
	v_mfma_f32_16x16x32_bf16 v[108:111], v[128:131], v[152:155], v[108:111]
	v_mfma_f32_16x16x32_bf16 v[92:95], v[128:131], v[160:163], v[92:95]
	v_mfma_f32_16x16x32_bf16 v[92:95], v[132:135], v[164:167], v[92:95]
	v_mfma_f32_16x16x32_bf16 v[88:91], v[140:143], v[164:167], v[88:91]
	v_mfma_f32_16x16x32_bf16 v[88:91], v[136:139], v[160:163], v[88:91]
	v_mfma_f32_16x16x32_bf16 v[72:75], v[136:139], v[168:171], v[72:75]
	v_mfma_f32_16x16x32_bf16 v[72:75], v[140:143], v[172:175], v[72:75]
	v_mfma_f32_16x16x32_bf16 v[76:79], v[132:135], v[172:175], v[76:79]
	v_mfma_f32_16x16x32_bf16 v[76:79], v[128:131], v[168:171], v[76:79]
	s_setprio 0
	s_barrier
; #define PG8_STAGE(bufoff, gbase, voff) do { _Pragma("unroll") for (int _i = 0; _i < 2; ++_i) \
;         __builtin_amdgcn_global_load_lds((const unsigned*)((const char*)(gbase) + (voff)[_i]), (LAS unsigned*)(lds + (bufoff) + ldsw + _i * 8192), 16, 0, 0); } while (0)
; #define PG8_LDA(dst, b, h) do { _Pragma("unroll") for (int m = 0; m < 4; ++m) _Pragma("unroll") for (int k = 0; k < 2; ++k) dst[m][k] = *(const LAS bf16x8*)(lds + PG8_SA(b, h) + aoff + m * 2048 + k * 1024); } while (0)
; #define PG8_LDB(dst, b, h) do { _Pragma("unroll") for (int n = 0; n < 2; ++n) _Pragma("unroll") for (int k = 0; k < 2; ++k) dst[n][k] = *(const LAS bf16x8*)(lds + PG8_SB(b, h) + boff + n * 2048 + k * 1024); } while (0)
; #define PG8_MMA(ai, bj, At, Bt) do { __builtin_amdgcn_s_setprio(1); _Pragma("unroll") for (int m = 0; m < 4; ++m) _Pragma("unroll") for (int n = 0; n < 2; ++n) _Pragma("unroll") for (int k = 0; k < 2; ++k) \
;         acc[ai][bj][m][n] = __builtin_amdgcn_mfma_f32_16x16x32_bf16(Bt[n][k], At[m][k], acc[ai][bj][m][n], 0, 0, 0); __builtin_amdgcn_s_setprio(0); } while (0)
; #define PG8_WAIT_V(n) asm volatile("s_waitcnt vmcnt(" #n ")" ::: "memory")
; #define PG8_WAIT_L(n) asm volatile("s_waitcnt lgkmcnt(" #n ")" ::: "memory")
; #define PG8_BAR __builtin_amdgcn_s_barrier()
; #define PG8_SCHED __builtin_amdgcn_sched_barrier(0)
; template <class Epi, class Ptrs>
; __device__ __forceinline__ void gemm_phase(LAS unsigned char* lds, const int K, const StaticOrder& S, const Ptrs& P, const Epi& E) {
;     ...
;             PG8_LDB(B1, 0, 1); PG8_STAGE(PG8_SB(0, 0), b2, voffB);
;             PG8_BAR; PG8_WAIT_L(0); PG8_MMA(0, 1, At, B1); PG8_BAR;
;             PG8_LDA(At, 0, 1); PG8_STAGE(PG8_SA(0, 0), a2, voffA);
;             PG8_BAR; PG8_WAIT_L(0); PG8_MMA(1, 0, At, B0); PG8_BAR; PG8_SCHED;
;             PG8_STAGE(PG8_SB(0, 1), b2 + hstep, voffB);
;             PG8_WAIT_V(6); PG8_BAR; PG8_MMA(1, 1, At, B1); PG8_BAR;
;             PG8_LDB(B0, 1, 0); PG8_SCHED; PG8_LDA(At, 1, 0); PG8_STAGE(PG8_SA(0, 1), a2 + hstep, voffA);
;             PG8_WAIT_L(8); PG8_BAR; PG8_WAIT_L(0); PG8_MMA(0, 0, At, B0); PG8_BAR; PG8_SCHED;
	s_add_i32 s69, s66, s51
	s_add_u32 s90, s42, 0x80
	s_addc_u32 s91, s43, 0
	s_mov_b32 m0, s69
	ds_read_b128 v[192:195], v210
	ds_read_b128 v[196:199], v210 offset:1024
	ds_read_b128 v[200:203], v210 offset:2048
	ds_read_b128 v[212:215], v210 offset:3072
	global_load_lds_dwordx4 v178, s[42:43]
	s_add_i32 m0, s69, 0x2000
	s_nop 0
	global_load_lds_dwordx4 v182, s[42:43]
	s_barrier
	s_waitcnt lgkmcnt(0)
	s_setprio 1
	s_waitcnt lgkmcnt(0)
	v_mfma_f32_16x16x32_bf16 v[116:119], v[192:195], v[144:147], v[116:119]
	v_mfma_f32_16x16x32_bf16 v[116:119], v[196:199], v[148:151], v[116:119]
	v_mfma_f32_16x16x32_bf16 v[112:115], v[212:215], v[148:151], v[112:115]
	v_mfma_f32_16x16x32_bf16 v[112:115], v[200:203], v[144:147], v[112:115]
	v_mfma_f32_16x16x32_bf16 v[96:99], v[200:203], v[152:155], v[96:99]
	v_mfma_f32_16x16x32_bf16 v[96:99], v[212:215], v[156:159], v[96:99]
	v_mfma_f32_16x16x32_bf16 v[100:103], v[196:199], v[156:159], v[100:103]
	v_mfma_f32_16x16x32_bf16 v[100:103], v[192:195], v[152:155], v[100:103]
	v_mfma_f32_16x16x32_bf16 v[84:87], v[192:195], v[160:163], v[84:87]
	v_mfma_f32_16x16x32_bf16 v[84:87], v[196:199], v[164:167], v[84:87]
	v_mfma_f32_16x16x32_bf16 v[80:83], v[212:215], v[164:167], v[80:83]
	v_mfma_f32_16x16x32_bf16 v[80:83], v[200:203], v[160:163], v[80:83]
	v_mfma_f32_16x16x32_bf16 v[64:67], v[200:203], v[168:171], v[64:67]
	v_mfma_f32_16x16x32_bf16 v[64:67], v[212:215], v[172:175], v[64:67]
	v_mfma_f32_16x16x32_bf16 v[68:71], v[196:199], v[172:175], v[68:71]
	v_mfma_f32_16x16x32_bf16 v[68:71], v[192:195], v[168:171], v[68:71]
	s_setprio 0
	s_mov_b32 m0, s54
	s_add_u32 s92, s44, 0x80
	s_addc_u32 s93, s45, 0
	s_barrier
	ds_read_b128 v[144:147], v209 offset:16384
	ds_read_b128 v[148:151], v209 offset:17408
	ds_read_b128 v[152:155], v209 offset:18432
	ds_read_b128 v[156:159], v209 offset:19456
	ds_read_b128 v[160:163], v209 offset:20480
	ds_read_b128 v[164:167], v209 offset:21504
	ds_read_b128 v[168:171], v209 offset:22528
	ds_read_b128 v[172:175], v209 offset:23552
	global_load_lds_dwordx4 v176, s[44:45]
	s_mov_b32 m0, s55
	s_nop 0
	global_load_lds_dwordx4 v180, s[44:45]
	s_barrier
	s_waitcnt lgkmcnt(0)
	s_setprio 1
	s_waitcnt lgkmcnt(0)
	v_mfma_f32_16x16x32_bf16 v[60:63], v[128:131], v[144:147], v[60:63]
	v_mfma_f32_16x16x32_bf16 v[60:63], v[132:135], v[148:151], v[60:63]
	v_mfma_f32_16x16x32_bf16 v[56:59], v[140:143], v[148:151], v[56:59]
	v_mfma_f32_16x16x32_bf16 v[56:59], v[136:139], v[144:147], v[56:59]
	v_mfma_f32_16x16x32_bf16 v[40:43], v[136:139], v[152:155], v[40:43]
	v_mfma_f32_16x16x32_bf16 v[40:43], v[140:143], v[156:159], v[40:43]
	v_mfma_f32_16x16x32_bf16 v[44:47], v[132:135], v[156:159], v[44:47]
	v_mfma_f32_16x16x32_bf16 v[44:47], v[128:131], v[152:155], v[44:47]
	v_mfma_f32_16x16x32_bf16 v[28:31], v[128:131], v[160:163], v[28:31]
	v_mfma_f32_16x16x32_bf16 v[28:31], v[132:135], v[164:167], v[28:31]
	v_mfma_f32_16x16x32_bf16 v[24:27], v[140:143], v[164:167], v[24:27]
	v_mfma_f32_16x16x32_bf16 v[24:27], v[136:139], v[160:163], v[24:27]
	v_mfma_f32_16x16x32_bf16 v[8:11], v[136:139], v[168:171], v[8:11]
	v_mfma_f32_16x16x32_bf16 v[8:11], v[140:143], v[172:175], v[8:11]
	v_mfma_f32_16x16x32_bf16 v[12:15], v[132:135], v[172:175], v[12:15]
	v_mfma_f32_16x16x32_bf16 v[12:15], v[128:131], v[168:171], v[12:15]
	s_setprio 0
	s_barrier
	s_add_u32 s70, s42, 0x40000
	s_addc_u32 s71, s43, 0
	s_add_i32 s69, s67, s51
	s_mov_b32 m0, s69
	s_nop 0
	global_load_lds_dwordx4 v178, s[70:71]
	s_add_i32 m0, s69, 0x2000
	s_nop 0
	global_load_lds_dwordx4 v182, s[70:71]
	s_waitcnt vmcnt(6)
	s_barrier
	s_setprio 1
	v_mfma_f32_16x16x32_bf16 v[52:55], v[192:195], v[144:147], v[52:55]
	v_mfma_f32_16x16x32_bf16 v[52:55], v[196:199], v[148:151], v[52:55]
	v_mfma_f32_16x16x32_bf16 v[48:51], v[212:215], v[148:151], v[48:51]
	v_mfma_f32_16x16x32_bf16 v[48:51], v[200:203], v[144:147], v[48:51]
	v_mfma_f32_16x16x32_bf16 v[32:35], v[200:203], v[152:155], v[32:35]
	v_mfma_f32_16x16x32_bf16 v[32:35], v[212:215], v[156:159], v[32:35]
	v_mfma_f32_16x16x32_bf16 v[36:39], v[196:199], v[156:159], v[36:39]
	v_mfma_f32_16x16x32_bf16 v[36:39], v[192:195], v[152:155], v[36:39]
	v_mfma_f32_16x16x32_bf16 v[20:23], v[192:195], v[160:163], v[20:23]
	v_mfma_f32_16x16x32_bf16 v[20:23], v[196:199], v[164:167], v[20:23]
	v_mfma_f32_16x16x32_bf16 v[16:19], v[212:215], v[164:167], v[16:19]
	v_mfma_f32_16x16x32_bf16 v[16:19], v[200:203], v[160:163], v[16:19]
	v_mfma_f32_16x16x32_bf16 v[0:3], v[200:203], v[168:171], v[0:3]
	v_mfma_f32_16x16x32_bf16 v[0:3], v[212:215], v[172:175], v[0:3]
	v_mfma_f32_16x16x32_bf16 v[4:7], v[196:199], v[172:175], v[4:7]
	v_mfma_f32_16x16x32_bf16 v[4:7], v[192:195], v[168:171], v[4:7]
	s_setprio 0
	s_add_i32 s69, 0, 0x18000
	s_barrier
	ds_read_b128 v[128:131], v252
	ds_read_b128 v[132:135], v252 offset:1024
	ds_read_b128 v[136:139], v252 offset:2048
	ds_read_b128 v[140:143], v252 offset:3072
	s_add_u32 s44, s44, 0x40000
	s_addc_u32 s45, s45, 0
	s_mov_b32 m0, s56
	ds_read_b128 v[144:147], v209 offset:32768
	ds_read_b128 v[148:151], v209 offset:33792
	ds_read_b128 v[152:155], v209 offset:34816
	ds_read_b128 v[156:159], v209 offset:35840
	ds_read_b128 v[160:163], v209 offset:36864
	ds_read_b128 v[164:167], v209 offset:37888
	ds_read_b128 v[168:171], v209 offset:38912
	ds_read_b128 v[172:175], v209 offset:39936
	global_load_lds_dwordx4 v176, s[44:45]
	s_mov_b32 m0, s57
	s_nop 0
	global_load_lds_dwordx4 v180, s[44:45]
	s_waitcnt lgkmcnt(8)
	s_barrier
; #define PG8_STAGE(bufoff, gbase, voff) do { _Pragma("unroll") for (int _i = 0; _i < 2; ++_i) \
;         __builtin_amdgcn_global_load_lds((const unsigned*)((const char*)(gbase) + (voff)[_i]), (LAS unsigned*)(lds + (bufoff) + ldsw + _i * 8192), 16, 0, 0); } while (0)
; #define PG8_LDA(dst, b, h) do { _Pragma("unroll") for (int m = 0; m < 4; ++m) _Pragma("unroll") for (int k = 0; k < 2; ++k) dst[m][k] = *(const LAS bf16x8*)(lds + PG8_SA(b, h) + aoff + m * 2048 + k * 1024); } while (0)
; #define PG8_LDB(dst, b, h) do { _Pragma("unroll") for (int n = 0; n < 2; ++n) _Pragma("unroll") for (int k = 0; k < 2; ++k) dst[n][k] = *(const LAS bf16x8*)(lds + PG8_SB(b, h) + boff + n * 2048 + k * 1024); } while (0)
; #define PG8_MMA(ai, bj, At, Bt) do { __builtin_amdgcn_s_setprio(1); _Pragma("unroll") for (int m = 0; m < 4; ++m) _Pragma("unroll") for (int n = 0; n < 2; ++n) _Pragma("unroll") for (int k = 0; k < 2; ++k) \
;         acc[ai][bj][m][n] = __builtin_amdgcn_mfma_f32_16x16x32_bf16(Bt[n][k], At[m][k], acc[ai][bj][m][n], 0, 0, 0); __builtin_amdgcn_s_setprio(0); } while (0)
; #define PG8_WAIT_V(n) asm volatile("s_waitcnt vmcnt(" #n ")" ::: "memory")
; #define PG8_WAIT_L(n) asm volatile("s_waitcnt lgkmcnt(" #n ")" ::: "memory")
; #define PG8_BAR __builtin_amdgcn_s_barrier()
; #define PG8_SCHED __builtin_amdgcn_sched_barrier(0)
; template <class Epi, class Ptrs>
; __device__ __forceinline__ void gemm_phase(LAS unsigned char* lds, const int K, const StaticOrder& S, const Ptrs& P, const Epi& E) {
;     ...
;             PG8_WAIT_L(8); PG8_BAR; PG8_WAIT_L(0); PG8_MMA(0, 0, At, B0); PG8_BAR; PG8_SCHED;
;             PG8_LDB(B1, 1, 1); PG8_STAGE(PG8_SB(1, 0), b3, voffB);
;             PG8_BAR; PG8_WAIT_L(0); PG8_MMA(0, 1, At, B1); PG8_BAR;
;             PG8_LDA(At, 1, 1); PG8_STAGE(PG8_SA(1, 0), a3, voffA);
;             PG8_BAR; PG8_WAIT_L(0); PG8_MMA(1, 0, At, B0); PG8_BAR; PG8_SCHED;
;             PG8_STAGE(PG8_SB(1, 1), b3 + hstep, voffB);
;             PG8_WAIT_V(6); PG8_BAR; PG8_MMA(1, 1, At, B1); PG8_BAR;
	s_waitcnt lgkmcnt(0)
	s_setprio 1
	s_waitcnt lgkmcnt(0)
	v_mfma_f32_16x16x32_bf16 v[124:127], v[128:131], v[144:147], v[124:127]
	v_mfma_f32_16x16x32_bf16 v[124:127], v[132:135], v[148:151], v[124:127]
	v_mfma_f32_16x16x32_bf16 v[120:123], v[140:143], v[148:151], v[120:123]
	v_mfma_f32_16x16x32_bf16 v[120:123], v[136:139], v[144:147], v[120:123]
	v_mfma_f32_16x16x32_bf16 v[104:107], v[136:139], v[152:155], v[104:107]
	v_mfma_f32_16x16x32_bf16 v[104:107], v[140:143], v[156:159], v[104:107]
	v_mfma_f32_16x16x32_bf16 v[108:111], v[132:135], v[156:159], v[108:111]
	v_mfma_f32_16x16x32_bf16 v[108:111], v[128:131], v[152:155], v[108:111]
	v_mfma_f32_16x16x32_bf16 v[92:95], v[128:131], v[160:163], v[92:95]
	v_mfma_f32_16x16x32_bf16 v[92:95], v[132:135], v[164:167], v[92:95]
	v_mfma_f32_16x16x32_bf16 v[88:91], v[140:143], v[164:167], v[88:91]
	v_mfma_f32_16x16x32_bf16 v[88:91], v[136:139], v[160:163], v[88:91]
	v_mfma_f32_16x16x32_bf16 v[72:75], v[136:139], v[168:171], v[72:75]
	v_mfma_f32_16x16x32_bf16 v[72:75], v[140:143], v[172:175], v[72:75]
	v_mfma_f32_16x16x32_bf16 v[76:79], v[132:135], v[172:175], v[76:79]
	v_mfma_f32_16x16x32_bf16 v[76:79], v[128:131], v[168:171], v[76:79]
	s_setprio 0
	s_barrier
	s_add_i32 s44, 0, 0x1c000
	s_add_i32 s45, s69, s51
	s_mov_b32 m0, s45
	ds_read_b128 v[192:195], v253
	ds_read_b128 v[196:199], v253 offset:1024
	ds_read_b128 v[200:203], v253 offset:2048
	ds_read_b128 v[212:215], v253 offset:3072
	global_load_lds_dwordx4 v178, s[90:91]
	s_add_i32 m0, s45, 0x2000
	s_nop 0
	global_load_lds_dwordx4 v182, s[90:91]
	s_barrier
	s_waitcnt lgkmcnt(0)
	s_setprio 1
	s_waitcnt lgkmcnt(0)
	v_mfma_f32_16x16x32_bf16 v[116:119], v[192:195], v[144:147], v[116:119]
	v_mfma_f32_16x16x32_bf16 v[116:119], v[196:199], v[148:151], v[116:119]
	v_mfma_f32_16x16x32_bf16 v[112:115], v[212:215], v[148:151], v[112:115]
	v_mfma_f32_16x16x32_bf16 v[112:115], v[200:203], v[144:147], v[112:115]
	v_mfma_f32_16x16x32_bf16 v[96:99], v[200:203], v[152:155], v[96:99]
	v_mfma_f32_16x16x32_bf16 v[96:99], v[212:215], v[156:159], v[96:99]
	v_mfma_f32_16x16x32_bf16 v[100:103], v[196:199], v[156:159], v[100:103]
	v_mfma_f32_16x16x32_bf16 v[100:103], v[192:195], v[152:155], v[100:103]
	v_mfma_f32_16x16x32_bf16 v[84:87], v[192:195], v[160:163], v[84:87]
	v_mfma_f32_16x16x32_bf16 v[84:87], v[196:199], v[164:167], v[84:87]
	v_mfma_f32_16x16x32_bf16 v[80:83], v[212:215], v[164:167], v[80:83]
	v_mfma_f32_16x16x32_bf16 v[80:83], v[200:203], v[160:163], v[80:83]
	v_mfma_f32_16x16x32_bf16 v[64:67], v[200:203], v[168:171], v[64:67]
	v_mfma_f32_16x16x32_bf16 v[64:67], v[212:215], v[172:175], v[64:67]
	v_mfma_f32_16x16x32_bf16 v[68:71], v[196:199], v[172:175], v[68:71]
	v_mfma_f32_16x16x32_bf16 v[68:71], v[192:195], v[168:171], v[68:71]
	s_setprio 0
	s_mov_b32 m0, s63
	s_barrier
	ds_read_b128 v[144:147], v209 offset:49152
	ds_read_b128 v[148:151], v209 offset:50176
	ds_read_b128 v[152:155], v209 offset:51200
	ds_read_b128 v[156:159], v209 offset:52224
	ds_read_b128 v[160:163], v209 offset:53248
	ds_read_b128 v[164:167], v209 offset:54272
	ds_read_b128 v[168:171], v209 offset:55296
	ds_read_b128 v[172:175], v209 offset:56320
	global_load_lds_dwordx4 v176, s[92:93]
	s_mov_b32 m0, s64
	s_nop 0
	global_load_lds_dwordx4 v180, s[92:93]
	s_barrier
	s_waitcnt lgkmcnt(0)
	s_setprio 1
	s_waitcnt lgkmcnt(0)
	v_mfma_f32_16x16x32_bf16 v[60:63], v[128:131], v[144:147], v[60:63]
	v_mfma_f32_16x16x32_bf16 v[60:63], v[132:135], v[148:151], v[60:63]
	v_mfma_f32_16x16x32_bf16 v[56:59], v[140:143], v[148:151], v[56:59]
	v_mfma_f32_16x16x32_bf16 v[56:59], v[136:139], v[144:147], v[56:59]
	v_mfma_f32_16x16x32_bf16 v[40:43], v[136:139], v[152:155], v[40:43]
	v_mfma_f32_16x16x32_bf16 v[40:43], v[140:143], v[156:159], v[40:43]
	v_mfma_f32_16x16x32_bf16 v[44:47], v[132:135], v[156:159], v[44:47]
	v_mfma_f32_16x16x32_bf16 v[44:47], v[128:131], v[152:155], v[44:47]
	v_mfma_f32_16x16x32_bf16 v[28:31], v[128:131], v[160:163], v[28:31]
	v_mfma_f32_16x16x32_bf16 v[28:31], v[132:135], v[164:167], v[28:31]
	v_mfma_f32_16x16x32_bf16 v[24:27], v[140:143], v[164:167], v[24:27]
	v_mfma_f32_16x16x32_bf16 v[24:27], v[136:139], v[160:163], v[24:27]
	v_mfma_f32_16x16x32_bf16 v[8:11], v[136:139], v[168:171], v[8:11]
	v_mfma_f32_16x16x32_bf16 v[8:11], v[140:143], v[172:175], v[8:11]
	v_mfma_f32_16x16x32_bf16 v[12:15], v[132:135], v[172:175], v[12:15]
	v_mfma_f32_16x16x32_bf16 v[12:15], v[128:131], v[168:171], v[12:15]
	s_setprio 0
	s_barrier
	s_add_u32 s42, s42, 0x40080
	s_addc_u32 s43, s43, 0
	s_add_i32 s44, s44, s51
	s_mov_b32 m0, s44
	s_nop 0
	global_load_lds_dwordx4 v178, s[42:43]
	s_add_i32 m0, s44, 0x2000
	s_nop 0
	global_load_lds_dwordx4 v182, s[42:43]
	s_waitcnt vmcnt(6)
	s_barrier
; __device__ __forceinline__ unsigned cvt_pk_bf16(float lo, float hi) { unsigned r; asm volatile("v_cvt_pk_bf16_f32 %0, %1, %2" : "=v"(r) : "v"(lo), "v"(hi)); return r; }
; __device__ __forceinline__ float x16_sum(float x) { auto s = __builtin_amdgcn_permlane16_swap(__float_as_uint(x), __float_as_uint(x), false, false); return __uint_as_float(s[0]) + __uint_as_float(s[1]); }
; __device__ __forceinline__ float x32_sum(float x) { auto s = __builtin_amdgcn_permlane32_swap(__float_as_uint(x), __float_as_uint(x), false, false); return __uint_as_float(s[0]) + __uint_as_float(s[1]); }
; template <class Epi, class Ptrs>
; __device__ __forceinline__ void gemm_phase(LAS unsigned char* lds, const int K, const StaticOrder& S, const Ptrs& P, const Epi& E) {
;     ...
;             PG8_WAIT_V(6); PG8_BAR; PG8_MMA(1, 1, At, B1); PG8_BAR;
;         }
;     __device__ __forceinline__ void operator()(const f32x4 (&acc)[2][2][4][2], const Unit& u, int ui, int wr, int wc, int fr, int fq) const {
;         const int row0 = u.pm * 256 + wr * 64 + fr, col0 = u.pn * 256 + wc * 32 + 8 * fq;
;         const float* xb0 = (u.pm * 256 < MP) ? xp : xs - (size_t)MP * DM;
; #pragma unroll
;         for (int ai = 0; ai < 2; ++ai) {
;             f32x4 xv[4][2][2];
; #pragma unroll
;             for (int m = 0; m < 4; ++m)
; #pragma unroll
;                 for (int bj = 0; bj < 2; ++bj) { const float* p = xb0 + (size_t)(row0 + ai * 128 + m * 16) * DM + col0 + bj * 128; xv[m][bj][0] = *(const f32x4*)p; xv[m][bj][1] = *(const f32x4*)(p + 4); }
; #pragma unroll
;             for (int m = 0; m < 4; ++m) { const int row = row0 + ai * 128 + m * 16; const size_t off = (size_t)row * DM + col0; float ss = 0.f;
; #pragma unroll
;                 for (int bj = 0; bj < 2; ++bj) {
;                     const f32x4 v0 = acc[ai][bj][m][0] + xv[m][bj][0], v1 = acc[ai][bj][m][1] + xv[m][bj][1];
;                     u32x4 w; w.x = cvt_pk_bf16(v0[0], v0[1]); w.y = cvt_pk_bf16(v0[2], v0[3]); w.z = cvt_pk_bf16(v1[0], v1[1]); w.w = cvt_pk_bf16(v1[2], v1[3]);
;                     *(u32x4*)(xb + off + bj * 128) = w;
;                     ss += (v0[0] * v0[0] + v0[1] * v0[1]) + (v0[2] * v0[2] + v0[3] * v0[3]) + (v1[0] * v1[0] + v1[1] * v1[1]) + (v1[2] * v1[2] + v1[3] * v1[3]); }
;                 ss = x32_sum(x16_sum(ss));
;                 if (fq == 0) part[(size_t)row * 16 + u.pn * 4 + wc] = ss; }
	s_setprio 1
	v_mfma_f32_16x16x32_bf16 v[52:55], v[192:195], v[144:147], v[52:55]
	v_mfma_f32_16x16x32_bf16 v[52:55], v[196:199], v[148:151], v[52:55]
	v_mfma_f32_16x16x32_bf16 v[48:51], v[212:215], v[148:151], v[48:51]
	v_mfma_f32_16x16x32_bf16 v[48:51], v[200:203], v[144:147], v[48:51]
	v_mfma_f32_16x16x32_bf16 v[32:35], v[200:203], v[152:155], v[32:35]
	v_mfma_f32_16x16x32_bf16 v[32:35], v[212:215], v[156:159], v[32:35]
	v_mfma_f32_16x16x32_bf16 v[36:39], v[196:199], v[156:159], v[36:39]
	v_mfma_f32_16x16x32_bf16 v[36:39], v[192:195], v[152:155], v[36:39]
	v_mfma_f32_16x16x32_bf16 v[20:23], v[192:195], v[160:163], v[20:23]
	v_mfma_f32_16x16x32_bf16 v[20:23], v[196:199], v[164:167], v[20:23]
	v_mfma_f32_16x16x32_bf16 v[16:19], v[212:215], v[164:167], v[16:19]
	v_mfma_f32_16x16x32_bf16 v[16:19], v[200:203], v[160:163], v[16:19]
	v_mfma_f32_16x16x32_bf16 v[0:3], v[200:203], v[168:171], v[0:3]
	v_mfma_f32_16x16x32_bf16 v[0:3], v[212:215], v[172:175], v[0:3]
	v_mfma_f32_16x16x32_bf16 v[4:7], v[196:199], v[172:175], v[4:7]
	v_mfma_f32_16x16x32_bf16 v[4:7], v[192:195], v[168:171], v[4:7]
	s_setprio 0
	s_add_i32 s41, s41, 2
	s_add_u32 s38, s38, 0x100
	s_addc_u32 s39, s39, 0
	s_add_u32 s21, s21, 0x100
	s_addc_u32 s23, s23, 0
	s_cmp_gt_u32 s41, 13
	s_barrier
	s_cbranch_scc0 .LBB0_353
	s_nop 0
	s_nop 0
	s_nop 0
	s_nop 0
	s_nop 0
	s_nop 0
	s_nop 0
	s_nop 0
	s_nop 0
	s_nop 0
	s_nop 0
	s_nop 0
	s_nop 0
	s_nop 0
	s_nop 0
	s_nop 0
	s_nop 0
	s_nop 0
	s_nop 0
	s_nop 0
	s_nop 0
	s_nop 0
	s_nop 0
	s_nop 0
	s_nop 0
	s_nop 0
	s_nop 0
	s_cmpk_lt_i32 s40, 0x80
	v_lshl_add_u32 v194, s40, 8, v204
	v_lshl_or_b32 v192, s12, 8, v206
	s_cselect_b32 s21, s37, s61
	s_cselect_b32 s23, s36, s60
	v_mov_b32_e32 v128, s23
	v_mov_b32_e32 v129, s21
	v_ashrrev_i32_e32 v193, 31, v192
	v_ashrrev_i32_e32 v195, 31, v194
	v_lshl_add_u64 v[196:197], v[192:193], 2, v[128:129]
	v_lshlrev_b64 v[128:129], 12, v[194:195]
	v_or_b32_e32 v202, 16, v194
	v_or_b32_e32 v200, 32, v194
	v_or_b32_e32 v198, 48, v194
	v_lshl_add_u64 v[128:129], v[196:197], 0, v[128:129]
	v_ashrrev_i32_e32 v203, 31, v202
	v_ashrrev_i32_e32 v201, 31, v200
	v_ashrrev_i32_e32 v199, 31, v198
	global_load_dwordx4 v[212:215], v[128:129], off
	global_load_dwordx4 v[216:219], v[128:129], off offset:16
	global_load_dwordx4 v[220:223], v[128:129], off offset:512
	global_load_dwordx4 v[224:227], v[128:129], off offset:528
	v_lshlrev_b64 v[128:129], 12, v[202:203]
	v_lshlrev_b64 v[130:131], 12, v[200:201]
	v_lshlrev_b64 v[132:133], 12, v[198:199]
	v_lshl_add_u64 v[128:129], v[196:197], 0, v[128:129]
	v_lshl_add_u64 v[130:131], v[196:197], 0, v[130:131]
	v_lshl_add_u64 v[132:133], v[196:197], 0, v[132:133]
	global_load_dwordx4 v[168:171], v[128:129], off offset:16
	global_load_dwordx4 v[172:175], v[128:129], off
	global_load_dwordx4 v[160:163], v[128:129], off offset:528
	global_load_dwordx4 v[164:167], v[128:129], off offset:512
	global_load_dwordx4 v[152:155], v[130:131], off offset:16
	global_load_dwordx4 v[156:159], v[130:131], off
	global_load_dwordx4 v[144:147], v[130:131], off offset:528
	global_load_dwordx4 v[148:151], v[130:131], off offset:512
	global_load_dwordx4 v[136:139], v[132:133], off offset:16
	global_load_dwordx4 v[140:143], v[132:133], off
	s_nop 0
	global_load_dwordx4 v[128:131], v[132:133], off offset:528
	s_nop 0
	global_load_dwordx4 v[132:135], v[132:133], off offset:512
	v_lshlrev_b64 v[228:229], 11, v[194:195]
	v_lshl_add_u64 v[228:229], s[14:15], 0, v[228:229]
	v_lshl_add_u64 v[228:229], v[192:193], 1, v[228:229]
	s_lshl_b32 s38, s12, 2
	s_ashr_i32 s39, s38, 31
	s_waitcnt vmcnt(0)
	v_pk_add_f32 v[126:127], v[126:127], v[214:215]
	v_pk_add_f32 v[124:125], v[124:125], v[212:213]
	v_pk_add_f32 v[118:119], v[118:119], v[222:223]
	v_pk_add_f32 v[116:117], v[116:117], v[220:221]
	v_pk_add_f32 v[120:121], v[120:121], v[216:217]
	v_pk_add_f32 v[214:215], v[112:113], v[224:225]
	v_cvt_pk_bf16_f32 v112, v124, v125
	v_cvt_pk_bf16_f32 v113, v126, v127
	v_mul_f32_e32 v125, v125, v125
	v_mul_f32_e32 v127, v127, v127
	v_mul_f32_e32 v211, v117, v117
	v_mul_f32_e32 v216, v119, v119
	v_pk_add_f32 v[122:123], v[122:123], v[218:219]
	v_pk_add_f32 v[212:213], v[114:115], v[226:227]
	v_cvt_pk_bf16_f32 v114, v120, v121
	v_cvt_pk_bf16_f32 v115, v122, v123
	v_mul_f32_e32 v121, v121, v121
	v_mul_f32_e32 v217, v215, v215
	global_store_dwordx4 v[228:229], v[112:115], off
	v_fmac_f32_e32 v125, v124, v124
	v_fmac_f32_e32 v127, v126, v126
	v_cvt_pk_bf16_f32 v112, v116, v117
	v_fmac_f32_e32 v211, v116, v116
	v_fmac_f32_e32 v216, v118, v118
	v_mul_f32_e32 v123, v123, v123
	v_mul_f32_e32 v218, v213, v213
	v_fmac_f32_e32 v121, v120, v120
	v_cvt_pk_bf16_f32 v113, v118, v119
	v_cvt_pk_bf16_f32 v114, v214, v215
	v_cvt_pk_bf16_f32 v115, v212, v213
	v_fmac_f32_e32 v217, v214, v214
	v_add_f32_e32 v116, v125, v127
	global_store_dwordx4 v[228:229], v[112:115], off offset:256
	v_fmac_f32_e32 v123, v122, v122
	v_fmac_f32_e32 v218, v212, v212
	v_add_f32_e32 v112, v211, v216
	v_add_f32_e32 v113, v116, v121
	v_add_f32_e32 v112, v112, v217
	v_add_f32_e32 v113, v123, v113
	v_add_f32_e32 v112, v218, v112
	v_add_f32_e32 v112, v113, v112
	v_mov_b32_e32 v113, v112
	s_nop 1
	v_permlane16_swap_b32_e32 v112, v113
	v_add_f32_e32 v112, v112, v113
	v_mov_b32_e32 v113, v112
	s_nop 1
	v_permlane32_swap_b32_e32 v112, v113
	s_and_saveexec_b64 s[40:41], s[6:7]
	s_cbranch_execz .LBB0_356
	v_lshlrev_b64 v[114:115], 6, v[194:195]
	v_lshl_add_u64 v[114:115], s[16:17], 0, v[114:115]
	v_lshl_add_u64 v[114:115], s[38:39], 2, v[114:115]
	s_lshl_b32 s12, s62, 2
	v_lshl_add_u64 v[114:115], v[114:115], 0, s[12:13]
	v_add_f32_e32 v112, v112, v113
	global_store_dword v[114:115], v112, off

; #define PG8_STAGE(bufoff, gbase, voff) do { _Pragma("unroll") for (int _i = 0; _i < 2; ++_i) \
;         __builtin_amdgcn_global_load_lds((const unsigned*)((const char*)(gbase) + (voff)[_i]), (LAS unsigned*)(lds + (bufoff) + ldsw + _i * 8192), 16, 0, 0); } while (0)
; #define PG8_WAIT_V(n) asm volatile("s_waitcnt vmcnt(" #n ")" ::: "memory")
; #define PG8_BAR __builtin_amdgcn_s_barrier()
; template <class Epi, class Ptrs>
; __device__ __forceinline__ void gemm_phase(LAS unsigned char* lds, const int K, const StaticOrder& S, const Ptrs& P, const Epi& E) {
;     const int tid = threadIdx.x, wid = __builtin_amdgcn_readfirstlane(tid >> 6), lane = tid & 63, wr = wid >> 2, wc = wid & 3, fr = lane & 15, fq = lane >> 4;
;     const int nt = K / BK;
;     unsigned voffA[2], voffB[2];
; #pragma unroll
;     for (int i = 0; i < 2; ++i) { int R, C; stage_rc(tid * 16 + i * 8192, R, C); const int Rb = (R & ~31) + perm32(R & 31);
;         voffA[i] = (unsigned)(R * K + C) * 2u; voffB[i] = (unsigned)(Rb * K + C) * 2u; }
;     const size_t kstep = (size_t)(BK * 2);
;     const size_t hstep = (size_t)HALF * K * 2;
;     const unsigned ldsw = (unsigned)wid * 1024u;
;     const int aoff = lds_byte(wr * 64 + fr, fq * 8), boff = lds_byte(wc * 32 + fr, fq * 8);
;     ...
;     PG8_STAGE(PG8_SB(0, 0), cB, voffB); PG8_STAGE(PG8_SA(0, 0), cA, voffA); PG8_STAGE(PG8_SB(0, 1), cB + hstep, voffB); PG8_STAGE(PG8_SA(0, 1), cA + hstep, voffA);
;     if (wr == 1) PG8_BAR;
;     PG8_WAIT_V(4); PG8_BAR;
;     PG8_STAGE(PG8_SB(1, 0), cB + kstep, voffB); PG8_STAGE(PG8_SA(1, 0), cA + kstep, voffA); PG8_STAGE(PG8_SB(1, 1), cB + hstep + kstep, voffB);
;     PG8_WAIT_V(6); PG8_BAR;
.LBB0_427:
	s_nop 0
	s_nop 0
	s_nop 0
	s_nop 0
	s_nop 0
	s_nop 0
	s_nop 0
	s_nop 0
	s_nop 0
	s_nop 0
	s_nop 0
	s_nop 0
	s_nop 0
	s_nop 0
	s_nop 0
	s_nop 0
	s_nop 0
	s_nop 0
	s_nop 0
	s_nop 0
	s_nop 0
	s_nop 0
	s_nop 0
	s_nop 0
	s_nop 0
	s_nop 0
	s_nop 0
	s_nop 0
	s_nop 0
	s_nop 0
	s_nop 0
	s_nop 0
	s_nop 0
	s_nop 0
	s_nop 0
	s_nop 0
	s_nop 0
	s_nop 0
	s_nop 0
	s_nop 0
	s_nop 0
	s_nop 0
	s_nop 0
	s_nop 0
	s_nop 0
	s_nop 0
	s_nop 0
	s_nop 0
	s_nop 0
	s_nop 0
	s_nop 0
	s_nop 0
	s_nop 0
	s_nop 0
	s_add_u32 s10, s28, 0xe000000
	s_addc_u32 s11, s29, 0
	s_lshl_b32 s4, s4, 5
	s_mov_b64 s[12:13], 0x80
	s_and_b32 s15, s4, 0x60
	s_add_i32 m0, s39, 0x18000
	v_lshl_add_u64 v[6:7], v[6:7], 0, s[12:13]
	s_ashr_i32 s60, s3, 31
	s_lshl_b32 s14, s1, 13
	s_lshl_b32 s16, s15, 7
	s_waitcnt vmcnt(4)
	s_barrier
	global_load_lds_dwordx4 v[6:7], off
	v_lshl_add_u64 v[4:5], v[4:5], 0, s[12:13]
	s_add_i32 m0, s39, 0x1a000
	s_add_i32 s61, s39, 0x8000
	s_add_i32 s62, s39, 0xa000
	global_load_lds_dwordx4 v[4:5], off
	v_lshl_add_u64 v[2:3], v[2:3], 0, s[12:13]
	s_mov_b32 m0, s61
	s_add_u32 s4, s42, 0x40080
	global_load_lds_dwordx4 v[2:3], off
	v_lshl_add_u64 v[0:1], v[0:1], 0, s[12:13]
	s_mov_b32 m0, s62
	s_addc_u32 s5, s43, 0
	global_load_lds_dwordx4 v[0:1], off
	s_add_i32 m0, s39, 0x1c000
	v_lshl_add_u64 v[0:1], s[4:5], 0, v[130:131]
	global_load_lds_dwordx4 v[0:1], off
	v_lshl_add_u64 v[0:1], s[4:5], 0, v[134:135]
	s_add_i32 m0, s39, 0x1e000
	s_sext_i32_i8 s69, s0
	global_load_lds_dwordx4 v[0:1], off
	v_and_b32_e32 v0, 15, v208
	v_lshlrev_b32_e32 v1, 1, v11
	v_lshlrev_b32_e32 v2, 6, v208
	s_movk_i32 s0, 0x3c0
	v_lshlrev_b32_e32 v3, 2, v208
	v_and_or_b32 v2, v2, s0, v1
	v_and_b32_e32 v3, 32, v3
	v_lshl_or_b32 v146, s1, 6, v0
	v_lshl_or_b32 v0, v0, 6, v1
	v_lshlrev_b32_e32 v1, 8, v208
	v_bitop3_b32 v147, s16, v2, v3 bitop3:0xf6
	v_and_b32_e32 v1, 0x38000, v1
	v_lshlrev_b32_e32 v2, 11, v10
	v_or3_b32 v1, v8, v1, v2
	v_add_u32_e32 v136, v1, v9
	v_lshlrev_b32_e32 v1, 4, v12
	s_waitcnt vmcnt(6)
	v_and_b32_e32 v1, 0x78000, v1
	v_bitop3_b32 v0, v0, s14, v3 bitop3:0xde
	v_or3_b32 v1, v8, v1, v2
	s_add_i32 s63, 0, 0x10000
	s_add_i32 s64, 0, 0x14000
	v_or_b32_e32 v148, s15, v11
	v_mov_b32_e32 v137, v131
	v_add_u32_e32 v138, v1, v9
	v_mov_b32_e32 v139, v131
	v_mov_b64_e32 v[140:141], 0x1800
	v_mov_b64_e32 v[142:143], 0x17ff
	v_add_u32_e32 v149, s63, v147
	v_add_u32_e32 v150, 0, v0
	v_add_u32_e32 v151, s64, v147
	s_mov_b64 s[14:15], 0x100000
	s_mov_b32 s65, 0x100000
	s_mov_b64 s[16:17], 0x120000
	s_mov_b32 s66, 0x120000
	s_mov_b64 s[18:19], 0x140000
	s_mov_b32 s67, 0x140000
	s_mov_b64 s[20:21], 0x160000
	s_mov_b32 s68, 0x160000
	s_barrier

; #define PG8_STAGE(bufoff, gbase, voff) do { _Pragma("unroll") for (int _i = 0; _i < 2; ++_i) \
;         __builtin_amdgcn_global_load_lds((const unsigned*)((const char*)(gbase) + (voff)[_i]), (LAS unsigned*)(lds + (bufoff) + ldsw + _i * 8192), 16, 0, 0); } while (0)
; #define PG8_LDA(dst, b, h) do { _Pragma("unroll") for (int m = 0; m < 4; ++m) _Pragma("unroll") for (int k = 0; k < 2; ++k) dst[m][k] = *(const LAS bf16x8*)(lds + PG8_SA(b, h) + aoff + m * 2048 + k * 1024); } while (0)
; #define PG8_LDB(dst, b, h) do { _Pragma("unroll") for (int n = 0; n < 2; ++n) _Pragma("unroll") for (int k = 0; k < 2; ++k) dst[n][k] = *(const LAS bf16x8*)(lds + PG8_SB(b, h) + boff + n * 2048 + k * 1024); } while (0)
; #define PG8_MMA(ai, bj, At, Bt) do { __builtin_amdgcn_s_setprio(1); _Pragma("unroll") for (int m = 0; m < 4; ++m) _Pragma("unroll") for (int n = 0; n < 2; ++n) _Pragma("unroll") for (int k = 0; k < 2; ++k) \
;         acc[ai][bj][m][n] = __builtin_amdgcn_mfma_f32_16x16x32_bf16(Bt[n][k], At[m][k], acc[ai][bj][m][n], 0, 0, 0); __builtin_amdgcn_s_setprio(0); } while (0)
; #define PG8_WAIT_L(n) asm volatile("s_waitcnt lgkmcnt(" #n ")" ::: "memory")
; #define PG8_BAR __builtin_amdgcn_s_barrier()
; #define PG8_SCHED __builtin_amdgcn_sched_barrier(0)
; template <class Epi, class Ptrs>
; __device__ __forceinline__ void gemm_phase(LAS unsigned char* lds, const int K, const StaticOrder& S, const Ptrs& P, const Epi& E) {
;     ...
;         for (int t = 0; t < nt; t += 2) {
;             const bool last = (t == nt - 2);
;             const char* a1 = cA + (size_t)(t + 1) * kstep;
;             const char* a2 = last ? nA : cA + (size_t)(t + 2) * kstep; const char* b2 = last ? nB : cB + (size_t)(t + 2) * kstep;
;             const char* a3 = a2 + kstep; const char* b3 = b2 + kstep;
;             PG8_LDB(B0, 0, 0); PG8_SCHED; PG8_LDA(At, 0, 0); PG8_STAGE(PG8_SA(1, 1), a1 + hstep, voffA);
;             PG8_WAIT_L(8); PG8_BAR; PG8_WAIT_L(0); PG8_MMA(0, 0, At, B0); PG8_BAR; PG8_SCHED;
;             PG8_LDB(B1, 0, 1); PG8_STAGE(PG8_SB(0, 0), b2, voffB);
;     ...
; #pragma unroll
;         for (int a = 0; a < 2; ++a)
; #pragma unroll
;             for (int b = 0; b < 2; ++b)
; #pragma unroll
;                 for (int m = 0; m < 4; ++m)
; #pragma unroll
;                     for (int n = 0; n < 2; ++n) acc[a][b][m][n] = (f32x4){0.f, 0.f, 0.f, 0.f};
;         cur = nxt; cA = nA; cB = nB; ++ui;
.LBB0_432:
	s_add_u32 s40, s40, 0x40080
	s_addc_u32 s41, s41, 0
	s_add_u32 s23, s42, 0x100
	v_mov_b32_e32 v0, 0
	s_addc_u32 s25, s43, 0
	s_mov_b32 s70, -2
	v_mov_b32_e32 v1, v0
	v_mov_b32_e32 v2, v0
	v_mov_b32_e32 v3, v0
	v_mov_b32_e32 v4, v0
	v_mov_b32_e32 v5, v0
	v_mov_b32_e32 v6, v0
	v_mov_b32_e32 v7, v0
	v_mov_b32_e32 v16, v0
	v_mov_b32_e32 v17, v0
	v_mov_b32_e32 v18, v0
	v_mov_b32_e32 v19, v0
	v_mov_b32_e32 v20, v0
	v_mov_b32_e32 v21, v0
	v_mov_b32_e32 v22, v0
	v_mov_b32_e32 v23, v0
	v_mov_b32_e32 v32, v0
	v_mov_b32_e32 v33, v0
	v_mov_b32_e32 v34, v0
	v_mov_b32_e32 v35, v0
	v_mov_b32_e32 v36, v0
	v_mov_b32_e32 v37, v0
	v_mov_b32_e32 v38, v0
	v_mov_b32_e32 v39, v0
	v_mov_b32_e32 v48, v0
	v_mov_b32_e32 v49, v0
	v_mov_b32_e32 v50, v0
	v_mov_b32_e32 v51, v0
	v_mov_b32_e32 v52, v0
	v_mov_b32_e32 v53, v0
	v_mov_b32_e32 v54, v0
	v_mov_b32_e32 v55, v0
	v_mov_b32_e32 v8, v0
	v_mov_b32_e32 v9, v0
	v_mov_b32_e32 v10, v0
	v_mov_b32_e32 v11, v0
	v_mov_b32_e32 v12, v0
	v_mov_b32_e32 v13, v0
	v_mov_b32_e32 v14, v0
	v_mov_b32_e32 v15, v0
	v_mov_b32_e32 v24, v0
	v_mov_b32_e32 v25, v0
	v_mov_b32_e32 v26, v0
	v_mov_b32_e32 v27, v0
	v_mov_b32_e32 v28, v0
	v_mov_b32_e32 v29, v0
	v_mov_b32_e32 v30, v0
	v_mov_b32_e32 v31, v0
	v_mov_b32_e32 v40, v0
	v_mov_b32_e32 v41, v0
	v_mov_b32_e32 v42, v0
	v_mov_b32_e32 v43, v0
	v_mov_b32_e32 v44, v0
	v_mov_b32_e32 v45, v0
	v_mov_b32_e32 v46, v0
	v_mov_b32_e32 v47, v0
	v_mov_b32_e32 v56, v0
	v_mov_b32_e32 v57, v0
	v_mov_b32_e32 v58, v0
	v_mov_b32_e32 v59, v0
	v_mov_b32_e32 v60, v0
	v_mov_b32_e32 v61, v0
	v_mov_b32_e32 v62, v0
	v_mov_b32_e32 v63, v0
	v_mov_b32_e32 v64, v0
	v_mov_b32_e32 v65, v0
	v_mov_b32_e32 v66, v0
	v_mov_b32_e32 v67, v0
	v_mov_b32_e32 v68, v0
	v_mov_b32_e32 v69, v0
	v_mov_b32_e32 v70, v0
	v_mov_b32_e32 v71, v0
	v_mov_b32_e32 v80, v0
	v_mov_b32_e32 v81, v0
	v_mov_b32_e32 v82, v0
	v_mov_b32_e32 v83, v0
	v_mov_b32_e32 v84, v0
	v_mov_b32_e32 v85, v0
	v_mov_b32_e32 v86, v0
	v_mov_b32_e32 v87, v0
	v_mov_b32_e32 v96, v0
	v_mov_b32_e32 v97, v0
	v_mov_b32_e32 v98, v0
	v_mov_b32_e32 v99, v0
	v_mov_b32_e32 v100, v0
	v_mov_b32_e32 v101, v0
	v_mov_b32_e32 v102, v0
	v_mov_b32_e32 v103, v0
	v_mov_b32_e32 v112, v0
	v_mov_b32_e32 v113, v0
	v_mov_b32_e32 v114, v0
	v_mov_b32_e32 v115, v0
	v_mov_b32_e32 v116, v0
	v_mov_b32_e32 v117, v0
	v_mov_b32_e32 v118, v0
	v_mov_b32_e32 v119, v0
	v_mov_b32_e32 v72, v0
	v_mov_b32_e32 v73, v0
	v_mov_b32_e32 v74, v0
	v_mov_b32_e32 v75, v0
	v_mov_b32_e32 v76, v0
	v_mov_b32_e32 v77, v0
	v_mov_b32_e32 v78, v0
	v_mov_b32_e32 v79, v0
	v_mov_b32_e32 v88, v0
	v_mov_b32_e32 v89, v0
	v_mov_b32_e32 v90, v0
	v_mov_b32_e32 v91, v0
	v_mov_b32_e32 v92, v0
	v_mov_b32_e32 v93, v0
	v_mov_b32_e32 v94, v0
	v_mov_b32_e32 v95, v0
	v_mov_b32_e32 v104, v0
	v_mov_b32_e32 v105, v0
	v_mov_b32_e32 v106, v0
	v_mov_b32_e32 v107, v0
	v_mov_b32_e32 v108, v0
	v_mov_b32_e32 v109, v0
	v_mov_b32_e32 v110, v0
	v_mov_b32_e32 v111, v0
	v_mov_b32_e32 v120, v0
	v_mov_b32_e32 v121, v0
	v_mov_b32_e32 v122, v0
	v_mov_b32_e32 v123, v0
	v_mov_b32_e32 v124, v0
	v_mov_b32_e32 v125, v0
	v_mov_b32_e32 v126, v0
	v_mov_b32_e32 v127, v0
	v_add_u32_e32 v252, 0x18000, v147
	v_add_u32_e32 v253, 0x1c000, v147
.LBB0_433:
	ds_read_b128 v[152:155], v149
	ds_read_b128 v[156:159], v149 offset:1024
	ds_read_b128 v[160:163], v149 offset:2048
	ds_read_b128 v[164:167], v149 offset:3072
	s_add_u32 s42, s40, 0xfffc0080
	s_addc_u32 s43, s41, -1
	s_cmp_eq_u32 s70, 12
	s_cselect_b32 s45, s1, s43
	s_cselect_b32 s44, s0, s42
	s_cselect_b32 s43, s37, s25
	s_cselect_b32 s42, s36, s23
	s_add_i32 m0, s39, 0xc000
	ds_read_b128 v[168:171], v150
	ds_read_b128 v[172:175], v150 offset:1024
	ds_read_b128 v[176:179], v150 offset:2048
	ds_read_b128 v[180:183], v150 offset:3072
	ds_read_b128 v[184:187], v150 offset:4096
	ds_read_b128 v[188:191], v150 offset:5120
	ds_read_b128 v[192:195], v150 offset:6144
	ds_read_b128 v[196:199], v150 offset:7168
	global_load_lds_dwordx4 v136, s[40:41]
	s_add_i32 m0, s39, 0xe000
	s_nop 0
	global_load_lds_dwordx4 v138, s[40:41]
	s_waitcnt lgkmcnt(8)
	s_barrier
	s_waitcnt lgkmcnt(0)
	s_setprio 1
	s_waitcnt lgkmcnt(0)
	v_mfma_f32_16x16x32_bf16 v[124:127], v[152:155], v[168:171], v[124:127]
	v_mfma_f32_16x16x32_bf16 v[124:127], v[156:159], v[172:175], v[124:127]
	v_mfma_f32_16x16x32_bf16 v[120:123], v[164:167], v[172:175], v[120:123]
	v_mfma_f32_16x16x32_bf16 v[120:123], v[160:163], v[168:171], v[120:123]
	v_mfma_f32_16x16x32_bf16 v[104:107], v[160:163], v[176:179], v[104:107]
	v_mfma_f32_16x16x32_bf16 v[104:107], v[164:167], v[180:183], v[104:107]
	v_mfma_f32_16x16x32_bf16 v[108:111], v[156:159], v[180:183], v[108:111]
	v_mfma_f32_16x16x32_bf16 v[108:111], v[152:155], v[176:179], v[108:111]
	v_mfma_f32_16x16x32_bf16 v[92:95], v[152:155], v[184:187], v[92:95]
	v_mfma_f32_16x16x32_bf16 v[92:95], v[156:159], v[188:191], v[92:95]
	v_mfma_f32_16x16x32_bf16 v[88:91], v[164:167], v[188:191], v[88:91]
	v_mfma_f32_16x16x32_bf16 v[88:91], v[160:163], v[184:187], v[88:91]
	v_mfma_f32_16x16x32_bf16 v[72:75], v[160:163], v[192:195], v[72:75]
	v_mfma_f32_16x16x32_bf16 v[72:75], v[164:167], v[196:199], v[72:75]
	v_mfma_f32_16x16x32_bf16 v[76:79], v[156:159], v[196:199], v[76:79]
	v_mfma_f32_16x16x32_bf16 v[76:79], v[152:155], v[192:195], v[76:79]
	s_setprio 0
	s_barrier
	s_add_i32 s71, s63, s51
	s_add_u32 s76, s42, 0x80
	s_addc_u32 s77, s43, 0
	s_mov_b32 m0, s71
	ds_read_b128 v[200:203], v151
	ds_read_b128 v[204:207], v151 offset:1024
	ds_read_b128 v[210:213], v151 offset:2048
	ds_read_b128 v[214:217], v151 offset:3072
	global_load_lds_dwordx4 v130, s[42:43]
	s_add_i32 m0, s71, 0x2000
	s_nop 0
	global_load_lds_dwordx4 v134, s[42:43]
	s_barrier
; #define PG8_STAGE(bufoff, gbase, voff) do { _Pragma("unroll") for (int _i = 0; _i < 2; ++_i) \
;         __builtin_amdgcn_global_load_lds((const unsigned*)((const char*)(gbase) + (voff)[_i]), (LAS unsigned*)(lds + (bufoff) + ldsw + _i * 8192), 16, 0, 0); } while (0)
; #define PG8_LDA(dst, b, h) do { _Pragma("unroll") for (int m = 0; m < 4; ++m) _Pragma("unroll") for (int k = 0; k < 2; ++k) dst[m][k] = *(const LAS bf16x8*)(lds + PG8_SA(b, h) + aoff + m * 2048 + k * 1024); } while (0)
; #define PG8_LDB(dst, b, h) do { _Pragma("unroll") for (int n = 0; n < 2; ++n) _Pragma("unroll") for (int k = 0; k < 2; ++k) dst[n][k] = *(const LAS bf16x8*)(lds + PG8_SB(b, h) + boff + n * 2048 + k * 1024); } while (0)
; #define PG8_MMA(ai, bj, At, Bt) do { __builtin_amdgcn_s_setprio(1); _Pragma("unroll") for (int m = 0; m < 4; ++m) _Pragma("unroll") for (int n = 0; n < 2; ++n) _Pragma("unroll") for (int k = 0; k < 2; ++k) \
;         acc[ai][bj][m][n] = __builtin_amdgcn_mfma_f32_16x16x32_bf16(Bt[n][k], At[m][k], acc[ai][bj][m][n], 0, 0, 0); __builtin_amdgcn_s_setprio(0); } while (0)
; #define PG8_WAIT_V(n) asm volatile("s_waitcnt vmcnt(" #n ")" ::: "memory")
; #define PG8_WAIT_L(n) asm volatile("s_waitcnt lgkmcnt(" #n ")" ::: "memory")
; #define PG8_BAR __builtin_amdgcn_s_barrier()
; #define PG8_SCHED __builtin_amdgcn_sched_barrier(0)
; template <class Epi, class Ptrs>
; __device__ __forceinline__ void gemm_phase(LAS unsigned char* lds, const int K, const StaticOrder& S, const Ptrs& P, const Epi& E) {
;     ...
;             PG8_BAR; PG8_WAIT_L(0); PG8_MMA(0, 1, At, B1); PG8_BAR;
;             PG8_LDA(At, 0, 1); PG8_STAGE(PG8_SA(0, 0), a2, voffA);
;             PG8_BAR; PG8_WAIT_L(0); PG8_MMA(1, 0, At, B0); PG8_BAR; PG8_SCHED;
;             PG8_STAGE(PG8_SB(0, 1), b2 + hstep, voffB);
;             PG8_WAIT_V(6); PG8_BAR; PG8_MMA(1, 1, At, B1); PG8_BAR;
;             PG8_LDB(B0, 1, 0); PG8_SCHED; PG8_LDA(At, 1, 0); PG8_STAGE(PG8_SA(0, 1), a2 + hstep, voffA);
	s_waitcnt lgkmcnt(0)
	s_setprio 1
	s_waitcnt lgkmcnt(0)
	v_mfma_f32_16x16x32_bf16 v[116:119], v[200:203], v[168:171], v[116:119]
	v_mfma_f32_16x16x32_bf16 v[116:119], v[204:207], v[172:175], v[116:119]
	v_mfma_f32_16x16x32_bf16 v[112:115], v[214:217], v[172:175], v[112:115]
	v_mfma_f32_16x16x32_bf16 v[112:115], v[210:213], v[168:171], v[112:115]
	v_mfma_f32_16x16x32_bf16 v[96:99], v[210:213], v[176:179], v[96:99]
	v_mfma_f32_16x16x32_bf16 v[96:99], v[214:217], v[180:183], v[96:99]
	v_mfma_f32_16x16x32_bf16 v[100:103], v[204:207], v[180:183], v[100:103]
	v_mfma_f32_16x16x32_bf16 v[100:103], v[200:203], v[176:179], v[100:103]
	v_mfma_f32_16x16x32_bf16 v[84:87], v[200:203], v[184:187], v[84:87]
	v_mfma_f32_16x16x32_bf16 v[84:87], v[204:207], v[188:191], v[84:87]
	v_mfma_f32_16x16x32_bf16 v[80:83], v[214:217], v[188:191], v[80:83]
	v_mfma_f32_16x16x32_bf16 v[80:83], v[210:213], v[184:187], v[80:83]
	v_mfma_f32_16x16x32_bf16 v[64:67], v[210:213], v[192:195], v[64:67]
	v_mfma_f32_16x16x32_bf16 v[64:67], v[214:217], v[196:199], v[64:67]
	v_mfma_f32_16x16x32_bf16 v[68:71], v[204:207], v[196:199], v[68:71]
	v_mfma_f32_16x16x32_bf16 v[68:71], v[200:203], v[192:195], v[68:71]
	s_setprio 0
	s_mov_b32 m0, s39
	s_add_u32 s78, s44, 0x80
	s_addc_u32 s79, s45, 0
	s_barrier
	ds_read_b128 v[168:171], v150 offset:16384
	ds_read_b128 v[172:175], v150 offset:17408
	ds_read_b128 v[176:179], v150 offset:18432
	ds_read_b128 v[180:183], v150 offset:19456
	ds_read_b128 v[184:187], v150 offset:20480
	ds_read_b128 v[188:191], v150 offset:21504
	ds_read_b128 v[192:195], v150 offset:22528
	ds_read_b128 v[196:199], v150 offset:23552
	global_load_lds_dwordx4 v128, s[44:45]
	s_mov_b32 m0, s56
	s_nop 0
	global_load_lds_dwordx4 v132, s[44:45]
	s_barrier
	s_waitcnt lgkmcnt(0)
	s_setprio 1
	s_waitcnt lgkmcnt(0)
	v_mfma_f32_16x16x32_bf16 v[60:63], v[152:155], v[168:171], v[60:63]
	v_mfma_f32_16x16x32_bf16 v[60:63], v[156:159], v[172:175], v[60:63]
	v_mfma_f32_16x16x32_bf16 v[56:59], v[164:167], v[172:175], v[56:59]
	v_mfma_f32_16x16x32_bf16 v[56:59], v[160:163], v[168:171], v[56:59]
	v_mfma_f32_16x16x32_bf16 v[40:43], v[160:163], v[176:179], v[40:43]
	v_mfma_f32_16x16x32_bf16 v[40:43], v[164:167], v[180:183], v[40:43]
	v_mfma_f32_16x16x32_bf16 v[44:47], v[156:159], v[180:183], v[44:47]
	v_mfma_f32_16x16x32_bf16 v[44:47], v[152:155], v[176:179], v[44:47]
	v_mfma_f32_16x16x32_bf16 v[28:31], v[152:155], v[184:187], v[28:31]
	v_mfma_f32_16x16x32_bf16 v[28:31], v[156:159], v[188:191], v[28:31]
	v_mfma_f32_16x16x32_bf16 v[24:27], v[164:167], v[188:191], v[24:27]
	v_mfma_f32_16x16x32_bf16 v[24:27], v[160:163], v[184:187], v[24:27]
	v_mfma_f32_16x16x32_bf16 v[8:11], v[160:163], v[192:195], v[8:11]
	v_mfma_f32_16x16x32_bf16 v[8:11], v[164:167], v[196:199], v[8:11]
	v_mfma_f32_16x16x32_bf16 v[12:15], v[156:159], v[196:199], v[12:15]
	v_mfma_f32_16x16x32_bf16 v[12:15], v[152:155], v[192:195], v[12:15]
	s_setprio 0
	s_barrier
	s_add_u32 s72, s42, 0x40000
	s_addc_u32 s73, s43, 0
	s_add_i32 s71, s64, s51
	s_mov_b32 m0, s71
	s_nop 0
	global_load_lds_dwordx4 v130, s[72:73]
	s_add_i32 m0, s71, 0x2000
	s_nop 0
	global_load_lds_dwordx4 v134, s[72:73]
	s_waitcnt vmcnt(6)
	s_barrier
	s_setprio 1
	v_mfma_f32_16x16x32_bf16 v[52:55], v[200:203], v[168:171], v[52:55]
	v_mfma_f32_16x16x32_bf16 v[52:55], v[204:207], v[172:175], v[52:55]
	v_mfma_f32_16x16x32_bf16 v[48:51], v[214:217], v[172:175], v[48:51]
	v_mfma_f32_16x16x32_bf16 v[48:51], v[210:213], v[168:171], v[48:51]
	v_mfma_f32_16x16x32_bf16 v[32:35], v[210:213], v[176:179], v[32:35]
	v_mfma_f32_16x16x32_bf16 v[32:35], v[214:217], v[180:183], v[32:35]
	v_mfma_f32_16x16x32_bf16 v[36:39], v[204:207], v[180:183], v[36:39]
	v_mfma_f32_16x16x32_bf16 v[36:39], v[200:203], v[176:179], v[36:39]
	v_mfma_f32_16x16x32_bf16 v[20:23], v[200:203], v[184:187], v[20:23]
	v_mfma_f32_16x16x32_bf16 v[20:23], v[204:207], v[188:191], v[20:23]
	v_mfma_f32_16x16x32_bf16 v[16:19], v[214:217], v[188:191], v[16:19]
	v_mfma_f32_16x16x32_bf16 v[16:19], v[210:213], v[184:187], v[16:19]
	v_mfma_f32_16x16x32_bf16 v[0:3], v[210:213], v[192:195], v[0:3]
	v_mfma_f32_16x16x32_bf16 v[0:3], v[214:217], v[196:199], v[0:3]
	v_mfma_f32_16x16x32_bf16 v[4:7], v[204:207], v[196:199], v[4:7]
	v_mfma_f32_16x16x32_bf16 v[4:7], v[200:203], v[192:195], v[4:7]
	s_setprio 0
	s_add_i32 s71, 0, 0x18000
	s_barrier
	ds_read_b128 v[152:155], v252
	ds_read_b128 v[156:159], v252 offset:1024
	ds_read_b128 v[160:163], v252 offset:2048
	ds_read_b128 v[164:167], v252 offset:3072
	s_add_u32 s44, s44, 0x40000
	s_addc_u32 s45, s45, 0
	s_mov_b32 m0, s57
	ds_read_b128 v[168:171], v150 offset:32768
	ds_read_b128 v[172:175], v150 offset:33792
	ds_read_b128 v[176:179], v150 offset:34816
	ds_read_b128 v[180:183], v150 offset:35840
	ds_read_b128 v[184:187], v150 offset:36864
	ds_read_b128 v[188:191], v150 offset:37888
	ds_read_b128 v[192:195], v150 offset:38912
	ds_read_b128 v[196:199], v150 offset:39936
	global_load_lds_dwordx4 v128, s[44:45]
	s_mov_b32 m0, s58
	s_nop 0
	global_load_lds_dwordx4 v132, s[44:45]
	s_waitcnt lgkmcnt(8)
	s_barrier
; #define PG8_STAGE(bufoff, gbase, voff) do { _Pragma("unroll") for (int _i = 0; _i < 2; ++_i) \
;         __builtin_amdgcn_global_load_lds((const unsigned*)((const char*)(gbase) + (voff)[_i]), (LAS unsigned*)(lds + (bufoff) + ldsw + _i * 8192), 16, 0, 0); } while (0)
; #define PG8_LDA(dst, b, h) do { _Pragma("unroll") for (int m = 0; m < 4; ++m) _Pragma("unroll") for (int k = 0; k < 2; ++k) dst[m][k] = *(const LAS bf16x8*)(lds + PG8_SA(b, h) + aoff + m * 2048 + k * 1024); } while (0)
; #define PG8_LDB(dst, b, h) do { _Pragma("unroll") for (int n = 0; n < 2; ++n) _Pragma("unroll") for (int k = 0; k < 2; ++k) dst[n][k] = *(const LAS bf16x8*)(lds + PG8_SB(b, h) + boff + n * 2048 + k * 1024); } while (0)
; #define PG8_MMA(ai, bj, At, Bt) do { __builtin_amdgcn_s_setprio(1); _Pragma("unroll") for (int m = 0; m < 4; ++m) _Pragma("unroll") for (int n = 0; n < 2; ++n) _Pragma("unroll") for (int k = 0; k < 2; ++k) \
;         acc[ai][bj][m][n] = __builtin_amdgcn_mfma_f32_16x16x32_bf16(Bt[n][k], At[m][k], acc[ai][bj][m][n], 0, 0, 0); __builtin_amdgcn_s_setprio(0); } while (0)
; #define PG8_WAIT_V(n) asm volatile("s_waitcnt vmcnt(" #n ")" ::: "memory")
; #define PG8_WAIT_L(n) asm volatile("s_waitcnt lgkmcnt(" #n ")" ::: "memory")
; #define PG8_BAR __builtin_amdgcn_s_barrier()
; #define PG8_SCHED __builtin_amdgcn_sched_barrier(0)
; template <class Epi, class Ptrs>
; __device__ __forceinline__ void gemm_phase(LAS unsigned char* lds, const int K, const StaticOrder& S, const Ptrs& P, const Epi& E) {
;     ...
;             PG8_WAIT_L(8); PG8_BAR; PG8_WAIT_L(0); PG8_MMA(0, 0, At, B0); PG8_BAR; PG8_SCHED;
;             PG8_LDB(B1, 1, 1); PG8_STAGE(PG8_SB(1, 0), b3, voffB);
;             PG8_BAR; PG8_WAIT_L(0); PG8_MMA(0, 1, At, B1); PG8_BAR;
;             PG8_LDA(At, 1, 1); PG8_STAGE(PG8_SA(1, 0), a3, voffA);
;             PG8_BAR; PG8_WAIT_L(0); PG8_MMA(1, 0, At, B0); PG8_BAR; PG8_SCHED;
;             PG8_STAGE(PG8_SB(1, 1), b3 + hstep, voffB);
;             PG8_WAIT_V(6); PG8_BAR; PG8_MMA(1, 1, At, B1); PG8_BAR;
	s_waitcnt lgkmcnt(0)
	s_setprio 1
	s_waitcnt lgkmcnt(0)
	v_mfma_f32_16x16x32_bf16 v[124:127], v[152:155], v[168:171], v[124:127]
	v_mfma_f32_16x16x32_bf16 v[124:127], v[156:159], v[172:175], v[124:127]
	v_mfma_f32_16x16x32_bf16 v[120:123], v[164:167], v[172:175], v[120:123]
	v_mfma_f32_16x16x32_bf16 v[120:123], v[160:163], v[168:171], v[120:123]
	v_mfma_f32_16x16x32_bf16 v[104:107], v[160:163], v[176:179], v[104:107]
	v_mfma_f32_16x16x32_bf16 v[104:107], v[164:167], v[180:183], v[104:107]
	v_mfma_f32_16x16x32_bf16 v[108:111], v[156:159], v[180:183], v[108:111]
	v_mfma_f32_16x16x32_bf16 v[108:111], v[152:155], v[176:179], v[108:111]
	v_mfma_f32_16x16x32_bf16 v[92:95], v[152:155], v[184:187], v[92:95]
	v_mfma_f32_16x16x32_bf16 v[92:95], v[156:159], v[188:191], v[92:95]
	v_mfma_f32_16x16x32_bf16 v[88:91], v[164:167], v[188:191], v[88:91]
	v_mfma_f32_16x16x32_bf16 v[88:91], v[160:163], v[184:187], v[88:91]
	v_mfma_f32_16x16x32_bf16 v[72:75], v[160:163], v[192:195], v[72:75]
	v_mfma_f32_16x16x32_bf16 v[72:75], v[164:167], v[196:199], v[72:75]
	v_mfma_f32_16x16x32_bf16 v[76:79], v[156:159], v[196:199], v[76:79]
	v_mfma_f32_16x16x32_bf16 v[76:79], v[152:155], v[192:195], v[76:79]
	s_setprio 0
	s_barrier
	s_add_i32 s44, 0, 0x1c000
	s_add_i32 s45, s71, s51
	s_mov_b32 m0, s45
	ds_read_b128 v[200:203], v253
	ds_read_b128 v[204:207], v253 offset:1024
	ds_read_b128 v[210:213], v253 offset:2048
	ds_read_b128 v[214:217], v253 offset:3072
	global_load_lds_dwordx4 v130, s[76:77]
	s_add_i32 m0, s45, 0x2000
	s_nop 0
	global_load_lds_dwordx4 v134, s[76:77]
	s_barrier
	s_waitcnt lgkmcnt(0)
	s_setprio 1
	s_waitcnt lgkmcnt(0)
	v_mfma_f32_16x16x32_bf16 v[116:119], v[200:203], v[168:171], v[116:119]
	v_mfma_f32_16x16x32_bf16 v[116:119], v[204:207], v[172:175], v[116:119]
	v_mfma_f32_16x16x32_bf16 v[112:115], v[214:217], v[172:175], v[112:115]
	v_mfma_f32_16x16x32_bf16 v[112:115], v[210:213], v[168:171], v[112:115]
	v_mfma_f32_16x16x32_bf16 v[96:99], v[210:213], v[176:179], v[96:99]
	v_mfma_f32_16x16x32_bf16 v[96:99], v[214:217], v[180:183], v[96:99]
	v_mfma_f32_16x16x32_bf16 v[100:103], v[204:207], v[180:183], v[100:103]
	v_mfma_f32_16x16x32_bf16 v[100:103], v[200:203], v[176:179], v[100:103]
	v_mfma_f32_16x16x32_bf16 v[84:87], v[200:203], v[184:187], v[84:87]
	v_mfma_f32_16x16x32_bf16 v[84:87], v[204:207], v[188:191], v[84:87]
	v_mfma_f32_16x16x32_bf16 v[80:83], v[214:217], v[188:191], v[80:83]
	v_mfma_f32_16x16x32_bf16 v[80:83], v[210:213], v[184:187], v[80:83]
	v_mfma_f32_16x16x32_bf16 v[64:67], v[210:213], v[192:195], v[64:67]
	v_mfma_f32_16x16x32_bf16 v[64:67], v[214:217], v[196:199], v[64:67]
	v_mfma_f32_16x16x32_bf16 v[68:71], v[204:207], v[196:199], v[68:71]
	v_mfma_f32_16x16x32_bf16 v[68:71], v[200:203], v[192:195], v[68:71]
	s_setprio 0
	s_mov_b32 m0, s61
	s_barrier
	ds_read_b128 v[168:171], v150 offset:49152
	ds_read_b128 v[172:175], v150 offset:50176
	ds_read_b128 v[176:179], v150 offset:51200
	ds_read_b128 v[180:183], v150 offset:52224
	ds_read_b128 v[184:187], v150 offset:53248
	ds_read_b128 v[188:191], v150 offset:54272
	ds_read_b128 v[192:195], v150 offset:55296
	ds_read_b128 v[196:199], v150 offset:56320
	global_load_lds_dwordx4 v128, s[78:79]
	s_mov_b32 m0, s62
	s_nop 0
	global_load_lds_dwordx4 v132, s[78:79]
	s_barrier
	s_waitcnt lgkmcnt(0)
	s_setprio 1
	s_waitcnt lgkmcnt(0)
	v_mfma_f32_16x16x32_bf16 v[60:63], v[152:155], v[168:171], v[60:63]
	v_mfma_f32_16x16x32_bf16 v[60:63], v[156:159], v[172:175], v[60:63]
	v_mfma_f32_16x16x32_bf16 v[56:59], v[164:167], v[172:175], v[56:59]
	v_mfma_f32_16x16x32_bf16 v[56:59], v[160:163], v[168:171], v[56:59]
	v_mfma_f32_16x16x32_bf16 v[40:43], v[160:163], v[176:179], v[40:43]
	v_mfma_f32_16x16x32_bf16 v[40:43], v[164:167], v[180:183], v[40:43]
	v_mfma_f32_16x16x32_bf16 v[44:47], v[156:159], v[180:183], v[44:47]
	v_mfma_f32_16x16x32_bf16 v[44:47], v[152:155], v[176:179], v[44:47]
	v_mfma_f32_16x16x32_bf16 v[28:31], v[152:155], v[184:187], v[28:31]
	v_mfma_f32_16x16x32_bf16 v[28:31], v[156:159], v[188:191], v[28:31]
	v_mfma_f32_16x16x32_bf16 v[24:27], v[164:167], v[188:191], v[24:27]
	v_mfma_f32_16x16x32_bf16 v[24:27], v[160:163], v[184:187], v[24:27]
	v_mfma_f32_16x16x32_bf16 v[8:11], v[160:163], v[192:195], v[8:11]
	v_mfma_f32_16x16x32_bf16 v[8:11], v[164:167], v[196:199], v[8:11]
	v_mfma_f32_16x16x32_bf16 v[12:15], v[156:159], v[196:199], v[12:15]
	v_mfma_f32_16x16x32_bf16 v[12:15], v[152:155], v[192:195], v[12:15]
	s_setprio 0
	s_barrier
	s_add_u32 s42, s42, 0x40080
	s_addc_u32 s43, s43, 0
	s_add_i32 s44, s44, s51
	s_mov_b32 m0, s44
	s_nop 0
	global_load_lds_dwordx4 v130, s[42:43]
	s_add_i32 m0, s44, 0x2000
	s_nop 0
	global_load_lds_dwordx4 v134, s[42:43]
	s_waitcnt vmcnt(6)
	s_barrier
	s_setprio 1
	v_mfma_f32_16x16x32_bf16 v[52:55], v[200:203], v[168:171], v[52:55]
	v_mfma_f32_16x16x32_bf16 v[52:55], v[204:207], v[172:175], v[52:55]
	v_mfma_f32_16x16x32_bf16 v[48:51], v[214:217], v[172:175], v[48:51]
	v_mfma_f32_16x16x32_bf16 v[48:51], v[210:213], v[168:171], v[48:51]
	v_mfma_f32_16x16x32_bf16 v[32:35], v[210:213], v[176:179], v[32:35]
	v_mfma_f32_16x16x32_bf16 v[32:35], v[214:217], v[180:183], v[32:35]
	v_mfma_f32_16x16x32_bf16 v[36:39], v[204:207], v[180:183], v[36:39]
	v_mfma_f32_16x16x32_bf16 v[36:39], v[200:203], v[176:179], v[36:39]
	v_mfma_f32_16x16x32_bf16 v[20:23], v[200:203], v[184:187], v[20:23]
	v_mfma_f32_16x16x32_bf16 v[20:23], v[204:207], v[188:191], v[20:23]
	v_mfma_f32_16x16x32_bf16 v[16:19], v[214:217], v[188:191], v[16:19]
	v_mfma_f32_16x16x32_bf16 v[16:19], v[210:213], v[184:187], v[16:19]
	v_mfma_f32_16x16x32_bf16 v[0:3], v[210:213], v[192:195], v[0:3]
	v_mfma_f32_16x16x32_bf16 v[0:3], v[214:217], v[196:199], v[0:3]
	v_mfma_f32_16x16x32_bf16 v[4:7], v[204:207], v[196:199], v[4:7]
	v_mfma_f32_16x16x32_bf16 v[4:7], v[200:203], v[192:195], v[4:7]
	s_setprio 0
	s_add_i32 s70, s70, 2
	s_add_u32 s40, s40, 0x100
	s_addc_u32 s41, s41, 0
	s_add_u32 s23, s23, 0x100
	s_addc_u32 s25, s25, 0
	s_cmp_gt_u32 s70, 13
	s_barrier
; __device__ __forceinline__ unsigned cvt_pk_bf16(float lo, float hi) { unsigned r; asm volatile("v_cvt_pk_bf16_f32 %0, %1, %2" : "=v"(r) : "v"(lo), "v"(hi)); return r; }
;     __device__ __forceinline__ void operator()(const f32x4 (&acc)[2][2][4][2], const Unit& u, int ui, int wr, int wc, int fr, int fq) const {
;     ...
;         for (int ai = 0; ai < 2; ++ai)
; #pragma unroll
;             for (int m = 0; m < 4; ++m) { bf16_t* rowp = hid + (size_t)(row0 + ai * 128 + m * 16) * DFF + col0;
; #pragma unroll
;                 for (int bj = 0; bj < 2; ++bj) { f32x4 v0 = acc[ai][bj][m][0], v1 = acc[ai][bj][m][1];
; #pragma unroll
;                     for (int j = 0; j < 4; ++j) { const float a = fmaxf(v0[j], 0.f), b = fmaxf(v1[j], 0.f); v0[j] = a * a; v1[j] = b * b; }
;                     u32x4 w; w.x = cvt_pk_bf16(v0[0], v0[1]); w.y = cvt_pk_bf16(v0[2], v0[3]); w.z = cvt_pk_bf16(v1[0], v1[1]); w.w = cvt_pk_bf16(v1[2], v1[3]);
;                     *(u32x4*)(rowp + bj * 128) = w; } }
	s_cbranch_scc0 .LBB0_433
	s_nop 0
	s_nop 0
	s_nop 0
	s_nop 0
	s_nop 0
	s_nop 0
	s_nop 0
	s_nop 0
	s_nop 0
	s_nop 0
	s_nop 0
	s_nop 0
	s_nop 0
	s_nop 0
	s_nop 0
	s_nop 0
	s_nop 0
	s_nop 0
	s_nop 0
	s_nop 0
	s_nop 0
	s_nop 0
	s_nop 0
	s_nop 0
	s_nop 0
	s_nop 0
	s_nop 0
	s_nop 0
	s_nop 0
	s_nop 0
	v_lshl_add_u32 v152, s38, 8, v146
	v_max_f32_e32 v120, 0, v120
	v_ashrrev_i32_e32 v153, 31, v152
	v_max_f32_e32 v121, 0, v121
	v_max_f32_e32 v122, 0, v122
	v_lshl_or_b32 v144, s69, 8, v148
	v_lshlrev_b64 v[154:155], 13, v[152:153]
	v_mul_f32_e32 v153, v120, v120
	v_max_f32_e32 v120, 0, v125
	v_ashrrev_i32_e32 v145, 31, v144
	v_max_f32_e32 v124, 0, v124
	v_mul_f32_e32 v125, v121, v121
	v_max_f32_e32 v121, 0, v126
	v_mul_f32_e32 v126, v122, v122
	v_max_f32_e32 v122, 0, v127
	v_max_f32_e32 v123, 0, v123
	v_lshl_add_u64 v[154:155], s[10:11], 0, v[154:155]
	v_lshlrev_b64 v[156:157], 1, v[144:145]
	v_mul_f32_e32 v120, v120, v120
	v_max_f32_e32 v112, 0, v112
	v_lshl_add_u64 v[144:145], v[154:155], 0, v[156:157]
	v_mul_f32_e32 v124, v124, v124
	v_mul_f32_e32 v121, v121, v121
	v_mul_f32_e32 v122, v122, v122
	v_mul_f32_e32 v123, v123, v123
	v_cvt_pk_bf16_f32 v120, v124, v120
	v_max_f32_e32 v113, 0, v113
	v_max_f32_e32 v114, 0, v114
	v_cvt_pk_bf16_f32 v121, v121, v122
	v_cvt_pk_bf16_f32 v122, v153, v125
	v_cvt_pk_bf16_f32 v123, v126, v123
	global_store_dwordx4 v[144:145], v[120:123], off
	s_nop 1
	v_mul_f32_e32 v120, v112, v112
	v_max_f32_e32 v112, 0, v117
	v_max_f32_e32 v116, 0, v116
	v_mul_f32_e32 v117, v113, v113
	v_max_f32_e32 v113, 0, v118
	v_mul_f32_e32 v118, v114, v114
	v_max_f32_e32 v114, 0, v119
	v_max_f32_e32 v115, 0, v115
	v_mul_f32_e32 v112, v112, v112
	v_mul_f32_e32 v116, v116, v116
	v_mul_f32_e32 v113, v113, v113
	v_mul_f32_e32 v114, v114, v114
	v_mul_f32_e32 v115, v115, v115
	v_cvt_pk_bf16_f32 v112, v116, v112
	v_max_f32_e32 v104, 0, v104
	v_cvt_pk_bf16_f32 v113, v113, v114
	v_cvt_pk_bf16_f32 v114, v120, v117
	v_cvt_pk_bf16_f32 v115, v118, v115
	global_store_dwordx4 v[144:145], v[112:115], off offset:256
	s_nop 0
	v_max_f32_e32 v105, 0, v105
	v_or_b32_e32 v112, 16, v152
	v_max_f32_e32 v106, 0, v106
	v_ashrrev_i32_e32 v113, 31, v112
	v_mul_f32_e32 v114, v104, v104
	v_max_f32_e32 v104, 0, v109
	v_lshlrev_b64 v[112:113], 13, v[112:113]
	v_max_f32_e32 v108, 0, v108
	v_mul_f32_e32 v109, v105, v105
	v_max_f32_e32 v105, 0, v110
	v_mul_f32_e32 v110, v106, v106
	v_max_f32_e32 v106, 0, v111
	v_max_f32_e32 v107, 0, v107
	v_lshl_add_u64 v[112:113], s[10:11], 0, v[112:113]
	v_mul_f32_e32 v104, v104, v104
	v_max_f32_e32 v96, 0, v96
	v_lshl_add_u64 v[112:113], v[112:113], 0, v[156:157]
	v_mul_f32_e32 v108, v108, v108
	v_mul_f32_e32 v105, v105, v105
	v_mul_f32_e32 v106, v106, v106
	v_mul_f32_e32 v107, v107, v107
	v_cvt_pk_bf16_f32 v104, v108, v104
	v_max_f32_e32 v97, 0, v97
	v_max_f32_e32 v98, 0, v98
	v_cvt_pk_bf16_f32 v105, v105, v106
	v_cvt_pk_bf16_f32 v106, v114, v109
	v_cvt_pk_bf16_f32 v107, v110, v107
	global_store_dwordx4 v[112:113], v[104:107], off
	s_nop 1
	v_mul_f32_e32 v104, v96, v96
	v_max_f32_e32 v96, 0, v101
	v_max_f32_e32 v100, 0, v100
	v_mul_f32_e32 v101, v97, v97
	v_max_f32_e32 v97, 0, v102
	v_mul_f32_e32 v102, v98, v98
	v_max_f32_e32 v98, 0, v103
	v_max_f32_e32 v99, 0, v99
	v_mul_f32_e32 v96, v96, v96
	v_mul_f32_e32 v100, v100, v100
	v_mul_f32_e32 v97, v97, v97
	v_mul_f32_e32 v98, v98, v98
	v_mul_f32_e32 v99, v99, v99
	v_cvt_pk_bf16_f32 v96, v100, v96
	v_max_f32_e32 v88, 0, v88
	v_cvt_pk_bf16_f32 v97, v97, v98
	v_cvt_pk_bf16_f32 v98, v104, v101
	v_cvt_pk_bf16_f32 v99, v102, v99
	global_store_dwordx4 v[112:113], v[96:99], off offset:256
	s_nop 0
	v_max_f32_e32 v89, 0, v89
	v_or_b32_e32 v96, 32, v152
	v_max_f32_e32 v90, 0, v90
	v_ashrrev_i32_e32 v97, 31, v96
	v_mul_f32_e32 v98, v88, v88
	v_max_f32_e32 v88, 0, v93
	v_lshlrev_b64 v[96:97], 13, v[96:97]
	v_max_f32_e32 v92, 0, v92
	v_mul_f32_e32 v93, v89, v89
	v_max_f32_e32 v89, 0, v94
	v_mul_f32_e32 v94, v90, v90
	v_max_f32_e32 v90, 0, v95
	v_max_f32_e32 v91, 0, v91
	v_lshl_add_u64 v[96:97], s[10:11], 0, v[96:97]
	v_mul_f32_e32 v88, v88, v88
	v_max_f32_e32 v80, 0, v80
	v_lshl_add_u64 v[96:97], v[96:97], 0, v[156:157]
	v_mul_f32_e32 v92, v92, v92
	v_mul_f32_e32 v89, v89, v89
	v_mul_f32_e32 v90, v90, v90
	v_mul_f32_e32 v91, v91, v91
	v_cvt_pk_bf16_f32 v88, v92, v88
	v_max_f32_e32 v81, 0, v81
	v_max_f32_e32 v82, 0, v82
	v_cvt_pk_bf16_f32 v89, v89, v90
	v_cvt_pk_bf16_f32 v90, v98, v93
	v_cvt_pk_bf16_f32 v91, v94, v91
	global_store_dwordx4 v[96:97], v[88:91], off
	s_nop 1
	v_mul_f32_e32 v88, v80, v80
	v_max_f32_e32 v80, 0, v85
	v_max_f32_e32 v84, 0, v84
	v_mul_f32_e32 v85, v81, v81
	v_max_f32_e32 v81, 0, v86
	v_mul_f32_e32 v86, v82, v82
	v_max_f32_e32 v82, 0, v87
	v_max_f32_e32 v83, 0, v83
	v_mul_f32_e32 v80, v80, v80
	v_mul_f32_e32 v84, v84, v84
	v_mul_f32_e32 v81, v81, v81
	v_mul_f32_e32 v82, v82, v82
	v_mul_f32_e32 v83, v83, v83
	v_cvt_pk_bf16_f32 v80, v84, v80
	v_max_f32_e32 v72, 0, v72
	v_cvt_pk_bf16_f32 v81, v81, v82
	v_cvt_pk_bf16_f32 v82, v88, v85
	v_cvt_pk_bf16_f32 v83, v86, v83
	global_store_dwordx4 v[96:97], v[80:83], off offset:256
	s_nop 0
	v_max_f32_e32 v73, 0, v73
	v_or_b32_e32 v80, 48, v152
	v_max_f32_e32 v74, 0, v74
	v_ashrrev_i32_e32 v81, 31, v80
	v_mul_f32_e32 v82, v72, v72
	v_max_f32_e32 v72, 0, v77
	v_lshlrev_b64 v[80:81], 13, v[80:81]
	v_max_f32_e32 v76, 0, v76
	v_mul_f32_e32 v77, v73, v73
	v_max_f32_e32 v73, 0, v78
	v_mul_f32_e32 v78, v74, v74
	v_max_f32_e32 v74, 0, v79
	v_max_f32_e32 v75, 0, v75
	v_lshl_add_u64 v[80:81], s[10:11], 0, v[80:81]
	v_mul_f32_e32 v72, v72, v72
	v_max_f32_e32 v64, 0, v64
	v_max_f32_e32 v65, 0, v65
	v_max_f32_e32 v66, 0, v66
; __device__ __forceinline__ unsigned cvt_pk_bf16(float lo, float hi) { unsigned r; asm volatile("v_cvt_pk_bf16_f32 %0, %1, %2" : "=v"(r) : "v"(lo), "v"(hi)); return r; }
; #define PG8_WAIT_V(n) asm volatile("s_waitcnt vmcnt(" #n ")" ::: "memory")
; #define PG8_BAR __builtin_amdgcn_s_barrier()
; template <class Epi, class Ptrs>
; __device__ __forceinline__ void gemm_phase(LAS unsigned char* lds, const int K, const StaticOrder& S, const Ptrs& P, const Epi& E) {
;     ...
;         cur = nxt; cA = nA; cB = nB; ++ui;
;     }
;     PG8_WAIT_V(0);
;     if (wr == 0) PG8_BAR;
;     __device__ __forceinline__ void operator()(const f32x4 (&acc)[2][2][4][2], const Unit& u, int ui, int wr, int wc, int fr, int fq) const {
;     ...
;             for (int m = 0; m < 4; ++m) { bf16_t* rowp = hid + (size_t)(row0 + ai * 128 + m * 16) * DFF + col0;
; #pragma unroll
;                 for (int bj = 0; bj < 2; ++bj) { f32x4 v0 = acc[ai][bj][m][0], v1 = acc[ai][bj][m][1];
; #pragma unroll
;                     for (int j = 0; j < 4; ++j) { const float a = fmaxf(v0[j], 0.f), b = fmaxf(v1[j], 0.f); v0[j] = a * a; v1[j] = b * b; }
;                     u32x4 w; w.x = cvt_pk_bf16(v0[0], v0[1]); w.y = cvt_pk_bf16(v0[2], v0[3]); w.z = cvt_pk_bf16(v1[0], v1[1]); w.w = cvt_pk_bf16(v1[2], v1[3]);
;                     *(u32x4*)(rowp + bj * 128) = w; } }
	v_lshl_add_u64 v[80:81], v[80:81], 0, v[156:157]
	v_mul_f32_e32 v76, v76, v76
	v_mul_f32_e32 v73, v73, v73
	v_mul_f32_e32 v74, v74, v74
	v_mul_f32_e32 v75, v75, v75
	v_cvt_pk_bf16_f32 v72, v76, v72
	v_cvt_pk_bf16_f32 v73, v73, v74
	v_cvt_pk_bf16_f32 v74, v82, v77
	v_cvt_pk_bf16_f32 v75, v78, v75
	global_store_dwordx4 v[80:81], v[72:75], off
	v_max_f32_e32 v68, 0, v68
	v_max_f32_e32 v67, 0, v67
	v_mul_f32_e32 v72, v64, v64
	v_max_f32_e32 v64, 0, v69
	v_mul_f32_e32 v69, v65, v65
	v_max_f32_e32 v65, 0, v70
	v_mul_f32_e32 v70, v66, v66
	v_max_f32_e32 v66, 0, v71
	v_mul_f32_e32 v64, v64, v64
	v_mul_f32_e32 v65, v65, v65
	v_mul_f32_e32 v66, v66, v66
	v_max_f32_e32 v56, 0, v56
	v_mul_f32_e32 v68, v68, v68
	v_mul_f32_e32 v67, v67, v67
	v_cvt_pk_bf16_f32 v64, v68, v64
	v_cvt_pk_bf16_f32 v65, v65, v66
	v_cvt_pk_bf16_f32 v66, v72, v69
	v_max_f32_e32 v57, 0, v57
	v_max_f32_e32 v58, 0, v58
	v_cvt_pk_bf16_f32 v67, v70, v67
	global_store_dwordx4 v[80:81], v[64:67], off offset:256
	s_nop 0
	v_max_f32_e32 v60, 0, v60
	v_mul_f32_e32 v66, v56, v56
	v_max_f32_e32 v56, 0, v61
	v_mul_f32_e32 v61, v57, v57
	v_max_f32_e32 v57, 0, v62
	v_mul_f32_e32 v62, v58, v58
	v_max_f32_e32 v58, 0, v63
	v_mul_f32_e32 v60, v60, v60
	v_mul_f32_e32 v56, v56, v56
	v_max_f32_e32 v59, 0, v59
	v_mul_f32_e32 v57, v57, v57
	v_mul_f32_e32 v58, v58, v58
	v_cvt_pk_bf16_f32 v56, v60, v56
	v_add_co_u32_e32 v60, vcc, s65, v144
	v_max_f32_e32 v48, 0, v48
	v_max_f32_e32 v49, 0, v49
	v_max_f32_e32 v50, 0, v50
	v_mul_f32_e32 v59, v59, v59
	v_cvt_pk_bf16_f32 v57, v57, v58
	v_cvt_pk_bf16_f32 v58, v66, v61
	v_addc_co_u32_e32 v61, vcc, 0, v145, vcc
	v_cvt_pk_bf16_f32 v59, v62, v59
	global_store_dwordx4 v[60:61], v[56:59], off
	v_max_f32_e32 v52, 0, v52
	v_max_f32_e32 v51, 0, v51
	v_mul_f32_e32 v56, v48, v48
	v_max_f32_e32 v48, 0, v53
	v_mul_f32_e32 v53, v49, v49
	v_max_f32_e32 v49, 0, v54
	v_mul_f32_e32 v54, v50, v50
	v_max_f32_e32 v50, 0, v55
	v_mul_f32_e32 v48, v48, v48
	v_mul_f32_e32 v49, v49, v49
	v_mul_f32_e32 v50, v50, v50
	v_max_f32_e32 v40, 0, v40
	v_lshl_add_u64 v[64:65], v[144:145], 0, s[14:15]
	v_mul_f32_e32 v52, v52, v52
	v_mul_f32_e32 v51, v51, v51
	v_cvt_pk_bf16_f32 v48, v52, v48
	v_cvt_pk_bf16_f32 v49, v49, v50
	v_cvt_pk_bf16_f32 v50, v56, v53
	v_max_f32_e32 v41, 0, v41
	v_max_f32_e32 v42, 0, v42
	v_cvt_pk_bf16_f32 v51, v54, v51
	global_store_dwordx4 v[64:65], v[48:51], off offset:256
	s_nop 0
	v_max_f32_e32 v44, 0, v44
	v_mul_f32_e32 v50, v40, v40
	v_max_f32_e32 v40, 0, v45
	v_mul_f32_e32 v45, v41, v41
	v_max_f32_e32 v41, 0, v46
	v_mul_f32_e32 v46, v42, v42
	v_max_f32_e32 v42, 0, v47
	v_mul_f32_e32 v44, v44, v44
	v_mul_f32_e32 v40, v40, v40
	v_max_f32_e32 v43, 0, v43
	v_mul_f32_e32 v41, v41, v41
	v_mul_f32_e32 v42, v42, v42
	v_cvt_pk_bf16_f32 v40, v44, v40
	v_add_co_u32_e32 v44, vcc, s66, v144
	v_max_f32_e32 v32, 0, v32
	v_max_f32_e32 v33, 0, v33
	v_max_f32_e32 v34, 0, v34
	v_mul_f32_e32 v43, v43, v43
	v_cvt_pk_bf16_f32 v41, v41, v42
	v_cvt_pk_bf16_f32 v42, v50, v45
	v_addc_co_u32_e32 v45, vcc, 0, v145, vcc
	v_cvt_pk_bf16_f32 v43, v46, v43
	global_store_dwordx4 v[44:45], v[40:43], off
	v_max_f32_e32 v36, 0, v36
	v_max_f32_e32 v35, 0, v35
	v_mul_f32_e32 v40, v32, v32
	v_max_f32_e32 v32, 0, v37
	v_mul_f32_e32 v37, v33, v33
	v_max_f32_e32 v33, 0, v38
	v_mul_f32_e32 v38, v34, v34
	v_max_f32_e32 v34, 0, v39
	v_mul_f32_e32 v32, v32, v32
	v_mul_f32_e32 v33, v33, v33
	v_mul_f32_e32 v34, v34, v34
	v_max_f32_e32 v24, 0, v24
	v_lshl_add_u64 v[48:49], v[144:145], 0, s[16:17]
	v_mul_f32_e32 v36, v36, v36
	v_mul_f32_e32 v35, v35, v35
	v_cvt_pk_bf16_f32 v32, v36, v32
	v_cvt_pk_bf16_f32 v33, v33, v34
	v_cvt_pk_bf16_f32 v34, v40, v37
	v_max_f32_e32 v25, 0, v25
	v_max_f32_e32 v26, 0, v26
	v_cvt_pk_bf16_f32 v35, v38, v35
	global_store_dwordx4 v[48:49], v[32:35], off offset:256
	s_nop 0
	v_max_f32_e32 v28, 0, v28
	v_mul_f32_e32 v34, v24, v24
	v_max_f32_e32 v24, 0, v29
	v_mul_f32_e32 v29, v25, v25
	v_max_f32_e32 v25, 0, v30
	v_mul_f32_e32 v30, v26, v26
	v_max_f32_e32 v26, 0, v31
	v_mul_f32_e32 v28, v28, v28
	v_mul_f32_e32 v24, v24, v24
	v_max_f32_e32 v27, 0, v27
	v_mul_f32_e32 v25, v25, v25
	v_mul_f32_e32 v26, v26, v26
	v_cvt_pk_bf16_f32 v24, v28, v24
	v_add_co_u32_e32 v28, vcc, s67, v144
	v_max_f32_e32 v16, 0, v16
	v_max_f32_e32 v17, 0, v17
	v_max_f32_e32 v18, 0, v18
	v_mul_f32_e32 v27, v27, v27
	v_cvt_pk_bf16_f32 v25, v25, v26
	v_cvt_pk_bf16_f32 v26, v34, v29
	v_addc_co_u32_e32 v29, vcc, 0, v145, vcc
	v_cvt_pk_bf16_f32 v27, v30, v27
	global_store_dwordx4 v[28:29], v[24:27], off
	v_max_f32_e32 v20, 0, v20
	v_max_f32_e32 v19, 0, v19
	v_mul_f32_e32 v24, v16, v16
	v_max_f32_e32 v16, 0, v21
	v_mul_f32_e32 v21, v17, v17
	v_max_f32_e32 v17, 0, v22
	v_mul_f32_e32 v22, v18, v18
	v_max_f32_e32 v18, 0, v23
	v_mul_f32_e32 v16, v16, v16
	v_mul_f32_e32 v17, v17, v17
	v_mul_f32_e32 v18, v18, v18
	v_max_f32_e32 v8, 0, v8
	v_lshl_add_u64 v[32:33], v[144:145], 0, s[18:19]
	v_mul_f32_e32 v20, v20, v20
	v_mul_f32_e32 v19, v19, v19
	v_cvt_pk_bf16_f32 v16, v20, v16
	v_cvt_pk_bf16_f32 v17, v17, v18
	v_cvt_pk_bf16_f32 v18, v24, v21
	v_max_f32_e32 v9, 0, v9
	v_max_f32_e32 v10, 0, v10
	v_cvt_pk_bf16_f32 v19, v22, v19
	global_store_dwordx4 v[32:33], v[16:19], off offset:256
	s_nop 0
	v_max_f32_e32 v12, 0, v12
	v_mul_f32_e32 v18, v8, v8
	v_max_f32_e32 v8, 0, v13
	v_mul_f32_e32 v13, v9, v9
	v_max_f32_e32 v9, 0, v14
	v_mul_f32_e32 v14, v10, v10
	v_max_f32_e32 v10, 0, v15
	v_mul_f32_e32 v12, v12, v12
	v_mul_f32_e32 v8, v8, v8
	v_max_f32_e32 v11, 0, v11
	v_mul_f32_e32 v9, v9, v9
	v_mul_f32_e32 v10, v10, v10
	v_cvt_pk_bf16_f32 v8, v12, v8
	v_add_co_u32_e32 v12, vcc, s68, v144
	v_max_f32_e32 v0, 0, v0
	v_max_f32_e32 v1, 0, v1
	v_max_f32_e32 v2, 0, v2
	v_mul_f32_e32 v11, v11, v11
	v_cvt_pk_bf16_f32 v9, v9, v10
	v_cvt_pk_bf16_f32 v10, v18, v13
	v_addc_co_u32_e32 v13, vcc, 0, v145, vcc
	v_cvt_pk_bf16_f32 v11, v14, v11
	global_store_dwordx4 v[12:13], v[8:11], off
	v_max_f32_e32 v3, 0, v3
	v_max_f32_e32 v4, 0, v4
	v_mul_f32_e32 v8, v0, v0
	v_max_f32_e32 v0, 0, v5
	v_mul_f32_e32 v5, v1, v1
	v_max_f32_e32 v1, 0, v6
	v_mul_f32_e32 v6, v2, v2
	v_max_f32_e32 v2, 0, v7
	v_lshl_add_u64 v[16:17], v[144:145], 0, s[20:21]
	v_mul_f32_e32 v0, v0, v0
	v_mul_f32_e32 v1, v1, v1
	v_mul_f32_e32 v2, v2, v2
	v_mul_f32_e32 v3, v3, v3
	s_and_b64 vcc, exec, s[4:5]
	s_mov_b32 s69, s22
	s_mov_b32 s38, s24
	s_mov_b64 s[40:41], s[0:1]
	s_mov_b64 s[42:43], s[36:37]
	v_mul_f32_e32 v4, v4, v4
	v_cvt_pk_bf16_f32 v0, v4, v0
	v_cvt_pk_bf16_f32 v1, v1, v2
	v_cvt_pk_bf16_f32 v2, v8, v5
	v_cvt_pk_bf16_f32 v3, v6, v3
	global_store_dwordx4 v[16:17], v[0:3], off offset:256
	s_cbranch_vccz .LBB0_428
	s_waitcnt vmcnt(0)
	s_cmpk_gt_u32 s46, 0xff
	s_cbranch_scc1 .LBB0_437
	s_barrier

; #define PG8_STAGE(bufoff, gbase, voff) do { _Pragma("unroll") for (int _i = 0; _i < 2; ++_i) \
;         __builtin_amdgcn_global_load_lds((const unsigned*)((const char*)(gbase) + (voff)[_i]), (LAS unsigned*)(lds + (bufoff) + ldsw + _i * 8192), 16, 0, 0); } while (0)
; #define PG8_LDA(dst, b, h) do { _Pragma("unroll") for (int m = 0; m < 4; ++m) _Pragma("unroll") for (int k = 0; k < 2; ++k) dst[m][k] = *(const LAS bf16x8*)(lds + PG8_SA(b, h) + aoff + m * 2048 + k * 1024); } while (0)
; #define PG8_LDB(dst, b, h) do { _Pragma("unroll") for (int n = 0; n < 2; ++n) _Pragma("unroll") for (int k = 0; k < 2; ++k) dst[n][k] = *(const LAS bf16x8*)(lds + PG8_SB(b, h) + boff + n * 2048 + k * 1024); } while (0)
; #define PG8_MMA(ai, bj, At, Bt) do { __builtin_amdgcn_s_setprio(1); _Pragma("unroll") for (int m = 0; m < 4; ++m) _Pragma("unroll") for (int n = 0; n < 2; ++n) _Pragma("unroll") for (int k = 0; k < 2; ++k) \
;         acc[ai][bj][m][n] = __builtin_amdgcn_mfma_f32_16x16x32_bf16(Bt[n][k], At[m][k], acc[ai][bj][m][n], 0, 0, 0); __builtin_amdgcn_s_setprio(0); } while (0)
; #define PG8_WAIT_L(n) asm volatile("s_waitcnt lgkmcnt(" #n ")" ::: "memory")
; #define PG8_BAR __builtin_amdgcn_s_barrier()
; #define PG8_SCHED __builtin_amdgcn_sched_barrier(0)
; template <class Epi, class Ptrs>
; __device__ __forceinline__ void gemm_phase(LAS unsigned char* lds, const int K, const StaticOrder& S, const Ptrs& P, const Epi& E) {
;     ...
;         for (int t = 0; t < nt; t += 2) {
;             const bool last = (t == nt - 2);
;             const char* a1 = cA + (size_t)(t + 1) * kstep;
;             const char* a2 = last ? nA : cA + (size_t)(t + 2) * kstep; const char* b2 = last ? nB : cB + (size_t)(t + 2) * kstep;
;             const char* a3 = a2 + kstep; const char* b3 = b2 + kstep;
;             PG8_LDB(B0, 0, 0); PG8_SCHED; PG8_LDA(At, 0, 0); PG8_STAGE(PG8_SA(1, 1), a1 + hstep, voffA);
;             PG8_WAIT_L(8); PG8_BAR; PG8_WAIT_L(0); PG8_MMA(0, 0, At, B0); PG8_BAR; PG8_SCHED;
;     ...
; #pragma unroll
;         for (int a = 0; a < 2; ++a)
; #pragma unroll
;             for (int b = 0; b < 2; ++b)
; #pragma unroll
;                 for (int m = 0; m < 4; ++m)
; #pragma unroll
;                     for (int n = 0; n < 2; ++n) acc[a][b][m][n] = (f32x4){0.f, 0.f, 0.f, 0.f};
.LBB0_521:
	s_add_u32 s20, s20, 0x100080
	s_nop 0
	s_nop 0
	s_nop 0
	s_nop 0
	s_nop 0
	s_nop 0
	s_nop 0
	s_nop 0
	s_nop 0
	s_nop 0
	s_nop 0
	s_nop 0
	s_nop 0
	s_nop 0
	s_nop 0
	s_nop 0
	s_nop 0
	s_nop 0
	s_nop 0
	s_nop 0
	s_nop 0
	s_nop 0
	s_nop 0
	s_nop 0
	s_nop 0
	s_nop 0
	s_nop 0
	s_nop 0
	s_nop 0
	s_nop 0
	s_nop 0
	s_nop 0
	s_nop 0
	s_nop 0
	s_nop 0
	s_nop 0
	s_nop 0
	s_nop 0
	s_nop 0
	s_nop 0
	s_nop 0
	s_nop 0
	s_nop 0
	s_nop 0
	s_nop 0
	s_nop 0
	s_nop 0
	s_nop 0
	s_nop 0
	s_nop 0
	s_nop 0
	s_nop 0
	s_nop 0
	s_nop 0
	s_nop 0
	s_nop 0
	s_nop 0
	s_nop 0
	s_nop 0
	s_nop 0
	s_nop 0
	s_nop 0
	s_addc_u32 s21, s21, 0
	s_add_u32 s11, s22, 0x100
	v_mov_b32_e32 v0, 0
	s_addc_u32 s13, s23, 0
	s_mov_b32 s46, -2
	v_mov_b32_e32 v1, v0
	v_mov_b32_e32 v2, v0
	v_mov_b32_e32 v3, v0
	v_mov_b32_e32 v4, v0
	v_mov_b32_e32 v5, v0
	v_mov_b32_e32 v6, v0
	v_mov_b32_e32 v7, v0
	v_mov_b32_e32 v12, v0
	v_mov_b32_e32 v13, v0
	v_mov_b32_e32 v14, v0
	v_mov_b32_e32 v15, v0
	v_mov_b32_e32 v20, v0
	v_mov_b32_e32 v21, v0
	v_mov_b32_e32 v22, v0
	v_mov_b32_e32 v23, v0
	v_mov_b32_e32 v28, v0
	v_mov_b32_e32 v29, v0
	v_mov_b32_e32 v30, v0
	v_mov_b32_e32 v31, v0
	v_mov_b32_e32 v36, v0
	v_mov_b32_e32 v37, v0
	v_mov_b32_e32 v38, v0
	v_mov_b32_e32 v39, v0
	v_mov_b32_e32 v44, v0
	v_mov_b32_e32 v45, v0
	v_mov_b32_e32 v46, v0
	v_mov_b32_e32 v47, v0
	v_mov_b32_e32 v52, v0
	v_mov_b32_e32 v53, v0
	v_mov_b32_e32 v54, v0
	v_mov_b32_e32 v55, v0
	v_mov_b32_e32 v8, v0
	v_mov_b32_e32 v9, v0
	v_mov_b32_e32 v10, v0
	v_mov_b32_e32 v11, v0
	v_mov_b32_e32 v16, v0
	v_mov_b32_e32 v17, v0
	v_mov_b32_e32 v18, v0
	v_mov_b32_e32 v19, v0
	v_mov_b32_e32 v24, v0
	v_mov_b32_e32 v25, v0
	v_mov_b32_e32 v26, v0
	v_mov_b32_e32 v27, v0
	v_mov_b32_e32 v32, v0
	v_mov_b32_e32 v33, v0
	v_mov_b32_e32 v34, v0
	v_mov_b32_e32 v35, v0
	v_mov_b32_e32 v40, v0
	v_mov_b32_e32 v41, v0
	v_mov_b32_e32 v42, v0
	v_mov_b32_e32 v43, v0
	v_mov_b32_e32 v48, v0
	v_mov_b32_e32 v49, v0
	v_mov_b32_e32 v50, v0
	v_mov_b32_e32 v51, v0
	v_mov_b32_e32 v56, v0
	v_mov_b32_e32 v57, v0
	v_mov_b32_e32 v58, v0
	v_mov_b32_e32 v59, v0
	v_mov_b32_e32 v60, v0
	v_mov_b32_e32 v61, v0
	v_mov_b32_e32 v62, v0
	v_mov_b32_e32 v63, v0
	v_mov_b32_e32 v64, v0
	v_mov_b32_e32 v65, v0
	v_mov_b32_e32 v66, v0
	v_mov_b32_e32 v67, v0
	v_mov_b32_e32 v68, v0
	v_mov_b32_e32 v69, v0
	v_mov_b32_e32 v70, v0
	v_mov_b32_e32 v71, v0
	v_mov_b32_e32 v80, v0
	v_mov_b32_e32 v81, v0
	v_mov_b32_e32 v82, v0
	v_mov_b32_e32 v83, v0
	v_mov_b32_e32 v84, v0
	v_mov_b32_e32 v85, v0
	v_mov_b32_e32 v86, v0
	v_mov_b32_e32 v87, v0
	v_mov_b32_e32 v96, v0
	v_mov_b32_e32 v97, v0
	v_mov_b32_e32 v98, v0
	v_mov_b32_e32 v99, v0
	v_mov_b32_e32 v100, v0
	v_mov_b32_e32 v101, v0
	v_mov_b32_e32 v102, v0
	v_mov_b32_e32 v103, v0
	v_mov_b32_e32 v108, v0
	v_mov_b32_e32 v109, v0
	v_mov_b32_e32 v110, v0
	v_mov_b32_e32 v111, v0
	v_mov_b32_e32 v116, v0
	v_mov_b32_e32 v117, v0
	v_mov_b32_e32 v118, v0
	v_mov_b32_e32 v119, v0
	v_mov_b32_e32 v72, v0
	v_mov_b32_e32 v73, v0
	v_mov_b32_e32 v74, v0
	v_mov_b32_e32 v75, v0
	v_mov_b32_e32 v76, v0
	v_mov_b32_e32 v77, v0
	v_mov_b32_e32 v78, v0
	v_mov_b32_e32 v79, v0
	v_mov_b32_e32 v88, v0
	v_mov_b32_e32 v89, v0
	v_mov_b32_e32 v90, v0
	v_mov_b32_e32 v91, v0
	v_mov_b32_e32 v92, v0
	v_mov_b32_e32 v93, v0
	v_mov_b32_e32 v94, v0
	v_mov_b32_e32 v95, v0
	v_mov_b32_e32 v104, v0
	v_mov_b32_e32 v105, v0
	v_mov_b32_e32 v106, v0
	v_mov_b32_e32 v107, v0
	v_mov_b32_e32 v112, v0
	v_mov_b32_e32 v113, v0
	v_mov_b32_e32 v114, v0
	v_mov_b32_e32 v115, v0
	v_mov_b32_e32 v120, v0
	v_mov_b32_e32 v121, v0
	v_mov_b32_e32 v122, v0
	v_mov_b32_e32 v123, v0
	v_mov_b32_e32 v124, v0
	v_mov_b32_e32 v125, v0
	v_mov_b32_e32 v126, v0
	v_mov_b32_e32 v127, v0
	v_add_u32_e32 v252, 0x18000, v187
	v_add_u32_e32 v253, 0x1c000, v187
.LBB0_522:
	ds_read_b128 v[128:131], v193
	ds_read_b128 v[132:135], v193 offset:1024
	ds_read_b128 v[136:139], v193 offset:2048
	ds_read_b128 v[140:143], v193 offset:3072
	s_add_u32 s22, s20, 0xfff00080
	s_addc_u32 s23, s21, -1
	s_cmp_eq_u32 s46, 60
	s_cselect_b32 s25, s5, s23
	s_cselect_b32 s24, s4, s22
	s_cselect_b32 s23, s15, s13
	s_cselect_b32 s22, s14, s11
	s_add_i32 m0, s17, 0xc000
	ds_read_b128 v[144:147], v194
	ds_read_b128 v[148:151], v194 offset:1024
	ds_read_b128 v[152:155], v194 offset:2048
	ds_read_b128 v[156:159], v194 offset:3072
	ds_read_b128 v[176:179], v194 offset:4096
	ds_read_b128 v[180:183], v194 offset:5120
	ds_read_b128 v[196:199], v194 offset:6144
	ds_read_b128 v[200:203], v194 offset:7168
	global_load_lds_dwordx4 v168, s[20:21]
	s_add_i32 m0, s17, 0xe000
	s_nop 0
	global_load_lds_dwordx4 v170, s[20:21]
	s_waitcnt lgkmcnt(8)
	s_barrier
	s_waitcnt lgkmcnt(0)
	s_setprio 1
	s_waitcnt lgkmcnt(0)
	v_mfma_f32_16x16x32_bf16 v[124:127], v[128:131], v[144:147], v[124:127]
	v_mfma_f32_16x16x32_bf16 v[124:127], v[132:135], v[148:151], v[124:127]
	v_mfma_f32_16x16x32_bf16 v[120:123], v[140:143], v[148:151], v[120:123]
	v_mfma_f32_16x16x32_bf16 v[120:123], v[136:139], v[144:147], v[120:123]
	v_mfma_f32_16x16x32_bf16 v[104:107], v[136:139], v[152:155], v[104:107]
	v_mfma_f32_16x16x32_bf16 v[104:107], v[140:143], v[156:159], v[104:107]
	v_mfma_f32_16x16x32_bf16 v[112:115], v[132:135], v[156:159], v[112:115]
	v_mfma_f32_16x16x32_bf16 v[112:115], v[128:131], v[152:155], v[112:115]
	v_mfma_f32_16x16x32_bf16 v[92:95], v[128:131], v[176:179], v[92:95]
	v_mfma_f32_16x16x32_bf16 v[92:95], v[132:135], v[180:183], v[92:95]
	v_mfma_f32_16x16x32_bf16 v[88:91], v[140:143], v[180:183], v[88:91]
	v_mfma_f32_16x16x32_bf16 v[88:91], v[136:139], v[176:179], v[88:91]
	v_mfma_f32_16x16x32_bf16 v[72:75], v[136:139], v[196:199], v[72:75]
	v_mfma_f32_16x16x32_bf16 v[72:75], v[140:143], v[200:203], v[72:75]
	v_mfma_f32_16x16x32_bf16 v[76:79], v[132:135], v[200:203], v[76:79]
	v_mfma_f32_16x16x32_bf16 v[76:79], v[128:131], v[196:199], v[76:79]
	s_setprio 0
	s_barrier
; #define PG8_STAGE(bufoff, gbase, voff) do { _Pragma("unroll") for (int _i = 0; _i < 2; ++_i) \
;         __builtin_amdgcn_global_load_lds((const unsigned*)((const char*)(gbase) + (voff)[_i]), (LAS unsigned*)(lds + (bufoff) + ldsw + _i * 8192), 16, 0, 0); } while (0)
; #define PG8_LDA(dst, b, h) do { _Pragma("unroll") for (int m = 0; m < 4; ++m) _Pragma("unroll") for (int k = 0; k < 2; ++k) dst[m][k] = *(const LAS bf16x8*)(lds + PG8_SA(b, h) + aoff + m * 2048 + k * 1024); } while (0)
; #define PG8_LDB(dst, b, h) do { _Pragma("unroll") for (int n = 0; n < 2; ++n) _Pragma("unroll") for (int k = 0; k < 2; ++k) dst[n][k] = *(const LAS bf16x8*)(lds + PG8_SB(b, h) + boff + n * 2048 + k * 1024); } while (0)
; #define PG8_MMA(ai, bj, At, Bt) do { __builtin_amdgcn_s_setprio(1); _Pragma("unroll") for (int m = 0; m < 4; ++m) _Pragma("unroll") for (int n = 0; n < 2; ++n) _Pragma("unroll") for (int k = 0; k < 2; ++k) \
;         acc[ai][bj][m][n] = __builtin_amdgcn_mfma_f32_16x16x32_bf16(Bt[n][k], At[m][k], acc[ai][bj][m][n], 0, 0, 0); __builtin_amdgcn_s_setprio(0); } while (0)
; #define PG8_WAIT_V(n) asm volatile("s_waitcnt vmcnt(" #n ")" ::: "memory")
; #define PG8_WAIT_L(n) asm volatile("s_waitcnt lgkmcnt(" #n ")" ::: "memory")
; #define PG8_BAR __builtin_amdgcn_s_barrier()
; #define PG8_SCHED __builtin_amdgcn_sched_barrier(0)
; template <class Epi, class Ptrs>
; __device__ __forceinline__ void gemm_phase(LAS unsigned char* lds, const int K, const StaticOrder& S, const Ptrs& P, const Epi& E) {
;     ...
;             PG8_LDB(B1, 0, 1); PG8_STAGE(PG8_SB(0, 0), b2, voffB);
;             PG8_BAR; PG8_WAIT_L(0); PG8_MMA(0, 1, At, B1); PG8_BAR;
;             PG8_LDA(At, 0, 1); PG8_STAGE(PG8_SA(0, 0), a2, voffA);
;             PG8_BAR; PG8_WAIT_L(0); PG8_MMA(1, 0, At, B0); PG8_BAR; PG8_SCHED;
;             PG8_STAGE(PG8_SB(0, 1), b2 + hstep, voffB);
;             PG8_WAIT_V(6); PG8_BAR; PG8_MMA(1, 1, At, B1); PG8_BAR;
;             PG8_LDB(B0, 1, 0); PG8_SCHED; PG8_LDA(At, 1, 0); PG8_STAGE(PG8_SA(0, 1), a2 + hstep, voffA);
	s_add_i32 s47, s42, s34
	s_add_u32 s90, s22, 0x80
	s_addc_u32 s91, s23, 0
	s_mov_b32 m0, s47
	ds_read_b128 v[204:207], v195
	ds_read_b128 v[208:211], v195 offset:1024
	ds_read_b128 v[212:215], v195 offset:2048
	ds_read_b128 v[216:219], v195 offset:3072
	global_load_lds_dwordx4 v162, s[22:23]
	s_add_i32 m0, s47, 0x2000
	s_nop 0
	global_load_lds_dwordx4 v166, s[22:23]
	s_barrier
	s_waitcnt lgkmcnt(0)
	s_setprio 1
	s_waitcnt lgkmcnt(0)
	v_mfma_f32_16x16x32_bf16 v[116:119], v[204:207], v[144:147], v[116:119]
	v_mfma_f32_16x16x32_bf16 v[116:119], v[208:211], v[148:151], v[116:119]
	v_mfma_f32_16x16x32_bf16 v[108:111], v[216:219], v[148:151], v[108:111]
	v_mfma_f32_16x16x32_bf16 v[108:111], v[212:215], v[144:147], v[108:111]
	v_mfma_f32_16x16x32_bf16 v[96:99], v[212:215], v[152:155], v[96:99]
	v_mfma_f32_16x16x32_bf16 v[96:99], v[216:219], v[156:159], v[96:99]
	v_mfma_f32_16x16x32_bf16 v[100:103], v[208:211], v[156:159], v[100:103]
	v_mfma_f32_16x16x32_bf16 v[100:103], v[204:207], v[152:155], v[100:103]
	v_mfma_f32_16x16x32_bf16 v[84:87], v[204:207], v[176:179], v[84:87]
	v_mfma_f32_16x16x32_bf16 v[84:87], v[208:211], v[180:183], v[84:87]
	v_mfma_f32_16x16x32_bf16 v[80:83], v[216:219], v[180:183], v[80:83]
	v_mfma_f32_16x16x32_bf16 v[80:83], v[212:215], v[176:179], v[80:83]
	v_mfma_f32_16x16x32_bf16 v[64:67], v[212:215], v[196:199], v[64:67]
	v_mfma_f32_16x16x32_bf16 v[64:67], v[216:219], v[200:203], v[64:67]
	v_mfma_f32_16x16x32_bf16 v[68:71], v[208:211], v[200:203], v[68:71]
	v_mfma_f32_16x16x32_bf16 v[68:71], v[204:207], v[196:199], v[68:71]
	s_setprio 0
	s_mov_b32 m0, s17
	s_add_u32 s92, s24, 0x80
	s_addc_u32 s93, s25, 0
	s_barrier
	ds_read_b128 v[144:147], v194 offset:16384
	ds_read_b128 v[148:151], v194 offset:17408
	ds_read_b128 v[152:155], v194 offset:18432
	ds_read_b128 v[156:159], v194 offset:19456
	ds_read_b128 v[176:179], v194 offset:20480
	ds_read_b128 v[180:183], v194 offset:21504
	ds_read_b128 v[196:199], v194 offset:22528
	ds_read_b128 v[200:203], v194 offset:23552
	global_load_lds_dwordx4 v160, s[24:25]
	s_mov_b32 m0, s19
	s_nop 0
	global_load_lds_dwordx4 v164, s[24:25]
	s_barrier
	s_waitcnt lgkmcnt(0)
	s_setprio 1
	s_waitcnt lgkmcnt(0)
	v_mfma_f32_16x16x32_bf16 v[60:63], v[128:131], v[144:147], v[60:63]
	v_mfma_f32_16x16x32_bf16 v[60:63], v[132:135], v[148:151], v[60:63]
	v_mfma_f32_16x16x32_bf16 v[56:59], v[140:143], v[148:151], v[56:59]
	v_mfma_f32_16x16x32_bf16 v[56:59], v[136:139], v[144:147], v[56:59]
	v_mfma_f32_16x16x32_bf16 v[40:43], v[136:139], v[152:155], v[40:43]
	v_mfma_f32_16x16x32_bf16 v[40:43], v[140:143], v[156:159], v[40:43]
	v_mfma_f32_16x16x32_bf16 v[48:51], v[132:135], v[156:159], v[48:51]
	v_mfma_f32_16x16x32_bf16 v[48:51], v[128:131], v[152:155], v[48:51]
	v_mfma_f32_16x16x32_bf16 v[32:35], v[128:131], v[176:179], v[32:35]
	v_mfma_f32_16x16x32_bf16 v[32:35], v[132:135], v[180:183], v[32:35]
	v_mfma_f32_16x16x32_bf16 v[24:27], v[140:143], v[180:183], v[24:27]
	v_mfma_f32_16x16x32_bf16 v[24:27], v[136:139], v[176:179], v[24:27]
	v_mfma_f32_16x16x32_bf16 v[8:11], v[136:139], v[196:199], v[8:11]
	v_mfma_f32_16x16x32_bf16 v[8:11], v[140:143], v[200:203], v[8:11]
	v_mfma_f32_16x16x32_bf16 v[16:19], v[132:135], v[200:203], v[16:19]
	v_mfma_f32_16x16x32_bf16 v[16:19], v[128:131], v[196:199], v[16:19]
	s_setprio 0
	s_barrier
	s_add_u32 s48, s22, 0x100000
	s_addc_u32 s49, s23, 0
	s_add_i32 s47, s43, s34
	s_mov_b32 m0, s47
	s_nop 0
	global_load_lds_dwordx4 v162, s[48:49]
	s_add_i32 m0, s47, 0x2000
	s_nop 0
	global_load_lds_dwordx4 v166, s[48:49]
	s_waitcnt vmcnt(6)
	s_barrier
	s_setprio 1
	v_mfma_f32_16x16x32_bf16 v[52:55], v[204:207], v[144:147], v[52:55]
	v_mfma_f32_16x16x32_bf16 v[52:55], v[208:211], v[148:151], v[52:55]
	v_mfma_f32_16x16x32_bf16 v[44:47], v[216:219], v[148:151], v[44:47]
	v_mfma_f32_16x16x32_bf16 v[44:47], v[212:215], v[144:147], v[44:47]
	v_mfma_f32_16x16x32_bf16 v[28:31], v[212:215], v[152:155], v[28:31]
	v_mfma_f32_16x16x32_bf16 v[28:31], v[216:219], v[156:159], v[28:31]
	v_mfma_f32_16x16x32_bf16 v[36:39], v[208:211], v[156:159], v[36:39]
	v_mfma_f32_16x16x32_bf16 v[36:39], v[204:207], v[152:155], v[36:39]
	v_mfma_f32_16x16x32_bf16 v[20:23], v[204:207], v[176:179], v[20:23]
	v_mfma_f32_16x16x32_bf16 v[20:23], v[208:211], v[180:183], v[20:23]
	v_mfma_f32_16x16x32_bf16 v[12:15], v[216:219], v[180:183], v[12:15]
	v_mfma_f32_16x16x32_bf16 v[12:15], v[212:215], v[176:179], v[12:15]
	v_mfma_f32_16x16x32_bf16 v[0:3], v[212:215], v[196:199], v[0:3]
	v_mfma_f32_16x16x32_bf16 v[0:3], v[216:219], v[200:203], v[0:3]
	v_mfma_f32_16x16x32_bf16 v[4:7], v[208:211], v[200:203], v[4:7]
	v_mfma_f32_16x16x32_bf16 v[4:7], v[204:207], v[196:199], v[4:7]
	s_setprio 0
	s_add_i32 s47, 0, 0x18000
	s_barrier
	ds_read_b128 v[128:131], v252
	ds_read_b128 v[132:135], v252 offset:1024
	ds_read_b128 v[136:139], v252 offset:2048
	ds_read_b128 v[140:143], v252 offset:3072
	s_add_u32 s24, s24, 0x100000
	s_addc_u32 s25, s25, 0
	s_mov_b32 m0, s40
	ds_read_b128 v[144:147], v194 offset:32768
	ds_read_b128 v[148:151], v194 offset:33792
	ds_read_b128 v[152:155], v194 offset:34816
	ds_read_b128 v[156:159], v194 offset:35840
	ds_read_b128 v[176:179], v194 offset:36864
	ds_read_b128 v[180:183], v194 offset:37888
	ds_read_b128 v[196:199], v194 offset:38912
	ds_read_b128 v[200:203], v194 offset:39936
	global_load_lds_dwordx4 v160, s[24:25]
	s_mov_b32 m0, s41
	s_nop 0
	global_load_lds_dwordx4 v164, s[24:25]
	s_waitcnt lgkmcnt(8)
	s_barrier
; #define PG8_STAGE(bufoff, gbase, voff) do { _Pragma("unroll") for (int _i = 0; _i < 2; ++_i) \
;         __builtin_amdgcn_global_load_lds((const unsigned*)((const char*)(gbase) + (voff)[_i]), (LAS unsigned*)(lds + (bufoff) + ldsw + _i * 8192), 16, 0, 0); } while (0)
; #define PG8_LDA(dst, b, h) do { _Pragma("unroll") for (int m = 0; m < 4; ++m) _Pragma("unroll") for (int k = 0; k < 2; ++k) dst[m][k] = *(const LAS bf16x8*)(lds + PG8_SA(b, h) + aoff + m * 2048 + k * 1024); } while (0)
; #define PG8_LDB(dst, b, h) do { _Pragma("unroll") for (int n = 0; n < 2; ++n) _Pragma("unroll") for (int k = 0; k < 2; ++k) dst[n][k] = *(const LAS bf16x8*)(lds + PG8_SB(b, h) + boff + n * 2048 + k * 1024); } while (0)
; #define PG8_MMA(ai, bj, At, Bt) do { __builtin_amdgcn_s_setprio(1); _Pragma("unroll") for (int m = 0; m < 4; ++m) _Pragma("unroll") for (int n = 0; n < 2; ++n) _Pragma("unroll") for (int k = 0; k < 2; ++k) \
;         acc[ai][bj][m][n] = __builtin_amdgcn_mfma_f32_16x16x32_bf16(Bt[n][k], At[m][k], acc[ai][bj][m][n], 0, 0, 0); __builtin_amdgcn_s_setprio(0); } while (0)
; #define PG8_WAIT_V(n) asm volatile("s_waitcnt vmcnt(" #n ")" ::: "memory")
; #define PG8_WAIT_L(n) asm volatile("s_waitcnt lgkmcnt(" #n ")" ::: "memory")
; #define PG8_BAR __builtin_amdgcn_s_barrier()
; #define PG8_SCHED __builtin_amdgcn_sched_barrier(0)
; template <class Epi, class Ptrs>
; __device__ __forceinline__ void gemm_phase(LAS unsigned char* lds, const int K, const StaticOrder& S, const Ptrs& P, const Epi& E) {
;     ...
;             PG8_WAIT_L(8); PG8_BAR; PG8_WAIT_L(0); PG8_MMA(0, 0, At, B0); PG8_BAR; PG8_SCHED;
;             PG8_LDB(B1, 1, 1); PG8_STAGE(PG8_SB(1, 0), b3, voffB);
;             PG8_BAR; PG8_WAIT_L(0); PG8_MMA(0, 1, At, B1); PG8_BAR;
;             PG8_LDA(At, 1, 1); PG8_STAGE(PG8_SA(1, 0), a3, voffA);
;             PG8_BAR; PG8_WAIT_L(0); PG8_MMA(1, 0, At, B0); PG8_BAR; PG8_SCHED;
;             PG8_STAGE(PG8_SB(1, 1), b3 + hstep, voffB);
;             PG8_WAIT_V(6); PG8_BAR; PG8_MMA(1, 1, At, B1); PG8_BAR;
	s_waitcnt lgkmcnt(0)
	s_setprio 1
	s_waitcnt lgkmcnt(0)
	v_mfma_f32_16x16x32_bf16 v[124:127], v[128:131], v[144:147], v[124:127]
	v_mfma_f32_16x16x32_bf16 v[124:127], v[132:135], v[148:151], v[124:127]
	v_mfma_f32_16x16x32_bf16 v[120:123], v[140:143], v[148:151], v[120:123]
	v_mfma_f32_16x16x32_bf16 v[120:123], v[136:139], v[144:147], v[120:123]
	v_mfma_f32_16x16x32_bf16 v[104:107], v[136:139], v[152:155], v[104:107]
	v_mfma_f32_16x16x32_bf16 v[104:107], v[140:143], v[156:159], v[104:107]
	v_mfma_f32_16x16x32_bf16 v[112:115], v[132:135], v[156:159], v[112:115]
	v_mfma_f32_16x16x32_bf16 v[112:115], v[128:131], v[152:155], v[112:115]
	v_mfma_f32_16x16x32_bf16 v[92:95], v[128:131], v[176:179], v[92:95]
	v_mfma_f32_16x16x32_bf16 v[92:95], v[132:135], v[180:183], v[92:95]
	v_mfma_f32_16x16x32_bf16 v[88:91], v[140:143], v[180:183], v[88:91]
	v_mfma_f32_16x16x32_bf16 v[88:91], v[136:139], v[176:179], v[88:91]
	v_mfma_f32_16x16x32_bf16 v[72:75], v[136:139], v[196:199], v[72:75]
	v_mfma_f32_16x16x32_bf16 v[72:75], v[140:143], v[200:203], v[72:75]
	v_mfma_f32_16x16x32_bf16 v[76:79], v[132:135], v[200:203], v[76:79]
	v_mfma_f32_16x16x32_bf16 v[76:79], v[128:131], v[196:199], v[76:79]
	s_setprio 0
	s_barrier
	s_add_i32 s24, 0, 0x1c000
	s_add_i32 s25, s47, s34
	s_mov_b32 m0, s25
	ds_read_b128 v[204:207], v253
	ds_read_b128 v[208:211], v253 offset:1024
	ds_read_b128 v[212:215], v253 offset:2048
	ds_read_b128 v[216:219], v253 offset:3072
	global_load_lds_dwordx4 v162, s[90:91]
	s_add_i32 m0, s25, 0x2000
	s_nop 0
	global_load_lds_dwordx4 v166, s[90:91]
	s_barrier
	s_waitcnt lgkmcnt(0)
	s_setprio 1
	s_waitcnt lgkmcnt(0)
	v_mfma_f32_16x16x32_bf16 v[116:119], v[204:207], v[144:147], v[116:119]
	v_mfma_f32_16x16x32_bf16 v[116:119], v[208:211], v[148:151], v[116:119]
	v_mfma_f32_16x16x32_bf16 v[108:111], v[216:219], v[148:151], v[108:111]
	v_mfma_f32_16x16x32_bf16 v[108:111], v[212:215], v[144:147], v[108:111]
	v_mfma_f32_16x16x32_bf16 v[96:99], v[212:215], v[152:155], v[96:99]
	v_mfma_f32_16x16x32_bf16 v[96:99], v[216:219], v[156:159], v[96:99]
	v_mfma_f32_16x16x32_bf16 v[100:103], v[208:211], v[156:159], v[100:103]
	v_mfma_f32_16x16x32_bf16 v[100:103], v[204:207], v[152:155], v[100:103]
	v_mfma_f32_16x16x32_bf16 v[84:87], v[204:207], v[176:179], v[84:87]
	v_mfma_f32_16x16x32_bf16 v[84:87], v[208:211], v[180:183], v[84:87]
	v_mfma_f32_16x16x32_bf16 v[80:83], v[216:219], v[180:183], v[80:83]
	v_mfma_f32_16x16x32_bf16 v[80:83], v[212:215], v[176:179], v[80:83]
	v_mfma_f32_16x16x32_bf16 v[64:67], v[212:215], v[196:199], v[64:67]
	v_mfma_f32_16x16x32_bf16 v[64:67], v[216:219], v[200:203], v[64:67]
	v_mfma_f32_16x16x32_bf16 v[68:71], v[208:211], v[200:203], v[68:71]
	v_mfma_f32_16x16x32_bf16 v[68:71], v[204:207], v[196:199], v[68:71]
	s_setprio 0
	s_mov_b32 m0, s28
	s_barrier
	ds_read_b128 v[144:147], v194 offset:49152
	ds_read_b128 v[148:151], v194 offset:50176
	ds_read_b128 v[152:155], v194 offset:51200
	ds_read_b128 v[156:159], v194 offset:52224
	ds_read_b128 v[176:179], v194 offset:53248
	ds_read_b128 v[180:183], v194 offset:54272
	ds_read_b128 v[196:199], v194 offset:55296
	ds_read_b128 v[200:203], v194 offset:56320
	global_load_lds_dwordx4 v160, s[92:93]
	s_mov_b32 m0, s29
	s_nop 0
	global_load_lds_dwordx4 v164, s[92:93]
	s_barrier
	s_waitcnt lgkmcnt(0)
	s_setprio 1
	s_waitcnt lgkmcnt(0)
	v_mfma_f32_16x16x32_bf16 v[60:63], v[128:131], v[144:147], v[60:63]
	v_mfma_f32_16x16x32_bf16 v[60:63], v[132:135], v[148:151], v[60:63]
	v_mfma_f32_16x16x32_bf16 v[56:59], v[140:143], v[148:151], v[56:59]
	v_mfma_f32_16x16x32_bf16 v[56:59], v[136:139], v[144:147], v[56:59]
	v_mfma_f32_16x16x32_bf16 v[40:43], v[136:139], v[152:155], v[40:43]
	v_mfma_f32_16x16x32_bf16 v[40:43], v[140:143], v[156:159], v[40:43]
	v_mfma_f32_16x16x32_bf16 v[48:51], v[132:135], v[156:159], v[48:51]
	v_mfma_f32_16x16x32_bf16 v[48:51], v[128:131], v[152:155], v[48:51]
	v_mfma_f32_16x16x32_bf16 v[32:35], v[128:131], v[176:179], v[32:35]
	v_mfma_f32_16x16x32_bf16 v[32:35], v[132:135], v[180:183], v[32:35]
	v_mfma_f32_16x16x32_bf16 v[24:27], v[140:143], v[180:183], v[24:27]
	v_mfma_f32_16x16x32_bf16 v[24:27], v[136:139], v[176:179], v[24:27]
	v_mfma_f32_16x16x32_bf16 v[8:11], v[136:139], v[196:199], v[8:11]
	v_mfma_f32_16x16x32_bf16 v[8:11], v[140:143], v[200:203], v[8:11]
	v_mfma_f32_16x16x32_bf16 v[16:19], v[132:135], v[200:203], v[16:19]
	v_mfma_f32_16x16x32_bf16 v[16:19], v[128:131], v[196:199], v[16:19]
	s_setprio 0
	s_barrier
	s_add_u32 s22, s22, 0x100080
	s_addc_u32 s23, s23, 0
	s_add_i32 s24, s24, s34
	s_mov_b32 m0, s24
	s_nop 0
	global_load_lds_dwordx4 v162, s[22:23]
	s_add_i32 m0, s24, 0x2000
	s_nop 0
	global_load_lds_dwordx4 v166, s[22:23]
	s_waitcnt vmcnt(6)
	s_barrier
	s_setprio 1
	v_mfma_f32_16x16x32_bf16 v[52:55], v[204:207], v[144:147], v[52:55]
	v_mfma_f32_16x16x32_bf16 v[52:55], v[208:211], v[148:151], v[52:55]
	v_mfma_f32_16x16x32_bf16 v[44:47], v[216:219], v[148:151], v[44:47]
	v_mfma_f32_16x16x32_bf16 v[44:47], v[212:215], v[144:147], v[44:47]
	v_mfma_f32_16x16x32_bf16 v[28:31], v[212:215], v[152:155], v[28:31]
	v_mfma_f32_16x16x32_bf16 v[28:31], v[216:219], v[156:159], v[28:31]
	v_mfma_f32_16x16x32_bf16 v[36:39], v[208:211], v[156:159], v[36:39]
	v_mfma_f32_16x16x32_bf16 v[36:39], v[204:207], v[152:155], v[36:39]
	v_mfma_f32_16x16x32_bf16 v[20:23], v[204:207], v[176:179], v[20:23]
	v_mfma_f32_16x16x32_bf16 v[20:23], v[208:211], v[180:183], v[20:23]
	v_mfma_f32_16x16x32_bf16 v[12:15], v[216:219], v[180:183], v[12:15]
	v_mfma_f32_16x16x32_bf16 v[12:15], v[212:215], v[176:179], v[12:15]
	v_mfma_f32_16x16x32_bf16 v[0:3], v[212:215], v[196:199], v[0:3]
	v_mfma_f32_16x16x32_bf16 v[0:3], v[216:219], v[200:203], v[0:3]
	v_mfma_f32_16x16x32_bf16 v[4:7], v[208:211], v[200:203], v[4:7]
	v_mfma_f32_16x16x32_bf16 v[4:7], v[204:207], v[196:199], v[4:7]
	s_setprio 0
	s_add_i32 s46, s46, 2
	s_add_u32 s20, s20, 0x100
	s_addc_u32 s21, s21, 0
	s_add_u32 s11, s11, 0x100
	s_addc_u32 s13, s13, 0
	s_cmp_gt_u32 s46, 61
	s_barrier
; __device__ __forceinline__ float bf_lo(unsigned w) { return __uint_as_float(w << 16); }
; __device__ __forceinline__ float bf_hi(unsigned w) { return __uint_as_float(w & 0xffff0000u); }
;     __device__ __forceinline__ void operator()(const f32x4 (&acc)[2][2][4][2], const Unit& u, int ui, int wr, int wc, int fr, int fq) const {
;         const int rl0 = wr * 64 + fr, col0 = u.pn * 256 + wc * 32 + 8 * fq;
;         u32x4 xv[2][4][2];
; #pragma unroll
;         for (int ai = 0; ai < 2; ++ai)
; #pragma unroll
;             for (int m = 0; m < 4; ++m)
; #pragma unroll
;                 for (int bj = 0; bj < 2; ++bj) xv[ai][m][bj] = *(const u32x4*)(xb + (size_t)(u.pm * 256 + rl0 + ai * 128 + m * 16) * DM + col0 + bj * 128);
; #pragma unroll
;         for (int ai = 0; ai < 2; ++ai)
; #pragma unroll
;             for (int m = 0; m < 4; ++m) { const int rl = rl0 + ai * 128 + m * 16; float* rowp = out + (size_t)(u.pm * 256 + rl) * DM + col0;
;                 const float r2 = tab[ui * 256 + rl];
; #pragma unroll
;                 for (int bj = 0; bj < 2; ++bj) { const u32x4 x = xv[ai][m][bj];
;                     const f32x4 x0 = {bf_lo(x.x), bf_hi(x.x), bf_lo(x.y), bf_hi(x.y)}, x1 = {bf_lo(x.z), bf_hi(x.z), bf_lo(x.w), bf_hi(x.w)};
;                     *(f32x4*)(rowp + bj * 128) = acc[ai][bj][m][0] * r2 + x0; *(f32x4*)(rowp + bj * 128 + 4) = acc[ai][bj][m][1] * r2 + x1; } }
	s_cbranch_scc0 .LBB0_522
	s_nop 0
	s_nop 0
	s_nop 0
	s_nop 0
	s_nop 0
	s_nop 0
	s_nop 0
	s_nop 0
	s_nop 0
	s_nop 0
	s_nop 0
	s_nop 0
	s_nop 0
	s_nop 0
	s_nop 0
	s_nop 0
	s_nop 0
	s_nop 0
	s_nop 0
	s_nop 0
	s_nop 0
	s_nop 0
	s_nop 0
	s_nop 0
	s_nop 0
	s_nop 0
	s_nop 0
	s_nop 0
	s_nop 0
	s_lshl_b32 s11, s18, 8
	v_lshl_or_b32 v128, s16, 8, v191
	v_add_u32_e32 v130, s11, v186
	v_ashrrev_i32_e32 v129, 31, v128
	v_ashrrev_i32_e32 v131, 31, v130
	v_lshl_add_u64 v[132:133], v[128:129], 1, s[6:7]
	v_lshlrev_b64 v[134:135], 11, v[130:131]
	v_lshl_add_u64 v[134:135], v[132:133], 0, v[134:135]
	global_load_dwordx4 v[198:201], v[134:135], off
	global_load_dwordx4 v[202:205], v[134:135], off offset:256
	v_or_b32_e32 v134, 16, v130
	v_ashrrev_i32_e32 v135, 31, v134
	v_lshlrev_b64 v[134:135], 11, v[134:135]
	v_lshl_add_u64 v[134:135], v[132:133], 0, v[134:135]
	global_load_dwordx4 v[206:209], v[134:135], off
	global_load_dwordx4 v[210:213], v[134:135], off offset:256
	v_or_b32_e32 v136, 32, v130
	v_ashrrev_i32_e32 v137, 31, v136
	v_or_b32_e32 v138, 48, v130
	v_add_u32_e32 v184, 0x80, v130
	v_add_u32_e32 v182, 0x90, v130
	v_add_u32_e32 v180, 0xa0, v130
	v_add_u32_e32 v178, 0xb0, v130
	v_lshlrev_b64 v[176:177], 2, v[128:129]
	v_lshlrev_b64 v[128:129], 12, v[130:131]
	v_lshlrev_b64 v[130:131], 11, v[136:137]
	v_lshl_add_u64 v[130:131], v[132:133], 0, v[130:131]
	global_load_dwordx4 v[214:217], v[130:131], off
	v_ashrrev_i32_e32 v139, 31, v138
	v_ashrrev_i32_e32 v185, 31, v184
	v_ashrrev_i32_e32 v183, 31, v182
	v_ashrrev_i32_e32 v181, 31, v180
	v_ashrrev_i32_e32 v179, 31, v178
	v_lshlrev_b64 v[134:135], 11, v[138:139]
	v_lshlrev_b64 v[136:137], 11, v[184:185]
	v_lshlrev_b64 v[138:139], 11, v[182:183]
	v_lshl_add_u32 v196, s45, 10, v192
	v_lshlrev_b64 v[140:141], 11, v[180:181]
	v_lshlrev_b64 v[142:143], 11, v[178:179]
	v_lshl_add_u64 v[128:129], s[26:27], 0, v[128:129]
	v_lshl_add_u64 v[134:135], v[132:133], 0, v[134:135]
	v_lshl_add_u64 v[136:137], v[132:133], 0, v[136:137]
	v_lshl_add_u64 v[138:139], v[132:133], 0, v[138:139]
	ds_read2_b32 v[230:231], v196 offset1:16
	v_lshl_add_u64 v[234:235], v[132:133], 0, v[140:141]
	v_lshl_add_u64 v[236:237], v[132:133], 0, v[142:143]
	v_lshl_add_u64 v[238:239], v[128:129], 0, v[176:177]
	global_load_dwordx4 v[218:221], v[130:131], off offset:256
	global_load_dwordx4 v[222:225], v[134:135], off
	global_load_dwordx4 v[226:229], v[134:135], off offset:256
	global_load_dwordx4 v[156:159], v[136:137], off
	global_load_dwordx4 v[152:155], v[136:137], off offset:256
	global_load_dwordx4 v[148:151], v[138:139], off
	global_load_dwordx4 v[144:147], v[138:139], off offset:256
	global_load_dwordx4 v[140:143], v[234:235], off
	s_nop 0
	global_load_dwordx4 v[136:139], v[234:235], off offset:256
	global_load_dwordx4 v[132:135], v[236:237], off
	global_load_dwordx4 v[128:131], v[236:237], off offset:256
	v_add_u32_e32 v232, s11, v188
	v_ashrrev_i32_e32 v233, 31, v232
	s_and_b64 vcc, exec, s[0:1]
	s_mov_b32 s16, s10
	s_mov_b32 s18, s12
	s_mov_b64 s[20:21], s[4:5]
	s_mov_b64 s[22:23], s[14:15]
	s_mov_b32 s45, s44
	s_waitcnt vmcnt(0)
	v_lshlrev_b32_e32 v234, 16, v198
	v_and_b32_e32 v235, 0xffff0000, v198
	v_lshlrev_b32_e32 v198, 16, v199
	v_and_b32_e32 v199, 0xffff0000, v199
	v_lshlrev_b32_e32 v242, 16, v204
	v_and_b32_e32 v243, 0xffff0000, v204
	v_lshlrev_b32_e32 v236, 16, v200
	v_and_b32_e32 v237, 0xffff0000, v200
	v_lshlrev_b32_e32 v200, 16, v201
	v_and_b32_e32 v201, 0xffff0000, v201
	v_lshlrev_b32_e32 v240, 16, v202
	v_and_b32_e32 v241, 0xffff0000, v202
	v_lshlrev_b32_e32 v202, 16, v203
	v_and_b32_e32 v203, 0xffff0000, v203
	v_lshlrev_b32_e32 v204, 16, v205
	v_and_b32_e32 v205, 0xffff0000, v205
	s_waitcnt lgkmcnt(0)
	v_pk_fma_f32 v[126:127], v[126:127], v[230:231], v[198:199] op_sel_hi:[1,0,1]
	v_pk_fma_f32 v[124:125], v[124:125], v[230:231], v[234:235] op_sel_hi:[1,0,1]
	v_pk_fma_f32 v[108:109], v[108:109], v[230:231], v[242:243] op_sel_hi:[1,0,1]
	v_pk_fma_f32 v[122:123], v[122:123], v[230:231], v[200:201] op_sel_hi:[1,0,1]
	v_pk_fma_f32 v[120:121], v[120:121], v[230:231], v[236:237] op_sel_hi:[1,0,1]
	v_pk_fma_f32 v[118:119], v[118:119], v[230:231], v[202:203] op_sel_hi:[1,0,1]
	v_pk_fma_f32 v[116:117], v[116:117], v[230:231], v[240:241] op_sel_hi:[1,0,1]
	v_pk_fma_f32 v[110:111], v[110:111], v[230:231], v[204:205] op_sel_hi:[1,0,1]
	global_store_dwordx4 v[238:239], v[124:127], off
	global_store_dwordx4 v[238:239], v[120:123], off offset:16
	global_store_dwordx4 v[238:239], v[116:119], off offset:512
	global_store_dwordx4 v[238:239], v[108:111], off offset:528
	v_mov_b32_e32 v122, v231
	v_lshlrev_b32_e32 v118, 16, v208
	v_lshlrev_b64 v[108:109], 12, v[232:233]
	v_lshl_add_u64 v[108:109], s[26:27], 0, v[108:109]
	v_lshl_add_u64 v[116:117], v[108:109], 0, v[176:177]
	v_lshlrev_b32_e32 v108, 16, v206
	v_and_b32_e32 v109, 0xffff0000, v206
	v_lshlrev_b32_e32 v110, 16, v207
	v_and_b32_e32 v111, 0xffff0000, v207
	v_pk_fma_f32 v[110:111], v[114:115], v[122:123], v[110:111] op_sel_hi:[1,0,1]
	v_pk_fma_f32 v[108:109], v[112:113], v[122:123], v[108:109] op_sel_hi:[1,0,1]
	global_store_dwordx4 v[116:117], v[108:111], off
	v_and_b32_e32 v119, 0xffff0000, v208
	v_lshlrev_b32_e32 v120, 16, v209
	v_lshlrev_b32_e32 v108, 16, v212
	v_and_b32_e32 v109, 0xffff0000, v212
	v_lshlrev_b32_e32 v110, 16, v213
	v_and_b32_e32 v111, 0xffff0000, v213
	v_pk_fma_f32 v[98:99], v[98:99], v[122:123], v[110:111] op_sel_hi:[1,0,1]
	v_pk_fma_f32 v[96:97], v[96:97], v[122:123], v[108:109] op_sel_hi:[1,0,1]
	v_and_b32_e32 v121, 0xffff0000, v209
	global_store_dwordx4 v[116:117], v[96:99], off offset:528
	ds_read2_b32 v[98:99], v196 offset0:32 offset1:48
	v_pk_fma_f32 v[106:107], v[106:107], v[122:123], v[120:121] op_sel_hi:[1,0,1]
	v_pk_fma_f32 v[104:105], v[104:105], v[122:123], v[118:119] op_sel_hi:[1,0,1]
	v_add_u32_e32 v96, s11, v189
	global_store_dwordx4 v[116:117], v[104:107], off offset:16
	v_ashrrev_i32_e32 v97, 31, v96
	v_lshlrev_b64 v[96:97], 12, v[96:97]
	v_lshlrev_b32_e32 v104, 16, v210
	v_and_b32_e32 v105, 0xffff0000, v210
	v_lshlrev_b32_e32 v106, 16, v211
	v_and_b32_e32 v107, 0xffff0000, v211
	v_pk_fma_f32 v[102:103], v[102:103], v[122:123], v[106:107] op_sel_hi:[1,0,1]
	v_pk_fma_f32 v[100:101], v[100:101], v[122:123], v[104:105] op_sel_hi:[1,0,1]
	global_store_dwordx4 v[116:117], v[100:103], off offset:512
	v_lshl_add_u64 v[96:97], s[26:27], 0, v[96:97]
	v_lshl_add_u64 v[96:97], v[96:97], 0, v[176:177]
	v_lshlrev_b32_e32 v100, 16, v214
	v_and_b32_e32 v101, 0xffff0000, v214
	v_lshlrev_b32_e32 v102, 16, v215
	v_and_b32_e32 v103, 0xffff0000, v215
	s_waitcnt lgkmcnt(0)
; __device__ __forceinline__ float bf_lo(unsigned w) { return __uint_as_float(w << 16); }
; __device__ __forceinline__ float bf_hi(unsigned w) { return __uint_as_float(w & 0xffff0000u); }
;     __device__ __forceinline__ void operator()(const f32x4 (&acc)[2][2][4][2], const Unit& u, int ui, int wr, int wc, int fr, int fq) const {
;     ...
;             for (int m = 0; m < 4; ++m) { const int rl = rl0 + ai * 128 + m * 16; float* rowp = out + (size_t)(u.pm * 256 + rl) * DM + col0;
;                 const float r2 = tab[ui * 256 + rl];
; #pragma unroll
;                 for (int bj = 0; bj < 2; ++bj) { const u32x4 x = xv[ai][m][bj];
;                     const f32x4 x0 = {bf_lo(x.x), bf_hi(x.x), bf_lo(x.y), bf_hi(x.y)}, x1 = {bf_lo(x.z), bf_hi(x.z), bf_lo(x.w), bf_hi(x.w)};
;                     *(f32x4*)(rowp + bj * 128) = acc[ai][bj][m][0] * r2 + x0; *(f32x4*)(rowp + bj * 128 + 4) = acc[ai][bj][m][1] * r2 + x1; } }
	v_pk_fma_f32 v[94:95], v[94:95], v[98:99], v[102:103] op_sel_hi:[1,0,1]
	v_pk_fma_f32 v[92:93], v[92:93], v[98:99], v[100:101] op_sel_hi:[1,0,1]
	global_store_dwordx4 v[96:97], v[92:95], off
	v_lshlrev_b32_e32 v104, 16, v216
	v_and_b32_e32 v105, 0xffff0000, v216
	v_lshlrev_b32_e32 v92, 16, v220
	v_and_b32_e32 v93, 0xffff0000, v220
	v_lshlrev_b32_e32 v94, 16, v221
	v_and_b32_e32 v95, 0xffff0000, v221
	v_lshlrev_b32_e32 v106, 16, v217
	v_and_b32_e32 v107, 0xffff0000, v217
	v_pk_fma_f32 v[82:83], v[82:83], v[98:99], v[94:95] op_sel_hi:[1,0,1]
	v_pk_fma_f32 v[80:81], v[80:81], v[98:99], v[92:93] op_sel_hi:[1,0,1]
	v_pk_fma_f32 v[90:91], v[90:91], v[98:99], v[106:107] op_sel_hi:[1,0,1]
	v_pk_fma_f32 v[88:89], v[88:89], v[98:99], v[104:105] op_sel_hi:[1,0,1]
	global_store_dwordx4 v[96:97], v[80:83], off offset:528
	global_store_dwordx4 v[96:97], v[88:91], off offset:16
	s_nop 0
	v_add_u32_e32 v80, s11, v190
	v_lshlrev_b32_e32 v88, 16, v218
	v_and_b32_e32 v89, 0xffff0000, v218
	v_lshlrev_b32_e32 v90, 16, v219
	v_and_b32_e32 v91, 0xffff0000, v219
	v_ashrrev_i32_e32 v81, 31, v80
	v_pk_fma_f32 v[86:87], v[86:87], v[98:99], v[90:91] op_sel_hi:[1,0,1]
	v_pk_fma_f32 v[84:85], v[84:85], v[98:99], v[88:89] op_sel_hi:[1,0,1]
	v_lshlrev_b64 v[80:81], 12, v[80:81]
	global_store_dwordx4 v[96:97], v[84:87], off offset:512
	v_lshl_add_u64 v[80:81], s[26:27], 0, v[80:81]
	v_lshlrev_b32_e32 v82, 16, v222
	v_and_b32_e32 v83, 0xffff0000, v222
	v_lshlrev_b32_e32 v84, 16, v223
	v_and_b32_e32 v85, 0xffff0000, v223
	v_mov_b32_e32 v90, v99
	v_lshl_add_u64 v[80:81], v[80:81], 0, v[176:177]
	v_pk_fma_f32 v[78:79], v[78:79], v[90:91], v[84:85] op_sel_hi:[1,0,1]
	v_pk_fma_f32 v[76:77], v[76:77], v[90:91], v[82:83] op_sel_hi:[1,0,1]
	global_store_dwordx4 v[80:81], v[76:79], off
	v_lshlrev_b32_e32 v86, 16, v224
	v_and_b32_e32 v87, 0xffff0000, v224
	v_lshlrev_b32_e32 v76, 16, v228
	v_and_b32_e32 v77, 0xffff0000, v228
	v_lshlrev_b32_e32 v78, 16, v229
	v_and_b32_e32 v79, 0xffff0000, v229
	v_pk_fma_f32 v[66:67], v[66:67], v[90:91], v[78:79] op_sel_hi:[1,0,1]
	v_pk_fma_f32 v[64:65], v[64:65], v[90:91], v[76:77] op_sel_hi:[1,0,1]
	v_lshlrev_b32_e32 v88, 16, v225
	v_and_b32_e32 v89, 0xffff0000, v225
	global_store_dwordx4 v[80:81], v[64:67], off offset:528
	ds_read2_b32 v[66:67], v196 offset0:128 offset1:144
	v_pk_fma_f32 v[74:75], v[74:75], v[90:91], v[88:89] op_sel_hi:[1,0,1]
	v_pk_fma_f32 v[72:73], v[72:73], v[90:91], v[86:87] op_sel_hi:[1,0,1]
	global_store_dwordx4 v[80:81], v[72:75], off offset:16
	v_lshlrev_b64 v[64:65], 12, v[184:185]
	v_lshl_add_u64 v[64:65], s[26:27], 0, v[64:65]
	v_lshlrev_b32_e32 v72, 16, v226
	v_and_b32_e32 v73, 0xffff0000, v226
	v_lshlrev_b32_e32 v74, 16, v227
	v_and_b32_e32 v75, 0xffff0000, v227
	v_pk_fma_f32 v[70:71], v[70:71], v[90:91], v[74:75] op_sel_hi:[1,0,1]
	v_pk_fma_f32 v[68:69], v[68:69], v[90:91], v[72:73] op_sel_hi:[1,0,1]
	global_store_dwordx4 v[80:81], v[68:71], off offset:512
	v_lshl_add_u64 v[64:65], v[64:65], 0, v[176:177]
	v_lshlrev_b32_e32 v72, 16, v158
	v_lshlrev_b32_e32 v68, 16, v156
	v_and_b32_e32 v69, 0xffff0000, v156
	v_lshlrev_b32_e32 v70, 16, v157
	v_and_b32_e32 v71, 0xffff0000, v157
	v_and_b32_e32 v73, 0xffff0000, v158
	v_lshlrev_b32_e32 v74, 16, v159
	v_and_b32_e32 v75, 0xffff0000, v159
	s_waitcnt lgkmcnt(0)
; __device__ __forceinline__ float bf_lo(unsigned w) { return __uint_as_float(w << 16); }
; __device__ __forceinline__ float bf_hi(unsigned w) { return __uint_as_float(w & 0xffff0000u); }
; #define PG8_WAIT_V(n) asm volatile("s_waitcnt vmcnt(" #n ")" ::: "memory")
; #define PG8_BAR __builtin_amdgcn_s_barrier()
; template <class Epi, class Ptrs>
; __device__ __forceinline__ void gemm_phase(LAS unsigned char* lds, const int K, const StaticOrder& S, const Ptrs& P, const Epi& E) {
;     ...
;         cur = nxt; cA = nA; cB = nB; ++ui;
;     }
;     PG8_WAIT_V(0);
;     if (wr == 0) PG8_BAR;
;     __device__ __forceinline__ void operator()(const f32x4 (&acc)[2][2][4][2], const Unit& u, int ui, int wr, int wc, int fr, int fq) const {
;     ...
;             for (int m = 0; m < 4; ++m) { const int rl = rl0 + ai * 128 + m * 16; float* rowp = out + (size_t)(u.pm * 256 + rl) * DM + col0;
;                 const float r2 = tab[ui * 256 + rl];
; #pragma unroll
;                 for (int bj = 0; bj < 2; ++bj) { const u32x4 x = xv[ai][m][bj];
;                     const f32x4 x0 = {bf_lo(x.x), bf_hi(x.x), bf_lo(x.y), bf_hi(x.y)}, x1 = {bf_lo(x.z), bf_hi(x.z), bf_lo(x.w), bf_hi(x.w)};
;                     *(f32x4*)(rowp + bj * 128) = acc[ai][bj][m][0] * r2 + x0; *(f32x4*)(rowp + bj * 128 + 4) = acc[ai][bj][m][1] * r2 + x1; } }
	v_pk_fma_f32 v[62:63], v[62:63], v[66:67], v[70:71] op_sel_hi:[1,0,1]
	v_pk_fma_f32 v[60:61], v[60:61], v[66:67], v[68:69] op_sel_hi:[1,0,1]
	global_store_dwordx4 v[64:65], v[60:63], off
	v_pk_fma_f32 v[58:59], v[58:59], v[66:67], v[74:75] op_sel_hi:[1,0,1]
	v_pk_fma_f32 v[56:57], v[56:57], v[66:67], v[72:73] op_sel_hi:[1,0,1]
	v_lshlrev_b32_e32 v60, 16, v154
	v_and_b32_e32 v61, 0xffff0000, v154
	v_lshlrev_b32_e32 v62, 16, v155
	v_and_b32_e32 v63, 0xffff0000, v155
	global_store_dwordx4 v[64:65], v[56:59], off offset:16
	v_pk_fma_f32 v[46:47], v[46:47], v[66:67], v[62:63] op_sel_hi:[1,0,1]
	v_pk_fma_f32 v[44:45], v[44:45], v[66:67], v[60:61] op_sel_hi:[1,0,1]
	v_lshlrev_b32_e32 v56, 16, v152
	v_and_b32_e32 v57, 0xffff0000, v152
	v_lshlrev_b32_e32 v58, 16, v153
	v_and_b32_e32 v59, 0xffff0000, v153
	v_pk_fma_f32 v[54:55], v[54:55], v[66:67], v[58:59] op_sel_hi:[1,0,1]
	v_pk_fma_f32 v[52:53], v[52:53], v[66:67], v[56:57] op_sel_hi:[1,0,1]
	global_store_dwordx4 v[64:65], v[44:47], off offset:528
	global_store_dwordx4 v[64:65], v[52:55], off offset:512
	v_lshlrev_b32_e32 v56, 16, v151
	v_lshlrev_b64 v[44:45], 12, v[182:183]
	v_lshl_add_u64 v[44:45], s[26:27], 0, v[44:45]
	v_lshlrev_b32_e32 v54, 16, v150
	v_and_b32_e32 v55, 0xffff0000, v150
	v_and_b32_e32 v57, 0xffff0000, v151
	v_mov_b32_e32 v58, v67
	v_lshl_add_u64 v[52:53], v[44:45], 0, v[176:177]
	v_pk_fma_f32 v[42:43], v[42:43], v[58:59], v[56:57] op_sel_hi:[1,0,1]
	v_pk_fma_f32 v[40:41], v[40:41], v[58:59], v[54:55] op_sel_hi:[1,0,1]
	v_lshlrev_b32_e32 v44, 16, v148
	v_and_b32_e32 v45, 0xffff0000, v148
	v_lshlrev_b32_e32 v46, 16, v149
	v_and_b32_e32 v47, 0xffff0000, v149
	global_store_dwordx4 v[52:53], v[40:43], off offset:16
	v_pk_fma_f32 v[46:47], v[50:51], v[58:59], v[46:47] op_sel_hi:[1,0,1]
	v_pk_fma_f32 v[44:45], v[48:49], v[58:59], v[44:45] op_sel_hi:[1,0,1]
	v_lshlrev_b32_e32 v40, 16, v144
	v_and_b32_e32 v41, 0xffff0000, v144
	v_lshlrev_b32_e32 v42, 16, v145
	v_and_b32_e32 v43, 0xffff0000, v145
	v_pk_fma_f32 v[38:39], v[38:39], v[58:59], v[42:43] op_sel_hi:[1,0,1]
	v_pk_fma_f32 v[36:37], v[36:37], v[58:59], v[40:41] op_sel_hi:[1,0,1]
	global_store_dwordx4 v[52:53], v[44:47], off
	global_store_dwordx4 v[52:53], v[36:39], off offset:512
	ds_read2_b32 v[38:39], v196 offset0:160 offset1:176
	v_lshlrev_b32_e32 v44, 16, v146
	v_and_b32_e32 v45, 0xffff0000, v146
	v_lshlrev_b32_e32 v46, 16, v147
	v_and_b32_e32 v47, 0xffff0000, v147
	v_pk_fma_f32 v[30:31], v[30:31], v[58:59], v[46:47] op_sel_hi:[1,0,1]
	v_pk_fma_f32 v[28:29], v[28:29], v[58:59], v[44:45] op_sel_hi:[1,0,1]
	global_store_dwordx4 v[52:53], v[28:31], off offset:528
	v_lshlrev_b32_e32 v40, 16, v142
	v_and_b32_e32 v41, 0xffff0000, v142
	v_lshlrev_b64 v[28:29], 12, v[180:181]
	v_lshl_add_u64 v[28:29], s[26:27], 0, v[28:29]
	v_lshl_add_u64 v[36:37], v[28:29], 0, v[176:177]
	v_lshlrev_b32_e32 v28, 16, v140
	v_and_b32_e32 v29, 0xffff0000, v140
	v_lshlrev_b32_e32 v30, 16, v141
	v_and_b32_e32 v31, 0xffff0000, v141
	s_waitcnt lgkmcnt(0)
	v_pk_fma_f32 v[30:31], v[34:35], v[38:39], v[30:31] op_sel_hi:[1,0,1]
	v_pk_fma_f32 v[28:29], v[32:33], v[38:39], v[28:29] op_sel_hi:[1,0,1]
	v_lshlrev_b32_e32 v42, 16, v143
	v_and_b32_e32 v43, 0xffff0000, v143
	global_store_dwordx4 v[36:37], v[28:31], off
	v_pk_fma_f32 v[26:27], v[26:27], v[38:39], v[42:43] op_sel_hi:[1,0,1]
	v_pk_fma_f32 v[24:25], v[24:25], v[38:39], v[40:41] op_sel_hi:[1,0,1]
	v_lshlrev_b32_e32 v28, 16, v138
	v_and_b32_e32 v29, 0xffff0000, v138
	v_lshlrev_b32_e32 v30, 16, v139
	v_and_b32_e32 v31, 0xffff0000, v139
	v_pk_fma_f32 v[14:15], v[14:15], v[38:39], v[30:31] op_sel_hi:[1,0,1]
	v_pk_fma_f32 v[12:13], v[12:13], v[38:39], v[28:29] op_sel_hi:[1,0,1]
	global_store_dwordx4 v[36:37], v[24:27], off offset:16
	global_store_dwordx4 v[36:37], v[12:15], off offset:528
	s_nop 0
	v_lshlrev_b32_e32 v24, 16, v136
	v_and_b32_e32 v25, 0xffff0000, v136
	v_lshlrev_b32_e32 v26, 16, v137
	v_and_b32_e32 v27, 0xffff0000, v137
	v_lshlrev_b64 v[12:13], 12, v[178:179]
	v_pk_fma_f32 v[22:23], v[22:23], v[38:39], v[26:27] op_sel_hi:[1,0,1]
	v_pk_fma_f32 v[20:21], v[20:21], v[38:39], v[24:25] op_sel_hi:[1,0,1]
	v_lshl_add_u64 v[12:13], s[26:27], 0, v[12:13]
	global_store_dwordx4 v[36:37], v[20:23], off offset:512
	v_lshlrev_b32_e32 v14, 16, v133
	v_and_b32_e32 v15, 0xffff0000, v133
	v_lshl_add_u64 v[20:21], v[12:13], 0, v[176:177]
	v_lshlrev_b32_e32 v12, 16, v132
	v_and_b32_e32 v13, 0xffff0000, v132
	v_lshlrev_b32_e32 v22, 16, v134
	v_and_b32_e32 v23, 0xffff0000, v134
	v_lshlrev_b32_e32 v24, 16, v135
	v_and_b32_e32 v25, 0xffff0000, v135
	v_mov_b32_e32 v26, v39
	v_pk_fma_f32 v[14:15], v[18:19], v[26:27], v[14:15] op_sel_hi:[1,0,1]
	v_pk_fma_f32 v[12:13], v[16:17], v[26:27], v[12:13] op_sel_hi:[1,0,1]
	v_pk_fma_f32 v[10:11], v[10:11], v[26:27], v[24:25] op_sel_hi:[1,0,1]
	v_pk_fma_f32 v[8:9], v[8:9], v[26:27], v[22:23] op_sel_hi:[1,0,1]
	global_store_dwordx4 v[20:21], v[12:15], off
	global_store_dwordx4 v[20:21], v[8:11], off offset:16
	s_nop 0
	v_lshlrev_b32_e32 v12, 16, v130
	v_lshlrev_b32_e32 v8, 16, v128
	v_and_b32_e32 v9, 0xffff0000, v128
	v_lshlrev_b32_e32 v10, 16, v129
	v_and_b32_e32 v11, 0xffff0000, v129
	v_and_b32_e32 v13, 0xffff0000, v130
	v_lshlrev_b32_e32 v14, 16, v131
	v_and_b32_e32 v15, 0xffff0000, v131
	v_pk_fma_f32 v[6:7], v[6:7], v[26:27], v[10:11] op_sel_hi:[1,0,1]
	v_pk_fma_f32 v[4:5], v[4:5], v[26:27], v[8:9] op_sel_hi:[1,0,1]
	v_pk_fma_f32 v[2:3], v[2:3], v[26:27], v[14:15] op_sel_hi:[1,0,1]
	v_pk_fma_f32 v[0:1], v[0:1], v[26:27], v[12:13] op_sel_hi:[1,0,1]
	global_store_dwordx4 v[20:21], v[4:7], off offset:512
	global_store_dwordx4 v[20:21], v[0:3], off offset:528
	s_cbranch_vccz .LBB0_517
	s_waitcnt vmcnt(0)
	s_cmpk_gt_u32 s33, 0xff
	s_cbranch_scc1 .LBB0_526
	s_barrier
